# r2 + GEMM LDS-DMA tile loads use saddr+voffset form (64-bit VALU address adds removed from the K-loops)
# speedup vs baseline: 1.0057x; 1.0057x over previous
.LBB0_81:
	ds_read_b128 v[146:149], v152
	ds_read_b128 v[154:157], v152 offset:1024
	ds_read_b128 v[158:161], v152 offset:2048
	ds_read_b128 v[162:165], v152 offset:3072
	s_add_i32 s78, s1, 2
	s_cmp_gt_u32 s1, 13
	s_cselect_b32 s62, s75, s2
	s_cselect_b32 s58, s74, s0
	s_mov_b32 m0, s65
	ds_read_b128 v[166:169], v153
	ds_read_b128 v[170:173], v153 offset:1024
	ds_read_b128 v[174:177], v153 offset:2048
	ds_read_b128 v[178:181], v153 offset:3072
	ds_read_b128 v[182:185], v153 offset:4096
	ds_read_b128 v[186:189], v153 offset:5120
	ds_read_b128 v[190:193], v153 offset:6144
	ds_read_b128 v[194:197], v153 offset:7168
	global_load_lds_dwordx4 v[142:143], off
	s_mov_b32 m0, s66
	s_nop 0
	global_load_lds_dwordx4 v[144:145], off
	s_waitcnt lgkmcnt(8)
	s_barrier
	s_waitcnt lgkmcnt(0)
	s_waitcnt lgkmcnt(0)
	v_mfma_f32_16x16x32_bf16 v[124:127], v[146:149], v[166:169], v[124:127]
	v_mfma_f32_16x16x32_bf16 v[120:123], v[158:161], v[166:169], v[120:123]
	v_mfma_f32_16x16x32_bf16 v[108:111], v[146:149], v[174:177], v[108:111]
	v_mfma_f32_16x16x32_bf16 v[104:107], v[158:161], v[174:177], v[104:107]
	v_mfma_f32_16x16x32_bf16 v[92:95], v[146:149], v[182:185], v[92:95]
	v_mfma_f32_16x16x32_bf16 v[88:91], v[158:161], v[182:185], v[88:91]
	v_mfma_f32_16x16x32_bf16 v[76:79], v[146:149], v[190:193], v[76:79]
	v_mfma_f32_16x16x32_bf16 v[72:75], v[158:161], v[190:193], v[72:75]
	v_mfma_f32_16x16x32_bf16 v[124:127], v[154:157], v[170:173], v[124:127]
	v_mfma_f32_16x16x32_bf16 v[120:123], v[162:165], v[170:173], v[120:123]
	v_mfma_f32_16x16x32_bf16 v[108:111], v[154:157], v[178:181], v[108:111]
	v_mfma_f32_16x16x32_bf16 v[104:107], v[162:165], v[178:181], v[104:107]
	v_mfma_f32_16x16x32_bf16 v[92:95], v[154:157], v[186:189], v[92:95]
	v_mfma_f32_16x16x32_bf16 v[88:91], v[162:165], v[186:189], v[88:91]
	v_mfma_f32_16x16x32_bf16 v[76:79], v[154:157], v[194:197], v[76:79]
	v_mfma_f32_16x16x32_bf16 v[72:75], v[162:165], v[194:197], v[72:75]
	s_barrier
	s_cselect_b32 s8, 0, s78
	s_ashr_i32 s63, s62, 31
	s_lshl_b64 s[60:61], s[62:63], 11
	s_add_u32 s1, s70, s60
	s_addc_u32 s79, s71, s61
	s_lshl_b64 s[60:61], s[8:9], 7
	s_add_u32 s80, s1, s60
	s_addc_u32 s81, s79, s61
	s_mov_b32 m0, s19
	ds_read_b128 v[198:201], v152 offset:16384
	ds_read_b128 v[202:205], v152 offset:17408
	ds_read_b128 v[206:209], v152 offset:18432
	ds_read_b128 v[210:213], v152 offset:19456
	global_load_lds_dwordx4 v132, s[80:81]
	s_mov_b32 m0, s20
	s_nop 0
	global_load_lds_dwordx4 v128, s[80:81]
	s_barrier
	s_waitcnt lgkmcnt(0)
	s_waitcnt lgkmcnt(0)
	v_mfma_f32_16x16x32_bf16 v[116:119], v[198:201], v[166:169], v[116:119]
	v_mfma_f32_16x16x32_bf16 v[112:115], v[206:209], v[166:169], v[112:115]
	v_mfma_f32_16x16x32_bf16 v[100:103], v[198:201], v[174:177], v[100:103]
	v_mfma_f32_16x16x32_bf16 v[96:99], v[206:209], v[174:177], v[96:99]
	v_mfma_f32_16x16x32_bf16 v[84:87], v[198:201], v[182:185], v[84:87]
	v_mfma_f32_16x16x32_bf16 v[80:83], v[206:209], v[182:185], v[80:83]
	v_mfma_f32_16x16x32_bf16 v[68:71], v[198:201], v[190:193], v[68:71]
	v_mfma_f32_16x16x32_bf16 v[64:67], v[206:209], v[190:193], v[64:67]
	v_mfma_f32_16x16x32_bf16 v[116:119], v[202:205], v[170:173], v[116:119]
	v_mfma_f32_16x16x32_bf16 v[112:115], v[210:213], v[170:173], v[112:115]
	v_mfma_f32_16x16x32_bf16 v[100:103], v[202:205], v[178:181], v[100:103]
	v_mfma_f32_16x16x32_bf16 v[96:99], v[210:213], v[178:181], v[96:99]
	v_mfma_f32_16x16x32_bf16 v[84:87], v[202:205], v[186:189], v[84:87]
	v_mfma_f32_16x16x32_bf16 v[80:83], v[210:213], v[186:189], v[80:83]
	v_mfma_f32_16x16x32_bf16 v[68:71], v[202:205], v[194:197], v[68:71]
	v_mfma_f32_16x16x32_bf16 v[64:67], v[210:213], v[194:197], v[64:67]
	s_ashr_i32 s59, s58, 31
	s_lshl_b64 s[80:81], s[58:59], 11
	s_add_u32 s82, s16, s80
	s_addc_u32 s83, s17, s81
	s_add_u32 s80, s82, s60
	s_addc_u32 s81, s83, s61
	s_mov_b32 m0, s18
	s_barrier
	ds_read_b128 v[166:169], v153 offset:16384
	ds_read_b128 v[170:173], v153 offset:17408
	ds_read_b128 v[174:177], v153 offset:18432
	ds_read_b128 v[178:181], v153 offset:19456
	ds_read_b128 v[182:185], v153 offset:20480
	ds_read_b128 v[186:189], v153 offset:21504
	ds_read_b128 v[190:193], v153 offset:22528
	ds_read_b128 v[194:197], v153 offset:23552
	global_load_lds_dwordx4 v134, s[80:81]
	s_mov_b32 m0, s21
	s_nop 0
	global_load_lds_dwordx4 v130, s[80:81]
	s_barrier
	s_waitcnt lgkmcnt(0)
	s_waitcnt lgkmcnt(0)
	v_mfma_f32_16x16x32_bf16 v[60:63], v[146:149], v[166:169], v[60:63]
	v_mfma_f32_16x16x32_bf16 v[56:59], v[158:161], v[166:169], v[56:59]
	v_mfma_f32_16x16x32_bf16 v[44:47], v[146:149], v[174:177], v[44:47]
	v_mfma_f32_16x16x32_bf16 v[40:43], v[158:161], v[174:177], v[40:43]
	v_mfma_f32_16x16x32_bf16 v[28:31], v[146:149], v[182:185], v[28:31]
	v_mfma_f32_16x16x32_bf16 v[24:27], v[158:161], v[182:185], v[24:27]
	v_mfma_f32_16x16x32_bf16 v[12:15], v[146:149], v[190:193], v[12:15]
	v_mfma_f32_16x16x32_bf16 v[8:11], v[158:161], v[190:193], v[8:11]
	v_mfma_f32_16x16x32_bf16 v[60:63], v[154:157], v[170:173], v[60:63]
	v_mfma_f32_16x16x32_bf16 v[56:59], v[162:165], v[170:173], v[56:59]
	v_mfma_f32_16x16x32_bf16 v[44:47], v[154:157], v[178:181], v[44:47]
	v_mfma_f32_16x16x32_bf16 v[40:43], v[162:165], v[178:181], v[40:43]
	v_mfma_f32_16x16x32_bf16 v[28:31], v[154:157], v[186:189], v[28:31]
	v_mfma_f32_16x16x32_bf16 v[24:27], v[162:165], v[186:189], v[24:27]
	v_mfma_f32_16x16x32_bf16 v[12:15], v[154:157], v[194:197], v[12:15]
	v_mfma_f32_16x16x32_bf16 v[8:11], v[162:165], v[194:197], v[8:11]
	s_barrier
	s_bitset1_b32 s62, 7
	s_ashr_i32 s63, s62, 31
	s_lshl_b64 s[62:63], s[62:63], 11
	s_add_u32 s80, s70, s62
	s_addc_u32 s81, s71, s63
	s_add_u32 s62, s80, s60
	s_addc_u32 s63, s81, s61
	s_mov_b32 m0, s22
	s_nop 0
	global_load_lds_dwordx4 v132, s[62:63]
	s_mov_b32 m0, s23
	s_nop 0
	global_load_lds_dwordx4 v128, s[62:63]
	s_waitcnt vmcnt(6)
	s_barrier
	v_mfma_f32_16x16x32_bf16 v[52:55], v[198:201], v[166:169], v[52:55]
	v_mfma_f32_16x16x32_bf16 v[48:51], v[206:209], v[166:169], v[48:51]
	v_mfma_f32_16x16x32_bf16 v[36:39], v[198:201], v[174:177], v[36:39]
	v_mfma_f32_16x16x32_bf16 v[32:35], v[206:209], v[174:177], v[32:35]
	v_mfma_f32_16x16x32_bf16 v[20:23], v[198:201], v[182:185], v[20:23]
	v_mfma_f32_16x16x32_bf16 v[16:19], v[206:209], v[182:185], v[16:19]
	v_mfma_f32_16x16x32_bf16 v[4:7], v[198:201], v[190:193], v[4:7]
	v_mfma_f32_16x16x32_bf16 v[0:3], v[206:209], v[190:193], v[0:3]
	v_mfma_f32_16x16x32_bf16 v[52:55], v[202:205], v[170:173], v[52:55]
	v_mfma_f32_16x16x32_bf16 v[48:51], v[210:213], v[170:173], v[48:51]
	v_mfma_f32_16x16x32_bf16 v[36:39], v[202:205], v[178:181], v[36:39]
	v_mfma_f32_16x16x32_bf16 v[32:35], v[210:213], v[178:181], v[32:35]
	v_mfma_f32_16x16x32_bf16 v[20:23], v[202:205], v[186:189], v[20:23]
	v_mfma_f32_16x16x32_bf16 v[16:19], v[210:213], v[186:189], v[16:19]
	v_mfma_f32_16x16x32_bf16 v[4:7], v[202:205], v[194:197], v[4:7]
	v_mfma_f32_16x16x32_bf16 v[0:3], v[210:213], v[194:197], v[0:3]
	s_barrier
	ds_read_b128 v[146:149], v152 offset:32768
	ds_read_b128 v[154:157], v152 offset:33792
	ds_read_b128 v[158:161], v152 offset:34816
	ds_read_b128 v[162:165], v152 offset:35840
	s_bitset1_b32 s58, 7
	s_ashr_i32 s59, s58, 31
	s_lshl_b64 s[58:59], s[58:59], 11
	s_add_u32 s58, s16, s58
	s_addc_u32 s59, s17, s59
	s_add_u32 s58, s58, s60
	s_addc_u32 s59, s59, s61
	s_mov_b32 m0, s24
	ds_read_b128 v[166:169], v153 offset:32768
	ds_read_b128 v[170:173], v153 offset:33792
	ds_read_b128 v[174:177], v153 offset:34816
	ds_read_b128 v[178:181], v153 offset:35840
	ds_read_b128 v[182:185], v153 offset:36864
	ds_read_b128 v[186:189], v153 offset:37888
	ds_read_b128 v[190:193], v153 offset:38912
	ds_read_b128 v[194:197], v153 offset:39936
	global_load_lds_dwordx4 v134, s[58:59]
	s_mov_b32 m0, s25
	s_nop 0
	global_load_lds_dwordx4 v130, s[58:59]
	s_waitcnt lgkmcnt(8)
	s_barrier
	s_waitcnt lgkmcnt(0)
	s_waitcnt lgkmcnt(0)
	v_mfma_f32_16x16x32_bf16 v[124:127], v[146:149], v[166:169], v[124:127]
	v_mfma_f32_16x16x32_bf16 v[120:123], v[158:161], v[166:169], v[120:123]
	v_mfma_f32_16x16x32_bf16 v[108:111], v[146:149], v[174:177], v[108:111]
	v_mfma_f32_16x16x32_bf16 v[104:107], v[158:161], v[174:177], v[104:107]
	v_mfma_f32_16x16x32_bf16 v[92:95], v[146:149], v[182:185], v[92:95]
	v_mfma_f32_16x16x32_bf16 v[88:91], v[158:161], v[182:185], v[88:91]
	v_mfma_f32_16x16x32_bf16 v[76:79], v[146:149], v[190:193], v[76:79]
	v_mfma_f32_16x16x32_bf16 v[72:75], v[158:161], v[190:193], v[72:75]
	v_mfma_f32_16x16x32_bf16 v[124:127], v[154:157], v[170:173], v[124:127]
	v_mfma_f32_16x16x32_bf16 v[120:123], v[162:165], v[170:173], v[120:123]
	v_mfma_f32_16x16x32_bf16 v[108:111], v[154:157], v[178:181], v[108:111]
	v_mfma_f32_16x16x32_bf16 v[104:107], v[162:165], v[178:181], v[104:107]
	v_mfma_f32_16x16x32_bf16 v[92:95], v[154:157], v[186:189], v[92:95]
	v_mfma_f32_16x16x32_bf16 v[88:91], v[162:165], v[186:189], v[88:91]
	v_mfma_f32_16x16x32_bf16 v[76:79], v[154:157], v[194:197], v[76:79]
	v_mfma_f32_16x16x32_bf16 v[72:75], v[162:165], v[194:197], v[72:75]
	s_barrier
	s_or_b32 s8, s8, 1
	s_lshl_b64 s[58:59], s[8:9], 7
	s_add_u32 s60, s1, s58
	s_addc_u32 s61, s79, s59
	s_mov_b32 m0, s26
	ds_read_b128 v[198:201], v152 offset:49152
	ds_read_b128 v[202:205], v152 offset:50176
	ds_read_b128 v[206:209], v152 offset:51200
	ds_read_b128 v[210:213], v152 offset:52224
	global_load_lds_dwordx4 v132, s[60:61]
	s_mov_b32 m0, s27
	s_nop 0
	global_load_lds_dwordx4 v128, s[60:61]
	s_barrier
	s_waitcnt lgkmcnt(0)
	s_waitcnt lgkmcnt(0)
	v_mfma_f32_16x16x32_bf16 v[116:119], v[198:201], v[166:169], v[116:119]
	v_mfma_f32_16x16x32_bf16 v[112:115], v[206:209], v[166:169], v[112:115]
	v_mfma_f32_16x16x32_bf16 v[100:103], v[198:201], v[174:177], v[100:103]
	v_mfma_f32_16x16x32_bf16 v[96:99], v[206:209], v[174:177], v[96:99]
	v_mfma_f32_16x16x32_bf16 v[84:87], v[198:201], v[182:185], v[84:87]
	v_mfma_f32_16x16x32_bf16 v[80:83], v[206:209], v[182:185], v[80:83]
	v_mfma_f32_16x16x32_bf16 v[68:71], v[198:201], v[190:193], v[68:71]
	v_mfma_f32_16x16x32_bf16 v[64:67], v[206:209], v[190:193], v[64:67]
	v_mfma_f32_16x16x32_bf16 v[116:119], v[202:205], v[170:173], v[116:119]
	v_mfma_f32_16x16x32_bf16 v[112:115], v[210:213], v[170:173], v[112:115]
	v_mfma_f32_16x16x32_bf16 v[100:103], v[202:205], v[178:181], v[100:103]
	v_mfma_f32_16x16x32_bf16 v[96:99], v[210:213], v[178:181], v[96:99]
	v_mfma_f32_16x16x32_bf16 v[84:87], v[202:205], v[186:189], v[84:87]
	v_mfma_f32_16x16x32_bf16 v[80:83], v[210:213], v[186:189], v[80:83]
	v_mfma_f32_16x16x32_bf16 v[68:71], v[202:205], v[194:197], v[68:71]
	v_mfma_f32_16x16x32_bf16 v[64:67], v[210:213], v[194:197], v[64:67]
	s_add_u32 s60, s82, s58
	s_addc_u32 s61, s83, s59
	s_mov_b32 m0, s28
	s_barrier
	ds_read_b128 v[166:169], v153 offset:49152
	ds_read_b128 v[170:173], v153 offset:50176
	ds_read_b128 v[174:177], v153 offset:51200
	ds_read_b128 v[178:181], v153 offset:52224
	ds_read_b128 v[182:185], v153 offset:53248
	ds_read_b128 v[186:189], v153 offset:54272
	ds_read_b128 v[190:193], v153 offset:55296
	ds_read_b128 v[194:197], v153 offset:56320
	global_load_lds_dwordx4 v134, s[60:61]
	s_mov_b32 m0, s29
	s_nop 0
	global_load_lds_dwordx4 v130, s[60:61]
	s_barrier
	s_waitcnt lgkmcnt(0)
	s_waitcnt lgkmcnt(0)
	v_mfma_f32_16x16x32_bf16 v[60:63], v[146:149], v[166:169], v[60:63]
	v_mfma_f32_16x16x32_bf16 v[56:59], v[158:161], v[166:169], v[56:59]
	v_mfma_f32_16x16x32_bf16 v[44:47], v[146:149], v[174:177], v[44:47]
	v_mfma_f32_16x16x32_bf16 v[40:43], v[158:161], v[174:177], v[40:43]
	v_mfma_f32_16x16x32_bf16 v[28:31], v[146:149], v[182:185], v[28:31]
	v_mfma_f32_16x16x32_bf16 v[24:27], v[158:161], v[182:185], v[24:27]
	v_mfma_f32_16x16x32_bf16 v[12:15], v[146:149], v[190:193], v[12:15]
	v_mfma_f32_16x16x32_bf16 v[8:11], v[158:161], v[190:193], v[8:11]
	v_mfma_f32_16x16x32_bf16 v[60:63], v[154:157], v[170:173], v[60:63]
	v_mfma_f32_16x16x32_bf16 v[56:59], v[162:165], v[170:173], v[56:59]
	v_mfma_f32_16x16x32_bf16 v[44:47], v[154:157], v[178:181], v[44:47]
	v_mfma_f32_16x16x32_bf16 v[40:43], v[162:165], v[178:181], v[40:43]
	v_mfma_f32_16x16x32_bf16 v[28:31], v[154:157], v[186:189], v[28:31]
	v_mfma_f32_16x16x32_bf16 v[24:27], v[162:165], v[186:189], v[24:27]
	v_mfma_f32_16x16x32_bf16 v[12:15], v[154:157], v[194:197], v[12:15]
	v_mfma_f32_16x16x32_bf16 v[8:11], v[162:165], v[194:197], v[8:11]
	s_barrier
	s_add_u32 s58, s80, s58
	s_addc_u32 s59, s81, s59
	s_mov_b32 m0, s30
	s_nop 0
	global_load_lds_dwordx4 v132, s[58:59]
	s_mov_b32 m0, s31
	s_nop 0
	global_load_lds_dwordx4 v128, s[58:59]
	s_waitcnt vmcnt(6)
	s_barrier
	v_mfma_f32_16x16x32_bf16 v[52:55], v[198:201], v[166:169], v[52:55]
	v_mfma_f32_16x16x32_bf16 v[48:51], v[206:209], v[166:169], v[48:51]
	v_mfma_f32_16x16x32_bf16 v[36:39], v[198:201], v[174:177], v[36:39]
	v_mfma_f32_16x16x32_bf16 v[32:35], v[206:209], v[174:177], v[32:35]
	v_mfma_f32_16x16x32_bf16 v[20:23], v[198:201], v[182:185], v[20:23]
	v_mfma_f32_16x16x32_bf16 v[16:19], v[206:209], v[182:185], v[16:19]
	v_mfma_f32_16x16x32_bf16 v[4:7], v[198:201], v[190:193], v[4:7]
	v_mfma_f32_16x16x32_bf16 v[0:3], v[206:209], v[190:193], v[0:3]
	v_mfma_f32_16x16x32_bf16 v[52:55], v[202:205], v[170:173], v[52:55]
	v_mfma_f32_16x16x32_bf16 v[48:51], v[210:213], v[170:173], v[48:51]
	v_mfma_f32_16x16x32_bf16 v[36:39], v[202:205], v[178:181], v[36:39]
	v_mfma_f32_16x16x32_bf16 v[32:35], v[210:213], v[178:181], v[32:35]
	v_mfma_f32_16x16x32_bf16 v[20:23], v[202:205], v[186:189], v[20:23]
	v_mfma_f32_16x16x32_bf16 v[16:19], v[210:213], v[186:189], v[16:19]
	v_mfma_f32_16x16x32_bf16 v[4:7], v[202:205], v[194:197], v[4:7]
	v_mfma_f32_16x16x32_bf16 v[0:3], v[210:213], v[194:197], v[0:3]
	v_lshl_add_u64 v[142:143], v[142:143], 0, s[10:11]
	v_lshl_add_u64 v[144:145], v[144:145], 0, s[10:11]
	s_cmp_ge_u32 s78, s3
	s_mov_b32 s1, s78
	s_barrier
	s_cbranch_scc0 .LBB0_81
	s_andn2_b64 vcc, exec, s[56:57]
	s_cbranch_vccnz .LBB0_84
	s_bitset1_b32 s0, 7
	s_ashr_i32 s1, s0, 31
	s_lshl_b64 s[0:1], s[0:1], 11
	s_add_u32 s0, s16, s0
	s_addc_u32 s1, s17, s1
	v_lshl_add_u64 v[194:195], s[0:1], 0, v[134:135]
	s_mov_b32 m0, s65
	v_lshl_add_u64 v[194:195], v[194:195], 0, s[52:53]
	ds_read_b128 v[142:145], v152
	ds_read_b128 v[146:149], v152 offset:1024
	ds_read_b128 v[154:157], v152 offset:2048
	ds_read_b128 v[158:161], v152 offset:3072
	ds_read_b128 v[162:165], v153
	ds_read_b128 v[166:169], v153 offset:1024
	ds_read_b128 v[170:173], v153 offset:2048
	ds_read_b128 v[174:177], v153 offset:3072
	ds_read_b128 v[178:181], v153 offset:4096
	ds_read_b128 v[182:185], v153 offset:5120
	ds_read_b128 v[186:189], v153 offset:6144
	ds_read_b128 v[190:193], v153 offset:7168
	global_load_lds_dwordx4 v[194:195], off
	v_lshl_add_u64 v[194:195], s[0:1], 0, v[130:131]
	v_lshl_add_u64 v[194:195], v[194:195], 0, s[52:53]
	s_mov_b32 m0, s66
	s_nop 0
	global_load_lds_dwordx4 v[194:195], off
	s_barrier
	s_waitcnt lgkmcnt(0)
	s_waitcnt lgkmcnt(0)
	v_mfma_f32_16x16x32_bf16 v[124:127], v[142:145], v[162:165], v[124:127]
	v_mfma_f32_16x16x32_bf16 v[120:123], v[154:157], v[162:165], v[120:123]
	v_mfma_f32_16x16x32_bf16 v[108:111], v[142:145], v[170:173], v[108:111]
	v_mfma_f32_16x16x32_bf16 v[104:107], v[154:157], v[170:173], v[104:107]
	v_mfma_f32_16x16x32_bf16 v[92:95], v[142:145], v[178:181], v[92:95]
	v_mfma_f32_16x16x32_bf16 v[88:91], v[154:157], v[178:181], v[88:91]
	v_mfma_f32_16x16x32_bf16 v[76:79], v[142:145], v[186:189], v[76:79]
	v_mfma_f32_16x16x32_bf16 v[72:75], v[154:157], v[186:189], v[72:75]
	v_mfma_f32_16x16x32_bf16 v[124:127], v[146:149], v[166:169], v[124:127]
	v_mfma_f32_16x16x32_bf16 v[120:123], v[158:161], v[166:169], v[120:123]
	v_mfma_f32_16x16x32_bf16 v[108:111], v[146:149], v[174:177], v[108:111]
	v_mfma_f32_16x16x32_bf16 v[104:107], v[158:161], v[174:177], v[104:107]
	v_mfma_f32_16x16x32_bf16 v[92:95], v[146:149], v[182:185], v[92:95]
	v_mfma_f32_16x16x32_bf16 v[88:91], v[158:161], v[182:185], v[88:91]
	v_mfma_f32_16x16x32_bf16 v[76:79], v[146:149], v[190:193], v[76:79]
	v_mfma_f32_16x16x32_bf16 v[72:75], v[158:161], v[190:193], v[72:75]
	s_barrier
	ds_read_b128 v[194:197], v152 offset:16384
	ds_read_b128 v[198:201], v152 offset:17408
	ds_read_b128 v[202:205], v152 offset:18432
	ds_read_b128 v[206:209], v152 offset:19456
	s_barrier
	s_waitcnt lgkmcnt(0)
	s_waitcnt lgkmcnt(0)
	v_mfma_f32_16x16x32_bf16 v[116:119], v[194:197], v[162:165], v[116:119]
	v_mfma_f32_16x16x32_bf16 v[112:115], v[202:205], v[162:165], v[112:115]
	v_mfma_f32_16x16x32_bf16 v[100:103], v[194:197], v[170:173], v[100:103]
	v_mfma_f32_16x16x32_bf16 v[96:99], v[202:205], v[170:173], v[96:99]
	v_mfma_f32_16x16x32_bf16 v[84:87], v[194:197], v[178:181], v[84:87]
	v_mfma_f32_16x16x32_bf16 v[80:83], v[202:205], v[178:181], v[80:83]
	v_mfma_f32_16x16x32_bf16 v[68:71], v[194:197], v[186:189], v[68:71]
	v_mfma_f32_16x16x32_bf16 v[64:67], v[202:205], v[186:189], v[64:67]
	v_mfma_f32_16x16x32_bf16 v[116:119], v[198:201], v[166:169], v[116:119]
	v_mfma_f32_16x16x32_bf16 v[112:115], v[206:209], v[166:169], v[112:115]
	v_mfma_f32_16x16x32_bf16 v[100:103], v[198:201], v[174:177], v[100:103]
	v_mfma_f32_16x16x32_bf16 v[96:99], v[206:209], v[174:177], v[96:99]
	v_mfma_f32_16x16x32_bf16 v[84:87], v[198:201], v[182:185], v[84:87]
	v_mfma_f32_16x16x32_bf16 v[80:83], v[206:209], v[182:185], v[80:83]
	v_mfma_f32_16x16x32_bf16 v[68:71], v[198:201], v[190:193], v[68:71]
	v_mfma_f32_16x16x32_bf16 v[64:67], v[206:209], v[190:193], v[64:67]
	s_barrier
	ds_read_b128 v[162:165], v153 offset:16384
	ds_read_b128 v[166:169], v153 offset:17408
	ds_read_b128 v[170:173], v153 offset:18432
	ds_read_b128 v[174:177], v153 offset:19456
	ds_read_b128 v[178:181], v153 offset:20480
	ds_read_b128 v[182:185], v153 offset:21504
	ds_read_b128 v[186:189], v153 offset:22528
	ds_read_b128 v[190:193], v153 offset:23552
	s_waitcnt vmcnt(4)
	s_barrier
	s_waitcnt lgkmcnt(0)
	s_waitcnt lgkmcnt(0)
	v_mfma_f32_16x16x32_bf16 v[60:63], v[142:145], v[162:165], v[60:63]
	v_mfma_f32_16x16x32_bf16 v[56:59], v[154:157], v[162:165], v[56:59]
	v_mfma_f32_16x16x32_bf16 v[44:47], v[142:145], v[170:173], v[44:47]
	v_mfma_f32_16x16x32_bf16 v[40:43], v[154:157], v[170:173], v[40:43]
	v_mfma_f32_16x16x32_bf16 v[28:31], v[142:145], v[178:181], v[28:31]
	v_mfma_f32_16x16x32_bf16 v[24:27], v[154:157], v[178:181], v[24:27]
	v_mfma_f32_16x16x32_bf16 v[12:15], v[142:145], v[186:189], v[12:15]
	v_mfma_f32_16x16x32_bf16 v[8:11], v[154:157], v[186:189], v[8:11]
	v_mfma_f32_16x16x32_bf16 v[60:63], v[146:149], v[166:169], v[60:63]
	v_mfma_f32_16x16x32_bf16 v[56:59], v[158:161], v[166:169], v[56:59]
	v_mfma_f32_16x16x32_bf16 v[44:47], v[146:149], v[174:177], v[44:47]
	v_mfma_f32_16x16x32_bf16 v[40:43], v[158:161], v[174:177], v[40:43]
	v_mfma_f32_16x16x32_bf16 v[28:31], v[146:149], v[182:185], v[28:31]
	v_mfma_f32_16x16x32_bf16 v[24:27], v[158:161], v[182:185], v[24:27]
	v_mfma_f32_16x16x32_bf16 v[12:15], v[146:149], v[190:193], v[12:15]
	v_mfma_f32_16x16x32_bf16 v[8:11], v[158:161], v[190:193], v[8:11]
	v_mfma_f32_16x16x32_bf16 v[52:55], v[194:197], v[162:165], v[52:55]
	v_mfma_f32_16x16x32_bf16 v[48:51], v[202:205], v[162:165], v[48:51]
	v_mfma_f32_16x16x32_bf16 v[36:39], v[194:197], v[170:173], v[36:39]
	v_mfma_f32_16x16x32_bf16 v[32:35], v[202:205], v[170:173], v[32:35]
	v_mfma_f32_16x16x32_bf16 v[20:23], v[194:197], v[178:181], v[20:23]
	v_mfma_f32_16x16x32_bf16 v[16:19], v[202:205], v[178:181], v[16:19]
	v_mfma_f32_16x16x32_bf16 v[4:7], v[194:197], v[186:189], v[4:7]
	v_mfma_f32_16x16x32_bf16 v[0:3], v[202:205], v[186:189], v[0:3]
	v_mfma_f32_16x16x32_bf16 v[52:55], v[198:201], v[166:169], v[52:55]
	v_mfma_f32_16x16x32_bf16 v[48:51], v[206:209], v[166:169], v[48:51]
	v_mfma_f32_16x16x32_bf16 v[36:39], v[198:201], v[174:177], v[36:39]
	v_mfma_f32_16x16x32_bf16 v[32:35], v[206:209], v[174:177], v[32:35]
	v_mfma_f32_16x16x32_bf16 v[20:23], v[198:201], v[182:185], v[20:23]
	v_mfma_f32_16x16x32_bf16 v[16:19], v[206:209], v[182:185], v[16:19]
	v_mfma_f32_16x16x32_bf16 v[4:7], v[198:201], v[190:193], v[4:7]
	v_mfma_f32_16x16x32_bf16 v[0:3], v[206:209], v[190:193], v[0:3]
	s_barrier
	ds_read_b128 v[142:145], v152 offset:32768
	ds_read_b128 v[146:149], v152 offset:33792
	ds_read_b128 v[154:157], v152 offset:34816
	ds_read_b128 v[158:161], v152 offset:35840
	ds_read_b128 v[162:165], v153 offset:32768
	ds_read_b128 v[166:169], v153 offset:33792
	ds_read_b128 v[170:173], v153 offset:34816
	ds_read_b128 v[174:177], v153 offset:35840
	ds_read_b128 v[178:181], v153 offset:36864
	ds_read_b128 v[182:185], v153 offset:37888
	ds_read_b128 v[186:189], v153 offset:38912
	ds_read_b128 v[190:193], v153 offset:39936
	s_waitcnt vmcnt(2)
	s_barrier
	s_waitcnt lgkmcnt(0)
	s_waitcnt lgkmcnt(0)
	v_mfma_f32_16x16x32_bf16 v[124:127], v[142:145], v[162:165], v[124:127]
	v_mfma_f32_16x16x32_bf16 v[120:123], v[154:157], v[162:165], v[120:123]
	v_mfma_f32_16x16x32_bf16 v[108:111], v[142:145], v[170:173], v[108:111]
	v_mfma_f32_16x16x32_bf16 v[104:107], v[154:157], v[170:173], v[104:107]
	v_mfma_f32_16x16x32_bf16 v[92:95], v[142:145], v[178:181], v[92:95]
	v_mfma_f32_16x16x32_bf16 v[88:91], v[154:157], v[178:181], v[88:91]
	v_mfma_f32_16x16x32_bf16 v[76:79], v[142:145], v[186:189], v[76:79]
	v_mfma_f32_16x16x32_bf16 v[72:75], v[154:157], v[186:189], v[72:75]
	v_mfma_f32_16x16x32_bf16 v[124:127], v[146:149], v[166:169], v[124:127]
	v_mfma_f32_16x16x32_bf16 v[120:123], v[158:161], v[166:169], v[120:123]
	v_mfma_f32_16x16x32_bf16 v[108:111], v[146:149], v[174:177], v[108:111]
	v_mfma_f32_16x16x32_bf16 v[104:107], v[158:161], v[174:177], v[104:107]
	v_mfma_f32_16x16x32_bf16 v[92:95], v[146:149], v[182:185], v[92:95]
	v_mfma_f32_16x16x32_bf16 v[88:91], v[158:161], v[182:185], v[88:91]
	v_mfma_f32_16x16x32_bf16 v[76:79], v[146:149], v[190:193], v[76:79]
	v_mfma_f32_16x16x32_bf16 v[72:75], v[158:161], v[190:193], v[72:75]
	s_barrier
	ds_read_b128 v[194:197], v152 offset:49152
	ds_read_b128 v[198:201], v152 offset:50176
	ds_read_b128 v[202:205], v152 offset:51200
	ds_read_b128 v[206:209], v152 offset:52224
	s_waitcnt vmcnt(0)
	s_barrier
	s_waitcnt lgkmcnt(0)
	s_waitcnt lgkmcnt(0)
	v_mfma_f32_16x16x32_bf16 v[116:119], v[194:197], v[162:165], v[116:119]
	v_mfma_f32_16x16x32_bf16 v[112:115], v[202:205], v[162:165], v[112:115]
	v_mfma_f32_16x16x32_bf16 v[100:103], v[194:197], v[170:173], v[100:103]
	v_mfma_f32_16x16x32_bf16 v[96:99], v[202:205], v[170:173], v[96:99]
	v_mfma_f32_16x16x32_bf16 v[84:87], v[194:197], v[178:181], v[84:87]
	v_mfma_f32_16x16x32_bf16 v[80:83], v[202:205], v[178:181], v[80:83]
	v_mfma_f32_16x16x32_bf16 v[68:71], v[194:197], v[186:189], v[68:71]
	v_mfma_f32_16x16x32_bf16 v[64:67], v[202:205], v[186:189], v[64:67]
	v_mfma_f32_16x16x32_bf16 v[116:119], v[198:201], v[166:169], v[116:119]
	v_mfma_f32_16x16x32_bf16 v[112:115], v[206:209], v[166:169], v[112:115]
	v_mfma_f32_16x16x32_bf16 v[100:103], v[198:201], v[174:177], v[100:103]
	v_mfma_f32_16x16x32_bf16 v[96:99], v[206:209], v[174:177], v[96:99]
	v_mfma_f32_16x16x32_bf16 v[84:87], v[198:201], v[182:185], v[84:87]
	v_mfma_f32_16x16x32_bf16 v[80:83], v[206:209], v[182:185], v[80:83]
	v_mfma_f32_16x16x32_bf16 v[68:71], v[198:201], v[190:193], v[68:71]
	v_mfma_f32_16x16x32_bf16 v[64:67], v[206:209], v[190:193], v[64:67]
	s_barrier
	ds_read_b128 v[162:165], v153 offset:49152
	ds_read_b128 v[166:169], v153 offset:50176
	ds_read_b128 v[170:173], v153 offset:51200
	ds_read_b128 v[174:177], v153 offset:52224
	ds_read_b128 v[178:181], v153 offset:53248
	ds_read_b128 v[182:185], v153 offset:54272
	ds_read_b128 v[186:189], v153 offset:55296
	ds_read_b128 v[190:193], v153 offset:56320
	s_barrier
	s_waitcnt lgkmcnt(0)
	s_waitcnt lgkmcnt(0)
	v_mfma_f32_16x16x32_bf16 v[60:63], v[142:145], v[162:165], v[60:63]
	v_mfma_f32_16x16x32_bf16 v[56:59], v[154:157], v[162:165], v[56:59]
	v_mfma_f32_16x16x32_bf16 v[44:47], v[142:145], v[170:173], v[44:47]
	v_mfma_f32_16x16x32_bf16 v[40:43], v[154:157], v[170:173], v[40:43]
	v_mfma_f32_16x16x32_bf16 v[28:31], v[142:145], v[178:181], v[28:31]
	v_mfma_f32_16x16x32_bf16 v[24:27], v[154:157], v[178:181], v[24:27]
	v_mfma_f32_16x16x32_bf16 v[12:15], v[142:145], v[186:189], v[12:15]
	v_mfma_f32_16x16x32_bf16 v[8:11], v[154:157], v[186:189], v[8:11]
	v_mfma_f32_16x16x32_bf16 v[60:63], v[146:149], v[166:169], v[60:63]
	v_mfma_f32_16x16x32_bf16 v[56:59], v[158:161], v[166:169], v[56:59]
	v_mfma_f32_16x16x32_bf16 v[44:47], v[146:149], v[174:177], v[44:47]
	v_mfma_f32_16x16x32_bf16 v[40:43], v[158:161], v[174:177], v[40:43]
	v_mfma_f32_16x16x32_bf16 v[28:31], v[146:149], v[182:185], v[28:31]
	v_mfma_f32_16x16x32_bf16 v[24:27], v[158:161], v[182:185], v[24:27]
	v_mfma_f32_16x16x32_bf16 v[12:15], v[146:149], v[190:193], v[12:15]
	v_mfma_f32_16x16x32_bf16 v[8:11], v[158:161], v[190:193], v[8:11]
	v_mfma_f32_16x16x32_bf16 v[52:55], v[194:197], v[162:165], v[52:55]
	v_mfma_f32_16x16x32_bf16 v[48:51], v[202:205], v[162:165], v[48:51]
	v_mfma_f32_16x16x32_bf16 v[36:39], v[194:197], v[170:173], v[36:39]
	v_mfma_f32_16x16x32_bf16 v[32:35], v[202:205], v[170:173], v[32:35]
	v_mfma_f32_16x16x32_bf16 v[20:23], v[194:197], v[178:181], v[20:23]
	v_mfma_f32_16x16x32_bf16 v[16:19], v[202:205], v[178:181], v[16:19]
	v_mfma_f32_16x16x32_bf16 v[4:7], v[194:197], v[186:189], v[4:7]
	v_mfma_f32_16x16x32_bf16 v[0:3], v[202:205], v[186:189], v[0:3]
	v_mfma_f32_16x16x32_bf16 v[52:55], v[198:201], v[166:169], v[52:55]
	v_mfma_f32_16x16x32_bf16 v[48:51], v[206:209], v[166:169], v[48:51]
	v_mfma_f32_16x16x32_bf16 v[36:39], v[198:201], v[174:177], v[36:39]
	v_mfma_f32_16x16x32_bf16 v[32:35], v[206:209], v[174:177], v[32:35]
	v_mfma_f32_16x16x32_bf16 v[20:23], v[198:201], v[182:185], v[20:23]
	v_mfma_f32_16x16x32_bf16 v[16:19], v[206:209], v[182:185], v[16:19]
	v_mfma_f32_16x16x32_bf16 v[4:7], v[198:201], v[190:193], v[4:7]
	v_mfma_f32_16x16x32_bf16 v[0:3], v[206:209], v[190:193], v[0:3]
	s_barrier

.LBB0_230:
	ds_read_b128 v[148:151], v146
	ds_read_b128 v[152:155], v146 offset:1024
	ds_read_b128 v[156:159], v146 offset:2048
	ds_read_b128 v[160:163], v146 offset:3072
	s_add_i32 s76, s53, 2
	s_cmp_eq_u32 s53, 0
	s_cselect_b32 s58, s54, s72
	s_cselect_b32 s56, s52, s67
	s_mov_b32 m0, s62
	ds_read_b128 v[164:167], v147
	ds_read_b128 v[168:171], v147 offset:1024
	ds_read_b128 v[172:175], v147 offset:2048
	ds_read_b128 v[176:179], v147 offset:3072
	ds_read_b128 v[180:183], v147 offset:4096
	ds_read_b128 v[184:187], v147 offset:5120
	ds_read_b128 v[188:191], v147 offset:6144
	ds_read_b128 v[192:195], v147 offset:7168
	global_load_lds_dwordx4 v[140:141], off
	s_mov_b32 m0, s63
	s_nop 0
	global_load_lds_dwordx4 v[142:143], off
	s_waitcnt lgkmcnt(8)
	s_barrier
	s_waitcnt lgkmcnt(0)
	s_waitcnt lgkmcnt(0)
	v_mfma_f32_16x16x32_bf16 v[124:127], v[148:151], v[164:167], v[124:127]
	v_mfma_f32_16x16x32_bf16 v[120:123], v[156:159], v[164:167], v[120:123]
	v_mfma_f32_16x16x32_bf16 v[116:119], v[148:151], v[172:175], v[116:119]
	v_mfma_f32_16x16x32_bf16 v[108:111], v[156:159], v[172:175], v[108:111]
	v_mfma_f32_16x16x32_bf16 v[100:103], v[148:151], v[180:183], v[100:103]
	v_mfma_f32_16x16x32_bf16 v[92:95], v[156:159], v[180:183], v[92:95]
	v_mfma_f32_16x16x32_bf16 v[84:87], v[148:151], v[188:191], v[84:87]
	v_mfma_f32_16x16x32_bf16 v[76:79], v[156:159], v[188:191], v[76:79]
	v_mfma_f32_16x16x32_bf16 v[124:127], v[152:155], v[168:171], v[124:127]
	v_mfma_f32_16x16x32_bf16 v[120:123], v[160:163], v[168:171], v[120:123]
	v_mfma_f32_16x16x32_bf16 v[116:119], v[152:155], v[176:179], v[116:119]
	v_mfma_f32_16x16x32_bf16 v[108:111], v[160:163], v[176:179], v[108:111]
	v_mfma_f32_16x16x32_bf16 v[100:103], v[152:155], v[184:187], v[100:103]
	v_mfma_f32_16x16x32_bf16 v[92:95], v[160:163], v[184:187], v[92:95]
	v_mfma_f32_16x16x32_bf16 v[84:87], v[152:155], v[192:195], v[84:87]
	v_mfma_f32_16x16x32_bf16 v[76:79], v[160:163], v[192:195], v[76:79]
	s_barrier
	s_cselect_b32 s53, 0x100, 0
	s_ashr_i32 s59, s58, 31
	s_lshl_b64 s[78:79], s[58:59], 9
	s_add_u32 s57, s17, s78
	s_addc_u32 s59, s18, s79
	s_add_u32 s78, s57, s53
	s_addc_u32 s79, s59, 0
	s_mov_b32 m0, s20
	v_lshl_add_u64 v[212:213], s[78:79], 0, v[132:133]
	ds_read_b128 v[196:199], v146 offset:16384
	ds_read_b128 v[200:203], v146 offset:17408
	ds_read_b128 v[204:207], v146 offset:18432
	ds_read_b128 v[208:211], v146 offset:19456
	global_load_lds_dwordx4 v[212:213], off
	v_lshl_add_u64 v[214:215], s[78:79], 0, v[128:129]
	s_mov_b32 m0, s21
	s_nop 0
	global_load_lds_dwordx4 v[214:215], off
	s_barrier
	s_waitcnt lgkmcnt(0)
	s_waitcnt lgkmcnt(0)
	v_mfma_f32_16x16x32_bf16 v[112:115], v[196:199], v[164:167], v[112:115]
	v_mfma_f32_16x16x32_bf16 v[104:107], v[204:207], v[164:167], v[104:107]
	v_mfma_f32_16x16x32_bf16 v[96:99], v[196:199], v[172:175], v[96:99]
	v_mfma_f32_16x16x32_bf16 v[88:91], v[204:207], v[172:175], v[88:91]
	v_mfma_f32_16x16x32_bf16 v[80:83], v[196:199], v[180:183], v[80:83]
	v_mfma_f32_16x16x32_bf16 v[72:75], v[204:207], v[180:183], v[72:75]
	v_mfma_f32_16x16x32_bf16 v[68:71], v[196:199], v[188:191], v[68:71]
	v_mfma_f32_16x16x32_bf16 v[64:67], v[204:207], v[188:191], v[64:67]
	v_mfma_f32_16x16x32_bf16 v[112:115], v[200:203], v[168:171], v[112:115]
	v_mfma_f32_16x16x32_bf16 v[104:107], v[208:211], v[168:171], v[104:107]
	v_mfma_f32_16x16x32_bf16 v[96:99], v[200:203], v[176:179], v[96:99]
	v_mfma_f32_16x16x32_bf16 v[88:91], v[208:211], v[176:179], v[88:91]
	v_mfma_f32_16x16x32_bf16 v[80:83], v[200:203], v[184:187], v[80:83]
	v_mfma_f32_16x16x32_bf16 v[72:75], v[208:211], v[184:187], v[72:75]
	v_mfma_f32_16x16x32_bf16 v[68:71], v[200:203], v[192:195], v[68:71]
	v_mfma_f32_16x16x32_bf16 v[64:67], v[208:211], v[192:195], v[64:67]
	s_ashr_i32 s57, s56, 31
	s_lshl_b64 s[78:79], s[56:57], 9
	s_add_u32 s57, s9, s78
	s_addc_u32 s59, s16, s79
	s_add_u32 s78, s57, s53
	s_addc_u32 s79, s59, 0
	s_mov_b32 m0, s19
	v_lshl_add_u64 v[216:217], s[78:79], 0, v[134:135]
	s_barrier
	ds_read_b128 v[164:167], v147 offset:16384
	ds_read_b128 v[168:171], v147 offset:17408
	ds_read_b128 v[172:175], v147 offset:18432
	ds_read_b128 v[176:179], v147 offset:19456
	ds_read_b128 v[180:183], v147 offset:20480
	ds_read_b128 v[184:187], v147 offset:21504
	ds_read_b128 v[188:191], v147 offset:22528
	ds_read_b128 v[192:195], v147 offset:23552
	global_load_lds_dwordx4 v[216:217], off
	v_lshl_add_u64 v[218:219], s[78:79], 0, v[130:131]
	s_mov_b32 m0, s22
	s_nop 0
	global_load_lds_dwordx4 v[218:219], off
	s_barrier
	s_waitcnt lgkmcnt(0)
	s_waitcnt lgkmcnt(0)
	v_mfma_f32_16x16x32_bf16 v[60:63], v[148:151], v[164:167], v[60:63]
	v_mfma_f32_16x16x32_bf16 v[56:59], v[156:159], v[164:167], v[56:59]
	v_mfma_f32_16x16x32_bf16 v[52:55], v[148:151], v[172:175], v[52:55]
	v_mfma_f32_16x16x32_bf16 v[44:47], v[156:159], v[172:175], v[44:47]
	v_mfma_f32_16x16x32_bf16 v[36:39], v[148:151], v[180:183], v[36:39]
	v_mfma_f32_16x16x32_bf16 v[28:31], v[156:159], v[180:183], v[28:31]
	v_mfma_f32_16x16x32_bf16 v[20:23], v[148:151], v[188:191], v[20:23]
	v_mfma_f32_16x16x32_bf16 v[12:15], v[156:159], v[188:191], v[12:15]
	v_mfma_f32_16x16x32_bf16 v[60:63], v[152:155], v[168:171], v[60:63]
	v_mfma_f32_16x16x32_bf16 v[56:59], v[160:163], v[168:171], v[56:59]
	v_mfma_f32_16x16x32_bf16 v[52:55], v[152:155], v[176:179], v[52:55]
	v_mfma_f32_16x16x32_bf16 v[44:47], v[160:163], v[176:179], v[44:47]
	v_mfma_f32_16x16x32_bf16 v[36:39], v[152:155], v[184:187], v[36:39]
	v_mfma_f32_16x16x32_bf16 v[28:31], v[160:163], v[184:187], v[28:31]
	v_mfma_f32_16x16x32_bf16 v[20:23], v[152:155], v[192:195], v[20:23]
	v_mfma_f32_16x16x32_bf16 v[12:15], v[160:163], v[192:195], v[12:15]
	s_barrier
	s_bitset1_b32 s58, 7
	s_ashr_i32 s59, s58, 31
	s_lshl_b64 s[58:59], s[58:59], 9
	s_add_u32 s57, s17, s58
	s_addc_u32 s59, s18, s59
	s_add_u32 s58, s57, s53
	s_addc_u32 s59, s59, 0
	s_mov_b32 m0, s23
	v_lshl_add_u64 v[220:221], s[58:59], 0, v[132:133]
	global_load_lds_dwordx4 v[220:221], off
	v_lshl_add_u64 v[222:223], s[58:59], 0, v[128:129]
	s_mov_b32 m0, s24
	s_nop 0
	global_load_lds_dwordx4 v[222:223], off
	s_waitcnt vmcnt(6)
	s_barrier
	v_mfma_f32_16x16x32_bf16 v[48:51], v[196:199], v[164:167], v[48:51]
	v_mfma_f32_16x16x32_bf16 v[40:43], v[204:207], v[164:167], v[40:43]
	v_mfma_f32_16x16x32_bf16 v[32:35], v[196:199], v[172:175], v[32:35]
	v_mfma_f32_16x16x32_bf16 v[24:27], v[204:207], v[172:175], v[24:27]
	v_mfma_f32_16x16x32_bf16 v[16:19], v[196:199], v[180:183], v[16:19]
	v_mfma_f32_16x16x32_bf16 v[8:11], v[204:207], v[180:183], v[8:11]
	v_mfma_f32_16x16x32_bf16 v[4:7], v[196:199], v[188:191], v[4:7]
	v_mfma_f32_16x16x32_bf16 v[0:3], v[204:207], v[188:191], v[0:3]
	v_mfma_f32_16x16x32_bf16 v[48:51], v[200:203], v[168:171], v[48:51]
	v_mfma_f32_16x16x32_bf16 v[40:43], v[208:211], v[168:171], v[40:43]
	v_mfma_f32_16x16x32_bf16 v[32:35], v[200:203], v[176:179], v[32:35]
	v_mfma_f32_16x16x32_bf16 v[24:27], v[208:211], v[176:179], v[24:27]
	v_mfma_f32_16x16x32_bf16 v[16:19], v[200:203], v[184:187], v[16:19]
	v_mfma_f32_16x16x32_bf16 v[8:11], v[208:211], v[184:187], v[8:11]
	v_mfma_f32_16x16x32_bf16 v[4:7], v[200:203], v[192:195], v[4:7]
	v_mfma_f32_16x16x32_bf16 v[0:3], v[208:211], v[192:195], v[0:3]
	s_barrier
	ds_read_b128 v[148:151], v146 offset:32768
	ds_read_b128 v[152:155], v146 offset:33792
	ds_read_b128 v[156:159], v146 offset:34816
	ds_read_b128 v[160:163], v146 offset:35840
	s_bitset1_b32 s56, 7
	s_ashr_i32 s57, s56, 31
	s_lshl_b64 s[56:57], s[56:57], 9
	s_add_u32 s56, s9, s56
	s_addc_u32 s57, s16, s57
	s_add_u32 s56, s56, s53
	s_addc_u32 s57, s57, 0
	s_mov_b32 m0, s25
	ds_read_b128 v[164:167], v147 offset:32768
	ds_read_b128 v[168:171], v147 offset:33792
	ds_read_b128 v[172:175], v147 offset:34816
	ds_read_b128 v[176:179], v147 offset:35840
	ds_read_b128 v[180:183], v147 offset:36864
	ds_read_b128 v[184:187], v147 offset:37888
	ds_read_b128 v[188:191], v147 offset:38912
	ds_read_b128 v[192:195], v147 offset:39936
	global_load_lds_dwordx4 v134, s[56:57]
	s_mov_b32 m0, s26
	s_nop 0
	global_load_lds_dwordx4 v130, s[56:57]
	s_waitcnt lgkmcnt(8)
	s_barrier
	s_waitcnt lgkmcnt(0)
	s_waitcnt lgkmcnt(0)
	v_mfma_f32_16x16x32_bf16 v[124:127], v[148:151], v[164:167], v[124:127]
	v_mfma_f32_16x16x32_bf16 v[120:123], v[156:159], v[164:167], v[120:123]
	v_mfma_f32_16x16x32_bf16 v[116:119], v[148:151], v[172:175], v[116:119]
	v_mfma_f32_16x16x32_bf16 v[108:111], v[156:159], v[172:175], v[108:111]
	v_mfma_f32_16x16x32_bf16 v[100:103], v[148:151], v[180:183], v[100:103]
	v_mfma_f32_16x16x32_bf16 v[92:95], v[156:159], v[180:183], v[92:95]
	v_mfma_f32_16x16x32_bf16 v[84:87], v[148:151], v[188:191], v[84:87]
	v_mfma_f32_16x16x32_bf16 v[76:79], v[156:159], v[188:191], v[76:79]
	v_mfma_f32_16x16x32_bf16 v[124:127], v[152:155], v[168:171], v[124:127]
	v_mfma_f32_16x16x32_bf16 v[120:123], v[160:163], v[168:171], v[120:123]
	v_mfma_f32_16x16x32_bf16 v[116:119], v[152:155], v[176:179], v[116:119]
	v_mfma_f32_16x16x32_bf16 v[108:111], v[160:163], v[176:179], v[108:111]
	v_mfma_f32_16x16x32_bf16 v[100:103], v[152:155], v[184:187], v[100:103]
	v_mfma_f32_16x16x32_bf16 v[92:95], v[160:163], v[184:187], v[92:95]
	v_mfma_f32_16x16x32_bf16 v[84:87], v[152:155], v[192:195], v[84:87]
	v_mfma_f32_16x16x32_bf16 v[76:79], v[160:163], v[192:195], v[76:79]
	s_barrier
	s_mov_b32 m0, s27
	v_lshl_add_u64 v[212:213], v[212:213], 0, s[0:1]
	ds_read_b128 v[196:199], v146 offset:49152
	ds_read_b128 v[200:203], v146 offset:50176
	ds_read_b128 v[204:207], v146 offset:51200
	ds_read_b128 v[208:211], v146 offset:52224
	global_load_lds_dwordx4 v[212:213], off
	v_lshl_add_u64 v[212:213], v[214:215], 0, s[0:1]
	s_mov_b32 m0, s28
	s_nop 0
	global_load_lds_dwordx4 v[212:213], off
	s_barrier
	s_waitcnt lgkmcnt(0)
	s_waitcnt lgkmcnt(0)
	v_mfma_f32_16x16x32_bf16 v[112:115], v[196:199], v[164:167], v[112:115]
	v_mfma_f32_16x16x32_bf16 v[104:107], v[204:207], v[164:167], v[104:107]
	v_mfma_f32_16x16x32_bf16 v[96:99], v[196:199], v[172:175], v[96:99]
	v_mfma_f32_16x16x32_bf16 v[88:91], v[204:207], v[172:175], v[88:91]
	v_mfma_f32_16x16x32_bf16 v[80:83], v[196:199], v[180:183], v[80:83]
	v_mfma_f32_16x16x32_bf16 v[72:75], v[204:207], v[180:183], v[72:75]
	v_mfma_f32_16x16x32_bf16 v[68:71], v[196:199], v[188:191], v[68:71]
	v_mfma_f32_16x16x32_bf16 v[64:67], v[204:207], v[188:191], v[64:67]
	v_mfma_f32_16x16x32_bf16 v[112:115], v[200:203], v[168:171], v[112:115]
	v_mfma_f32_16x16x32_bf16 v[104:107], v[208:211], v[168:171], v[104:107]
	v_mfma_f32_16x16x32_bf16 v[96:99], v[200:203], v[176:179], v[96:99]
	v_mfma_f32_16x16x32_bf16 v[88:91], v[208:211], v[176:179], v[88:91]
	v_mfma_f32_16x16x32_bf16 v[80:83], v[200:203], v[184:187], v[80:83]
	v_mfma_f32_16x16x32_bf16 v[72:75], v[208:211], v[184:187], v[72:75]
	v_mfma_f32_16x16x32_bf16 v[68:71], v[200:203], v[192:195], v[68:71]
	v_mfma_f32_16x16x32_bf16 v[64:67], v[208:211], v[192:195], v[64:67]
	s_mov_b32 m0, s29
	v_lshl_add_u64 v[212:213], v[216:217], 0, s[0:1]
	s_barrier
	ds_read_b128 v[164:167], v147 offset:49152
	ds_read_b128 v[168:171], v147 offset:50176
	ds_read_b128 v[172:175], v147 offset:51200
	ds_read_b128 v[176:179], v147 offset:52224
	ds_read_b128 v[180:183], v147 offset:53248
	ds_read_b128 v[184:187], v147 offset:54272
	ds_read_b128 v[188:191], v147 offset:55296
	ds_read_b128 v[192:195], v147 offset:56320
	global_load_lds_dwordx4 v[212:213], off
	v_lshl_add_u64 v[212:213], v[218:219], 0, s[0:1]
	s_mov_b32 m0, s30
	s_nop 0
	global_load_lds_dwordx4 v[212:213], off
	s_barrier
	s_waitcnt lgkmcnt(0)
	s_waitcnt lgkmcnt(0)
	v_mfma_f32_16x16x32_bf16 v[60:63], v[148:151], v[164:167], v[60:63]
	v_mfma_f32_16x16x32_bf16 v[56:59], v[156:159], v[164:167], v[56:59]
	v_mfma_f32_16x16x32_bf16 v[52:55], v[148:151], v[172:175], v[52:55]
	v_mfma_f32_16x16x32_bf16 v[44:47], v[156:159], v[172:175], v[44:47]
	v_mfma_f32_16x16x32_bf16 v[36:39], v[148:151], v[180:183], v[36:39]
	v_mfma_f32_16x16x32_bf16 v[28:31], v[156:159], v[180:183], v[28:31]
	v_mfma_f32_16x16x32_bf16 v[20:23], v[148:151], v[188:191], v[20:23]
	v_mfma_f32_16x16x32_bf16 v[12:15], v[156:159], v[188:191], v[12:15]
	v_mfma_f32_16x16x32_bf16 v[60:63], v[152:155], v[168:171], v[60:63]
	v_mfma_f32_16x16x32_bf16 v[56:59], v[160:163], v[168:171], v[56:59]
	v_mfma_f32_16x16x32_bf16 v[52:55], v[152:155], v[176:179], v[52:55]
	v_mfma_f32_16x16x32_bf16 v[44:47], v[160:163], v[176:179], v[44:47]
	v_mfma_f32_16x16x32_bf16 v[36:39], v[152:155], v[184:187], v[36:39]
	v_mfma_f32_16x16x32_bf16 v[28:31], v[160:163], v[184:187], v[28:31]
	v_mfma_f32_16x16x32_bf16 v[20:23], v[152:155], v[192:195], v[20:23]
	v_mfma_f32_16x16x32_bf16 v[12:15], v[160:163], v[192:195], v[12:15]
	s_barrier
	s_mov_b32 m0, s31
	v_lshl_add_u64 v[148:149], v[220:221], 0, s[0:1]
	global_load_lds_dwordx4 v[148:149], off
	v_lshl_add_u64 v[148:149], v[222:223], 0, s[0:1]
	s_mov_b32 m0, s33
	s_nop 0
	global_load_lds_dwordx4 v[148:149], off
	s_waitcnt vmcnt(6)
	s_barrier
	v_mfma_f32_16x16x32_bf16 v[48:51], v[196:199], v[164:167], v[48:51]
	v_mfma_f32_16x16x32_bf16 v[40:43], v[204:207], v[164:167], v[40:43]
	v_mfma_f32_16x16x32_bf16 v[32:35], v[196:199], v[172:175], v[32:35]
	v_mfma_f32_16x16x32_bf16 v[24:27], v[204:207], v[172:175], v[24:27]
	v_mfma_f32_16x16x32_bf16 v[16:19], v[196:199], v[180:183], v[16:19]
	v_mfma_f32_16x16x32_bf16 v[8:11], v[204:207], v[180:183], v[8:11]
	v_mfma_f32_16x16x32_bf16 v[4:7], v[196:199], v[188:191], v[4:7]
	v_mfma_f32_16x16x32_bf16 v[0:3], v[204:207], v[188:191], v[0:3]
	v_mfma_f32_16x16x32_bf16 v[48:51], v[200:203], v[168:171], v[48:51]
	v_mfma_f32_16x16x32_bf16 v[40:43], v[208:211], v[168:171], v[40:43]
	v_mfma_f32_16x16x32_bf16 v[32:35], v[200:203], v[176:179], v[32:35]
	v_mfma_f32_16x16x32_bf16 v[24:27], v[208:211], v[176:179], v[24:27]
	v_mfma_f32_16x16x32_bf16 v[16:19], v[200:203], v[184:187], v[16:19]
	v_mfma_f32_16x16x32_bf16 v[8:11], v[208:211], v[184:187], v[8:11]
	v_mfma_f32_16x16x32_bf16 v[4:7], v[200:203], v[192:195], v[4:7]
	v_mfma_f32_16x16x32_bf16 v[0:3], v[208:211], v[192:195], v[0:3]
	v_lshl_add_u64 v[140:141], v[140:141], 0, s[4:5]
	v_lshl_add_u64 v[142:143], v[142:143], 0, s[4:5]
	s_cmp_ge_u32 s76, s75
	s_mov_b32 s53, s76
	s_barrier
	s_cbranch_scc0 .LBB0_230
	s_andn2_b64 vcc, exec, s[10:11]
	s_cbranch_vccnz .LBB0_226
	s_bitset1_b32 s52, 7
	s_ashr_i32 s53, s52, 31
	s_lshl_b64 s[52:53], s[52:53], 9
	s_add_u32 s52, s9, s52
	s_addc_u32 s53, s16, s53
	v_lshl_add_u64 v[192:193], s[52:53], 0, v[134:135]
	s_mov_b32 m0, s62
	v_lshl_add_u64 v[192:193], v[192:193], 0, s[6:7]
	ds_read_b128 v[140:143], v146
	ds_read_b128 v[148:151], v146 offset:1024
	ds_read_b128 v[152:155], v146 offset:2048
	ds_read_b128 v[156:159], v146 offset:3072
	ds_read_b128 v[160:163], v147
	ds_read_b128 v[164:167], v147 offset:1024
	ds_read_b128 v[168:171], v147 offset:2048
	ds_read_b128 v[172:175], v147 offset:3072
	ds_read_b128 v[176:179], v147 offset:4096
	ds_read_b128 v[180:183], v147 offset:5120
	ds_read_b128 v[184:187], v147 offset:6144
	ds_read_b128 v[188:191], v147 offset:7168
	global_load_lds_dwordx4 v[192:193], off
	v_lshl_add_u64 v[192:193], s[52:53], 0, v[130:131]
	v_lshl_add_u64 v[192:193], v[192:193], 0, s[6:7]
	s_mov_b32 m0, s63
	s_nop 0
	global_load_lds_dwordx4 v[192:193], off
	s_barrier
	s_waitcnt lgkmcnt(0)
	s_waitcnt lgkmcnt(0)
	v_mfma_f32_16x16x32_bf16 v[124:127], v[140:143], v[160:163], v[124:127]
	v_mfma_f32_16x16x32_bf16 v[120:123], v[152:155], v[160:163], v[120:123]
	v_mfma_f32_16x16x32_bf16 v[116:119], v[140:143], v[168:171], v[116:119]
	v_mfma_f32_16x16x32_bf16 v[108:111], v[152:155], v[168:171], v[108:111]
	v_mfma_f32_16x16x32_bf16 v[100:103], v[140:143], v[176:179], v[100:103]
	v_mfma_f32_16x16x32_bf16 v[92:95], v[152:155], v[176:179], v[92:95]
	v_mfma_f32_16x16x32_bf16 v[84:87], v[140:143], v[184:187], v[84:87]
	v_mfma_f32_16x16x32_bf16 v[76:79], v[152:155], v[184:187], v[76:79]
	v_mfma_f32_16x16x32_bf16 v[124:127], v[148:151], v[164:167], v[124:127]
	v_mfma_f32_16x16x32_bf16 v[120:123], v[156:159], v[164:167], v[120:123]
	v_mfma_f32_16x16x32_bf16 v[116:119], v[148:151], v[172:175], v[116:119]
	v_mfma_f32_16x16x32_bf16 v[108:111], v[156:159], v[172:175], v[108:111]
	v_mfma_f32_16x16x32_bf16 v[100:103], v[148:151], v[180:183], v[100:103]
	v_mfma_f32_16x16x32_bf16 v[92:95], v[156:159], v[180:183], v[92:95]
	v_mfma_f32_16x16x32_bf16 v[84:87], v[148:151], v[188:191], v[84:87]
	v_mfma_f32_16x16x32_bf16 v[76:79], v[156:159], v[188:191], v[76:79]
	s_barrier
	ds_read_b128 v[192:195], v146 offset:16384
	ds_read_b128 v[196:199], v146 offset:17408
	ds_read_b128 v[200:203], v146 offset:18432
	ds_read_b128 v[204:207], v146 offset:19456
	s_barrier
	s_waitcnt lgkmcnt(0)
	s_waitcnt lgkmcnt(0)
	v_mfma_f32_16x16x32_bf16 v[112:115], v[192:195], v[160:163], v[112:115]
	v_mfma_f32_16x16x32_bf16 v[104:107], v[200:203], v[160:163], v[104:107]
	v_mfma_f32_16x16x32_bf16 v[96:99], v[192:195], v[168:171], v[96:99]
	v_mfma_f32_16x16x32_bf16 v[88:91], v[200:203], v[168:171], v[88:91]
	v_mfma_f32_16x16x32_bf16 v[80:83], v[192:195], v[176:179], v[80:83]
	v_mfma_f32_16x16x32_bf16 v[72:75], v[200:203], v[176:179], v[72:75]
	v_mfma_f32_16x16x32_bf16 v[68:71], v[192:195], v[184:187], v[68:71]
	v_mfma_f32_16x16x32_bf16 v[64:67], v[200:203], v[184:187], v[64:67]
	v_mfma_f32_16x16x32_bf16 v[112:115], v[196:199], v[164:167], v[112:115]
	v_mfma_f32_16x16x32_bf16 v[104:107], v[204:207], v[164:167], v[104:107]
	v_mfma_f32_16x16x32_bf16 v[96:99], v[196:199], v[172:175], v[96:99]
	v_mfma_f32_16x16x32_bf16 v[88:91], v[204:207], v[172:175], v[88:91]
	v_mfma_f32_16x16x32_bf16 v[80:83], v[196:199], v[180:183], v[80:83]
	v_mfma_f32_16x16x32_bf16 v[72:75], v[204:207], v[180:183], v[72:75]
	v_mfma_f32_16x16x32_bf16 v[68:71], v[196:199], v[188:191], v[68:71]
	v_mfma_f32_16x16x32_bf16 v[64:67], v[204:207], v[188:191], v[64:67]
	s_barrier
	ds_read_b128 v[160:163], v147 offset:16384
	ds_read_b128 v[164:167], v147 offset:17408
	ds_read_b128 v[168:171], v147 offset:18432
	ds_read_b128 v[172:175], v147 offset:19456
	ds_read_b128 v[176:179], v147 offset:20480
	ds_read_b128 v[180:183], v147 offset:21504
	ds_read_b128 v[184:187], v147 offset:22528
	ds_read_b128 v[188:191], v147 offset:23552
	s_waitcnt vmcnt(4)
	s_barrier
	s_waitcnt lgkmcnt(0)
	s_waitcnt lgkmcnt(0)
	v_mfma_f32_16x16x32_bf16 v[60:63], v[140:143], v[160:163], v[60:63]
	v_mfma_f32_16x16x32_bf16 v[56:59], v[152:155], v[160:163], v[56:59]
	v_mfma_f32_16x16x32_bf16 v[52:55], v[140:143], v[168:171], v[52:55]
	v_mfma_f32_16x16x32_bf16 v[44:47], v[152:155], v[168:171], v[44:47]
	v_mfma_f32_16x16x32_bf16 v[36:39], v[140:143], v[176:179], v[36:39]
	v_mfma_f32_16x16x32_bf16 v[28:31], v[152:155], v[176:179], v[28:31]
	v_mfma_f32_16x16x32_bf16 v[20:23], v[140:143], v[184:187], v[20:23]
	v_mfma_f32_16x16x32_bf16 v[12:15], v[152:155], v[184:187], v[12:15]
	v_mfma_f32_16x16x32_bf16 v[60:63], v[148:151], v[164:167], v[60:63]
	v_mfma_f32_16x16x32_bf16 v[56:59], v[156:159], v[164:167], v[56:59]
	v_mfma_f32_16x16x32_bf16 v[52:55], v[148:151], v[172:175], v[52:55]
	v_mfma_f32_16x16x32_bf16 v[44:47], v[156:159], v[172:175], v[44:47]
	v_mfma_f32_16x16x32_bf16 v[36:39], v[148:151], v[180:183], v[36:39]
	v_mfma_f32_16x16x32_bf16 v[28:31], v[156:159], v[180:183], v[28:31]
	v_mfma_f32_16x16x32_bf16 v[20:23], v[148:151], v[188:191], v[20:23]
	v_mfma_f32_16x16x32_bf16 v[12:15], v[156:159], v[188:191], v[12:15]
	v_mfma_f32_16x16x32_bf16 v[48:51], v[192:195], v[160:163], v[48:51]
	v_mfma_f32_16x16x32_bf16 v[40:43], v[200:203], v[160:163], v[40:43]
	v_mfma_f32_16x16x32_bf16 v[32:35], v[192:195], v[168:171], v[32:35]
	v_mfma_f32_16x16x32_bf16 v[24:27], v[200:203], v[168:171], v[24:27]
	v_mfma_f32_16x16x32_bf16 v[16:19], v[192:195], v[176:179], v[16:19]
	v_mfma_f32_16x16x32_bf16 v[8:11], v[200:203], v[176:179], v[8:11]
	v_mfma_f32_16x16x32_bf16 v[4:7], v[192:195], v[184:187], v[4:7]
	v_mfma_f32_16x16x32_bf16 v[0:3], v[200:203], v[184:187], v[0:3]
	v_mfma_f32_16x16x32_bf16 v[48:51], v[196:199], v[164:167], v[48:51]
	v_mfma_f32_16x16x32_bf16 v[40:43], v[204:207], v[164:167], v[40:43]
	v_mfma_f32_16x16x32_bf16 v[32:35], v[196:199], v[172:175], v[32:35]
	v_mfma_f32_16x16x32_bf16 v[24:27], v[204:207], v[172:175], v[24:27]
	v_mfma_f32_16x16x32_bf16 v[16:19], v[196:199], v[180:183], v[16:19]
	v_mfma_f32_16x16x32_bf16 v[8:11], v[204:207], v[180:183], v[8:11]
	v_mfma_f32_16x16x32_bf16 v[4:7], v[196:199], v[188:191], v[4:7]
	v_mfma_f32_16x16x32_bf16 v[0:3], v[204:207], v[188:191], v[0:3]
	s_barrier
	ds_read_b128 v[140:143], v146 offset:32768
	ds_read_b128 v[148:151], v146 offset:33792
	ds_read_b128 v[152:155], v146 offset:34816
	ds_read_b128 v[156:159], v146 offset:35840
	ds_read_b128 v[160:163], v147 offset:32768
	ds_read_b128 v[164:167], v147 offset:33792
	ds_read_b128 v[168:171], v147 offset:34816
	ds_read_b128 v[172:175], v147 offset:35840
	ds_read_b128 v[176:179], v147 offset:36864
	ds_read_b128 v[180:183], v147 offset:37888
	ds_read_b128 v[184:187], v147 offset:38912
	ds_read_b128 v[188:191], v147 offset:39936
	s_waitcnt vmcnt(2)
	s_barrier
	s_waitcnt lgkmcnt(0)
	s_waitcnt lgkmcnt(0)
	v_mfma_f32_16x16x32_bf16 v[124:127], v[140:143], v[160:163], v[124:127]
	v_mfma_f32_16x16x32_bf16 v[120:123], v[152:155], v[160:163], v[120:123]
	v_mfma_f32_16x16x32_bf16 v[116:119], v[140:143], v[168:171], v[116:119]
	v_mfma_f32_16x16x32_bf16 v[108:111], v[152:155], v[168:171], v[108:111]
	v_mfma_f32_16x16x32_bf16 v[100:103], v[140:143], v[176:179], v[100:103]
	v_mfma_f32_16x16x32_bf16 v[92:95], v[152:155], v[176:179], v[92:95]
	v_mfma_f32_16x16x32_bf16 v[84:87], v[140:143], v[184:187], v[84:87]
	v_mfma_f32_16x16x32_bf16 v[76:79], v[152:155], v[184:187], v[76:79]
	v_mfma_f32_16x16x32_bf16 v[124:127], v[148:151], v[164:167], v[124:127]
	v_mfma_f32_16x16x32_bf16 v[120:123], v[156:159], v[164:167], v[120:123]
	v_mfma_f32_16x16x32_bf16 v[116:119], v[148:151], v[172:175], v[116:119]
	v_mfma_f32_16x16x32_bf16 v[108:111], v[156:159], v[172:175], v[108:111]
	v_mfma_f32_16x16x32_bf16 v[100:103], v[148:151], v[180:183], v[100:103]
	v_mfma_f32_16x16x32_bf16 v[92:95], v[156:159], v[180:183], v[92:95]
	v_mfma_f32_16x16x32_bf16 v[84:87], v[148:151], v[188:191], v[84:87]
	v_mfma_f32_16x16x32_bf16 v[76:79], v[156:159], v[188:191], v[76:79]
	s_barrier
	ds_read_b128 v[192:195], v146 offset:49152
	ds_read_b128 v[196:199], v146 offset:50176
	ds_read_b128 v[200:203], v146 offset:51200
	ds_read_b128 v[204:207], v146 offset:52224
	s_waitcnt vmcnt(0)
	s_barrier
	s_waitcnt lgkmcnt(0)
	s_waitcnt lgkmcnt(0)
	v_mfma_f32_16x16x32_bf16 v[112:115], v[192:195], v[160:163], v[112:115]
	v_mfma_f32_16x16x32_bf16 v[104:107], v[200:203], v[160:163], v[104:107]
	v_mfma_f32_16x16x32_bf16 v[96:99], v[192:195], v[168:171], v[96:99]
	v_mfma_f32_16x16x32_bf16 v[88:91], v[200:203], v[168:171], v[88:91]
	v_mfma_f32_16x16x32_bf16 v[80:83], v[192:195], v[176:179], v[80:83]
	v_mfma_f32_16x16x32_bf16 v[72:75], v[200:203], v[176:179], v[72:75]
	v_mfma_f32_16x16x32_bf16 v[68:71], v[192:195], v[184:187], v[68:71]
	v_mfma_f32_16x16x32_bf16 v[64:67], v[200:203], v[184:187], v[64:67]
	v_mfma_f32_16x16x32_bf16 v[112:115], v[196:199], v[164:167], v[112:115]
	v_mfma_f32_16x16x32_bf16 v[104:107], v[204:207], v[164:167], v[104:107]
	v_mfma_f32_16x16x32_bf16 v[96:99], v[196:199], v[172:175], v[96:99]
	v_mfma_f32_16x16x32_bf16 v[88:91], v[204:207], v[172:175], v[88:91]
	v_mfma_f32_16x16x32_bf16 v[80:83], v[196:199], v[180:183], v[80:83]
	v_mfma_f32_16x16x32_bf16 v[72:75], v[204:207], v[180:183], v[72:75]
	v_mfma_f32_16x16x32_bf16 v[68:71], v[196:199], v[188:191], v[68:71]
	v_mfma_f32_16x16x32_bf16 v[64:67], v[204:207], v[188:191], v[64:67]
	s_barrier
	ds_read_b128 v[160:163], v147 offset:49152
	ds_read_b128 v[164:167], v147 offset:50176
	ds_read_b128 v[168:171], v147 offset:51200
	ds_read_b128 v[172:175], v147 offset:52224
	ds_read_b128 v[176:179], v147 offset:53248
	ds_read_b128 v[180:183], v147 offset:54272
	ds_read_b128 v[184:187], v147 offset:55296
	ds_read_b128 v[188:191], v147 offset:56320
	s_barrier
	s_waitcnt lgkmcnt(0)
	s_waitcnt lgkmcnt(0)
	v_mfma_f32_16x16x32_bf16 v[60:63], v[140:143], v[160:163], v[60:63]
	v_mfma_f32_16x16x32_bf16 v[56:59], v[152:155], v[160:163], v[56:59]
	v_mfma_f32_16x16x32_bf16 v[52:55], v[140:143], v[168:171], v[52:55]
	v_mfma_f32_16x16x32_bf16 v[44:47], v[152:155], v[168:171], v[44:47]
	v_mfma_f32_16x16x32_bf16 v[36:39], v[140:143], v[176:179], v[36:39]
	v_mfma_f32_16x16x32_bf16 v[28:31], v[152:155], v[176:179], v[28:31]
	v_mfma_f32_16x16x32_bf16 v[20:23], v[140:143], v[184:187], v[20:23]
	v_mfma_f32_16x16x32_bf16 v[12:15], v[152:155], v[184:187], v[12:15]
	v_mfma_f32_16x16x32_bf16 v[60:63], v[148:151], v[164:167], v[60:63]
	v_mfma_f32_16x16x32_bf16 v[56:59], v[156:159], v[164:167], v[56:59]
	v_mfma_f32_16x16x32_bf16 v[52:55], v[148:151], v[172:175], v[52:55]
	v_mfma_f32_16x16x32_bf16 v[44:47], v[156:159], v[172:175], v[44:47]
	v_mfma_f32_16x16x32_bf16 v[36:39], v[148:151], v[180:183], v[36:39]
	v_mfma_f32_16x16x32_bf16 v[28:31], v[156:159], v[180:183], v[28:31]
	v_mfma_f32_16x16x32_bf16 v[20:23], v[148:151], v[188:191], v[20:23]
	v_mfma_f32_16x16x32_bf16 v[12:15], v[156:159], v[188:191], v[12:15]
	v_mfma_f32_16x16x32_bf16 v[48:51], v[192:195], v[160:163], v[48:51]
	v_mfma_f32_16x16x32_bf16 v[40:43], v[200:203], v[160:163], v[40:43]
	v_mfma_f32_16x16x32_bf16 v[32:35], v[192:195], v[168:171], v[32:35]
	v_mfma_f32_16x16x32_bf16 v[24:27], v[200:203], v[168:171], v[24:27]
	v_mfma_f32_16x16x32_bf16 v[16:19], v[192:195], v[176:179], v[16:19]
	v_mfma_f32_16x16x32_bf16 v[8:11], v[200:203], v[176:179], v[8:11]
	v_mfma_f32_16x16x32_bf16 v[4:7], v[192:195], v[184:187], v[4:7]
	v_mfma_f32_16x16x32_bf16 v[0:3], v[200:203], v[184:187], v[0:3]
	v_mfma_f32_16x16x32_bf16 v[48:51], v[196:199], v[164:167], v[48:51]
	v_mfma_f32_16x16x32_bf16 v[40:43], v[204:207], v[164:167], v[40:43]
	v_mfma_f32_16x16x32_bf16 v[32:35], v[196:199], v[172:175], v[32:35]
	v_mfma_f32_16x16x32_bf16 v[24:27], v[204:207], v[172:175], v[24:27]
	v_mfma_f32_16x16x32_bf16 v[16:19], v[196:199], v[180:183], v[16:19]
	v_mfma_f32_16x16x32_bf16 v[8:11], v[204:207], v[180:183], v[8:11]
	v_mfma_f32_16x16x32_bf16 v[4:7], v[196:199], v[188:191], v[4:7]
	v_mfma_f32_16x16x32_bf16 v[0:3], v[204:207], v[188:191], v[0:3]
	s_barrier
	s_branch .LBB0_226

.LBB0_243:
	s_or_b64 exec, exec, s[8:9]
	s_add_i32 s58, s58, s13
	s_cmpk_gt_i32 s58, 0x2ff
	s_cselect_b64 s[8:9], -1, 0
	s_and_b64 vcc, exec, s[8:9]
	s_cbranch_vccnz .LBB0_238
	s_ashr_i32 s11, s58, 31
	s_lshr_b32 s11, s11, 29
	s_add_i32 s11, s58, s11
	s_ashr_i32 s53, s11, 3
	s_and_b32 s11, s11, -8
	s_sub_i32 s11, s58, s11
	s_cmp_lt_i32 s11, 0
	s_cselect_b32 s59, s21, 0x60
	s_mul_i32 s11, s59, s11
	s_add_i32 s11, s11, s53
	s_ashr_i32 s53, s11, 31
	s_lshr_b32 s53, s53, 27
	s_add_i32 s53, s11, s53
	s_and_b32 s59, s53, 0xffe0
	s_sub_i32 s11, s11, s59
	s_bfe_i32 s59, s11, 0x80000
	s_bfe_u32 s59, s59, 0x3000c
	s_add_i32 s59, s11, s59
	s_bfe_i32 s60, s59, 0x80000
	s_and_b32 s59, s59, 0xf8
	s_sub_i32 s11, s11, s59
	s_sext_i32_i8 s11, s11
	s_lshl_b32 s53, s53, 6
	s_sext_i32_i16 s61, s60
	s_and_b32 s53, s53, 0xfffff800
	s_lshl_b32 s11, s11, 8
	s_add_i32 s60, s11, s53
	s_lshl_b32 s11, s61, 5
	s_and_b32 s62, s11, 0xffffff00
	s_ashr_i32 s63, s62, 31
	s_lshl_b64 s[64:65], s[62:63], 8
	s_add_u32 s64, s18, s64
	s_addc_u32 s65, s19, s65
	s_mov_b32 m0, s22
	v_lshl_add_u64 v[136:137], s[64:65], 0, v[132:133]
	s_ashr_i32 s61, s60, 31
	global_load_lds_dwordx4 v[136:137], off
	v_lshl_add_u64 v[136:137], s[64:65], 0, v[128:129]
	s_lshl_b64 s[64:65], s[60:61], 8
	s_add_u32 s64, s16, s64
	s_addc_u32 s65, s17, s65
	s_bitset1_b32 s62, 7
	s_ashr_i32 s63, s62, 31
	s_lshl_b64 s[62:63], s[62:63], 8
	s_add_u32 s62, s18, s62
	s_mov_b32 m0, s23
	s_addc_u32 s63, s19, s63
	s_bitset1_b32 s60, 7
	global_load_lds_dwordx4 v[136:137], off
	v_lshl_add_u64 v[136:137], s[64:65], 0, v[134:135]
	s_mov_b32 m0, s20
	s_ashr_i32 s61, s60, 31
	global_load_lds_dwordx4 v[136:137], off
	v_lshl_add_u64 v[136:137], s[64:65], 0, v[130:131]
	s_mov_b32 m0, s24
	s_lshl_b64 s[60:61], s[60:61], 8
	global_load_lds_dwordx4 v[136:137], off
	v_lshl_add_u64 v[136:137], s[62:63], 0, v[132:133]
	s_mov_b32 m0, s25
	s_add_u32 s60, s16, s60
	global_load_lds_dwordx4 v[136:137], off
	v_lshl_add_u64 v[136:137], s[62:63], 0, v[128:129]
	s_mov_b32 m0, s26
	s_addc_u32 s61, s17, s61
	global_load_lds_dwordx4 v[136:137], off
	s_mov_b32 m0, s27
	s_nop 0
	global_load_lds_dwordx4 v134, s[60:61]
	s_mov_b32 m0, s28
	s_nop 0
	global_load_lds_dwordx4 v130, s[60:61]
	s_branch .LBB0_238

.LBB0_321:
	ds_read_b128 v[148:151], v146
	ds_read_b128 v[152:155], v146 offset:1024
	ds_read_b128 v[156:159], v146 offset:2048
	ds_read_b128 v[160:163], v146 offset:3072
	s_add_i32 s11, s2, 2
	s_cmp_gt_u32 s2, 13
	s_cselect_b32 s58, s74, s52
	s_cselect_b32 s54, s73, s10
	s_mov_b32 m0, s62
	ds_read_b128 v[164:167], v147
	ds_read_b128 v[168:171], v147 offset:1024
	ds_read_b128 v[172:175], v147 offset:2048
	ds_read_b128 v[176:179], v147 offset:3072
	ds_read_b128 v[180:183], v147 offset:4096
	ds_read_b128 v[184:187], v147 offset:5120
	ds_read_b128 v[188:191], v147 offset:6144
	ds_read_b128 v[192:195], v147 offset:7168
	global_load_lds_dwordx4 v[140:141], off
	s_mov_b32 m0, s63
	s_nop 0
	global_load_lds_dwordx4 v[142:143], off
	s_waitcnt lgkmcnt(8)
	s_barrier
	s_waitcnt lgkmcnt(0)
	s_waitcnt lgkmcnt(0)
	v_mfma_f32_16x16x32_bf16 v[124:127], v[148:151], v[164:167], v[124:127]
	v_mfma_f32_16x16x32_bf16 v[120:123], v[156:159], v[164:167], v[120:123]
	v_mfma_f32_16x16x32_bf16 v[116:119], v[148:151], v[172:175], v[116:119]
	v_mfma_f32_16x16x32_bf16 v[112:115], v[156:159], v[172:175], v[112:115]
	v_mfma_f32_16x16x32_bf16 v[100:103], v[148:151], v[180:183], v[100:103]
	v_mfma_f32_16x16x32_bf16 v[96:99], v[156:159], v[180:183], v[96:99]
	v_mfma_f32_16x16x32_bf16 v[84:87], v[148:151], v[188:191], v[84:87]
	v_mfma_f32_16x16x32_bf16 v[80:83], v[156:159], v[188:191], v[80:83]
	v_mfma_f32_16x16x32_bf16 v[124:127], v[152:155], v[168:171], v[124:127]
	v_mfma_f32_16x16x32_bf16 v[120:123], v[160:163], v[168:171], v[120:123]
	v_mfma_f32_16x16x32_bf16 v[116:119], v[152:155], v[176:179], v[116:119]
	v_mfma_f32_16x16x32_bf16 v[112:115], v[160:163], v[176:179], v[112:115]
	v_mfma_f32_16x16x32_bf16 v[100:103], v[152:155], v[184:187], v[100:103]
	v_mfma_f32_16x16x32_bf16 v[96:99], v[160:163], v[184:187], v[96:99]
	v_mfma_f32_16x16x32_bf16 v[84:87], v[152:155], v[192:195], v[84:87]
	v_mfma_f32_16x16x32_bf16 v[80:83], v[160:163], v[192:195], v[80:83]
	s_barrier
	s_cselect_b32 s2, 0, s11
	s_ashr_i32 s59, s58, 31
	s_lshl_b64 s[56:57], s[58:59], 11
	s_add_u32 s78, s18, s56
	s_addc_u32 s79, s19, s57
	s_lshl_b64 s[56:57], s[2:3], 7
	s_add_u32 s76, s78, s56
	s_addc_u32 s77, s79, s57
	s_mov_b32 m0, s21
	ds_read_b128 v[196:199], v146 offset:16384
	ds_read_b128 v[200:203], v146 offset:17408
	ds_read_b128 v[204:207], v146 offset:18432
	ds_read_b128 v[208:211], v146 offset:19456
	global_load_lds_dwordx4 v132, s[76:77]
	s_mov_b32 m0, s22
	s_nop 0
	global_load_lds_dwordx4 v128, s[76:77]
	s_barrier
	s_waitcnt lgkmcnt(0)
	s_waitcnt lgkmcnt(0)
	v_mfma_f32_16x16x32_bf16 v[108:111], v[196:199], v[164:167], v[108:111]
	v_mfma_f32_16x16x32_bf16 v[104:107], v[204:207], v[164:167], v[104:107]
	v_mfma_f32_16x16x32_bf16 v[92:95], v[196:199], v[172:175], v[92:95]
	v_mfma_f32_16x16x32_bf16 v[88:91], v[204:207], v[172:175], v[88:91]
	v_mfma_f32_16x16x32_bf16 v[76:79], v[196:199], v[180:183], v[76:79]
	v_mfma_f32_16x16x32_bf16 v[72:75], v[204:207], v[180:183], v[72:75]
	v_mfma_f32_16x16x32_bf16 v[68:71], v[196:199], v[188:191], v[68:71]
	v_mfma_f32_16x16x32_bf16 v[64:67], v[204:207], v[188:191], v[64:67]
	v_mfma_f32_16x16x32_bf16 v[108:111], v[200:203], v[168:171], v[108:111]
	v_mfma_f32_16x16x32_bf16 v[104:107], v[208:211], v[168:171], v[104:107]
	v_mfma_f32_16x16x32_bf16 v[92:95], v[200:203], v[176:179], v[92:95]
	v_mfma_f32_16x16x32_bf16 v[88:91], v[208:211], v[176:179], v[88:91]
	v_mfma_f32_16x16x32_bf16 v[76:79], v[200:203], v[184:187], v[76:79]
	v_mfma_f32_16x16x32_bf16 v[72:75], v[208:211], v[184:187], v[72:75]
	v_mfma_f32_16x16x32_bf16 v[68:71], v[200:203], v[192:195], v[68:71]
	v_mfma_f32_16x16x32_bf16 v[64:67], v[208:211], v[192:195], v[64:67]
	s_ashr_i32 s55, s54, 31
	s_lshl_b64 s[76:77], s[54:55], 11
	s_add_u32 s80, s16, s76
	s_addc_u32 s81, s17, s77
	s_add_u32 s76, s80, s56
	s_addc_u32 s77, s81, s57
	s_mov_b32 m0, s20
	s_barrier
	ds_read_b128 v[164:167], v147 offset:16384
	ds_read_b128 v[168:171], v147 offset:17408
	ds_read_b128 v[172:175], v147 offset:18432
	ds_read_b128 v[176:179], v147 offset:19456
	ds_read_b128 v[180:183], v147 offset:20480
	ds_read_b128 v[184:187], v147 offset:21504
	ds_read_b128 v[188:191], v147 offset:22528
	ds_read_b128 v[192:195], v147 offset:23552
	global_load_lds_dwordx4 v134, s[76:77]
	s_mov_b32 m0, s23
	s_nop 0
	global_load_lds_dwordx4 v130, s[76:77]
	s_barrier
	s_waitcnt lgkmcnt(0)
	s_waitcnt lgkmcnt(0)
	v_mfma_f32_16x16x32_bf16 v[60:63], v[148:151], v[164:167], v[60:63]
	v_mfma_f32_16x16x32_bf16 v[56:59], v[156:159], v[164:167], v[56:59]
	v_mfma_f32_16x16x32_bf16 v[52:55], v[148:151], v[172:175], v[52:55]
	v_mfma_f32_16x16x32_bf16 v[48:51], v[156:159], v[172:175], v[48:51]
	v_mfma_f32_16x16x32_bf16 v[36:39], v[148:151], v[180:183], v[36:39]
	v_mfma_f32_16x16x32_bf16 v[32:35], v[156:159], v[180:183], v[32:35]
	v_mfma_f32_16x16x32_bf16 v[20:23], v[148:151], v[188:191], v[20:23]
	v_mfma_f32_16x16x32_bf16 v[16:19], v[156:159], v[188:191], v[16:19]
	v_mfma_f32_16x16x32_bf16 v[60:63], v[152:155], v[168:171], v[60:63]
	v_mfma_f32_16x16x32_bf16 v[56:59], v[160:163], v[168:171], v[56:59]
	v_mfma_f32_16x16x32_bf16 v[52:55], v[152:155], v[176:179], v[52:55]
	v_mfma_f32_16x16x32_bf16 v[48:51], v[160:163], v[176:179], v[48:51]
	v_mfma_f32_16x16x32_bf16 v[36:39], v[152:155], v[184:187], v[36:39]
	v_mfma_f32_16x16x32_bf16 v[32:35], v[160:163], v[184:187], v[32:35]
	v_mfma_f32_16x16x32_bf16 v[20:23], v[152:155], v[192:195], v[20:23]
	v_mfma_f32_16x16x32_bf16 v[16:19], v[160:163], v[192:195], v[16:19]
	s_barrier
	s_bitset1_b32 s58, 7
	s_ashr_i32 s59, s58, 31
	s_lshl_b64 s[58:59], s[58:59], 11
	s_add_u32 s76, s18, s58
	s_addc_u32 s77, s19, s59
	s_add_u32 s58, s76, s56
	s_addc_u32 s59, s77, s57
	s_mov_b32 m0, s24
	s_nop 0
	global_load_lds_dwordx4 v132, s[58:59]
	s_mov_b32 m0, s25
	s_nop 0
	global_load_lds_dwordx4 v128, s[58:59]
	s_waitcnt vmcnt(6)
	s_barrier
	v_mfma_f32_16x16x32_bf16 v[44:47], v[196:199], v[164:167], v[44:47]
	v_mfma_f32_16x16x32_bf16 v[40:43], v[204:207], v[164:167], v[40:43]
	v_mfma_f32_16x16x32_bf16 v[28:31], v[196:199], v[172:175], v[28:31]
	v_mfma_f32_16x16x32_bf16 v[24:27], v[204:207], v[172:175], v[24:27]
	v_mfma_f32_16x16x32_bf16 v[12:15], v[196:199], v[180:183], v[12:15]
	v_mfma_f32_16x16x32_bf16 v[8:11], v[204:207], v[180:183], v[8:11]
	v_mfma_f32_16x16x32_bf16 v[4:7], v[196:199], v[188:191], v[4:7]
	v_mfma_f32_16x16x32_bf16 v[0:3], v[204:207], v[188:191], v[0:3]
	v_mfma_f32_16x16x32_bf16 v[44:47], v[200:203], v[168:171], v[44:47]
	v_mfma_f32_16x16x32_bf16 v[40:43], v[208:211], v[168:171], v[40:43]
	v_mfma_f32_16x16x32_bf16 v[28:31], v[200:203], v[176:179], v[28:31]
	v_mfma_f32_16x16x32_bf16 v[24:27], v[208:211], v[176:179], v[24:27]
	v_mfma_f32_16x16x32_bf16 v[12:15], v[200:203], v[184:187], v[12:15]
	v_mfma_f32_16x16x32_bf16 v[8:11], v[208:211], v[184:187], v[8:11]
	v_mfma_f32_16x16x32_bf16 v[4:7], v[200:203], v[192:195], v[4:7]
	v_mfma_f32_16x16x32_bf16 v[0:3], v[208:211], v[192:195], v[0:3]
	s_barrier
	ds_read_b128 v[148:151], v146 offset:32768
	ds_read_b128 v[152:155], v146 offset:33792
	ds_read_b128 v[156:159], v146 offset:34816
	ds_read_b128 v[160:163], v146 offset:35840
	s_bitset1_b32 s54, 7
	s_ashr_i32 s55, s54, 31
	s_lshl_b64 s[54:55], s[54:55], 11
	s_add_u32 s54, s16, s54
	s_addc_u32 s55, s17, s55
	s_add_u32 s54, s54, s56
	s_addc_u32 s55, s55, s57
	s_mov_b32 m0, s26
	ds_read_b128 v[164:167], v147 offset:32768
	ds_read_b128 v[168:171], v147 offset:33792
	ds_read_b128 v[172:175], v147 offset:34816
	ds_read_b128 v[176:179], v147 offset:35840
	ds_read_b128 v[180:183], v147 offset:36864
	ds_read_b128 v[184:187], v147 offset:37888
	ds_read_b128 v[188:191], v147 offset:38912
	ds_read_b128 v[192:195], v147 offset:39936
	global_load_lds_dwordx4 v134, s[54:55]
	s_mov_b32 m0, s27
	s_nop 0
	global_load_lds_dwordx4 v130, s[54:55]
	s_waitcnt lgkmcnt(8)
	s_barrier
	s_waitcnt lgkmcnt(0)
	s_waitcnt lgkmcnt(0)
	v_mfma_f32_16x16x32_bf16 v[124:127], v[148:151], v[164:167], v[124:127]
	v_mfma_f32_16x16x32_bf16 v[120:123], v[156:159], v[164:167], v[120:123]
	v_mfma_f32_16x16x32_bf16 v[116:119], v[148:151], v[172:175], v[116:119]
	v_mfma_f32_16x16x32_bf16 v[112:115], v[156:159], v[172:175], v[112:115]
	v_mfma_f32_16x16x32_bf16 v[100:103], v[148:151], v[180:183], v[100:103]
	v_mfma_f32_16x16x32_bf16 v[96:99], v[156:159], v[180:183], v[96:99]
	v_mfma_f32_16x16x32_bf16 v[84:87], v[148:151], v[188:191], v[84:87]
	v_mfma_f32_16x16x32_bf16 v[80:83], v[156:159], v[188:191], v[80:83]
	v_mfma_f32_16x16x32_bf16 v[124:127], v[152:155], v[168:171], v[124:127]
	v_mfma_f32_16x16x32_bf16 v[120:123], v[160:163], v[168:171], v[120:123]
	v_mfma_f32_16x16x32_bf16 v[116:119], v[152:155], v[176:179], v[116:119]
	v_mfma_f32_16x16x32_bf16 v[112:115], v[160:163], v[176:179], v[112:115]
	v_mfma_f32_16x16x32_bf16 v[100:103], v[152:155], v[184:187], v[100:103]
	v_mfma_f32_16x16x32_bf16 v[96:99], v[160:163], v[184:187], v[96:99]
	v_mfma_f32_16x16x32_bf16 v[84:87], v[152:155], v[192:195], v[84:87]
	v_mfma_f32_16x16x32_bf16 v[80:83], v[160:163], v[192:195], v[80:83]
	s_barrier
	s_or_b32 s2, s2, 1
	s_lshl_b64 s[54:55], s[2:3], 7
	s_add_u32 s56, s78, s54
	s_addc_u32 s57, s79, s55
	s_mov_b32 m0, s28
	ds_read_b128 v[196:199], v146 offset:49152
	ds_read_b128 v[200:203], v146 offset:50176
	ds_read_b128 v[204:207], v146 offset:51200
	ds_read_b128 v[208:211], v146 offset:52224
	global_load_lds_dwordx4 v132, s[56:57]
	s_mov_b32 m0, s29
	s_nop 0
	global_load_lds_dwordx4 v128, s[56:57]
	s_barrier
	s_waitcnt lgkmcnt(0)
	s_waitcnt lgkmcnt(0)
	v_mfma_f32_16x16x32_bf16 v[108:111], v[196:199], v[164:167], v[108:111]
	v_mfma_f32_16x16x32_bf16 v[104:107], v[204:207], v[164:167], v[104:107]
	v_mfma_f32_16x16x32_bf16 v[92:95], v[196:199], v[172:175], v[92:95]
	v_mfma_f32_16x16x32_bf16 v[88:91], v[204:207], v[172:175], v[88:91]
	v_mfma_f32_16x16x32_bf16 v[76:79], v[196:199], v[180:183], v[76:79]
	v_mfma_f32_16x16x32_bf16 v[72:75], v[204:207], v[180:183], v[72:75]
	v_mfma_f32_16x16x32_bf16 v[68:71], v[196:199], v[188:191], v[68:71]
	v_mfma_f32_16x16x32_bf16 v[64:67], v[204:207], v[188:191], v[64:67]
	v_mfma_f32_16x16x32_bf16 v[108:111], v[200:203], v[168:171], v[108:111]
	v_mfma_f32_16x16x32_bf16 v[104:107], v[208:211], v[168:171], v[104:107]
	v_mfma_f32_16x16x32_bf16 v[92:95], v[200:203], v[176:179], v[92:95]
	v_mfma_f32_16x16x32_bf16 v[88:91], v[208:211], v[176:179], v[88:91]
	v_mfma_f32_16x16x32_bf16 v[76:79], v[200:203], v[184:187], v[76:79]
	v_mfma_f32_16x16x32_bf16 v[72:75], v[208:211], v[184:187], v[72:75]
	v_mfma_f32_16x16x32_bf16 v[68:71], v[200:203], v[192:195], v[68:71]
	v_mfma_f32_16x16x32_bf16 v[64:67], v[208:211], v[192:195], v[64:67]
	s_add_u32 s56, s80, s54
	s_addc_u32 s57, s81, s55
	s_mov_b32 m0, s30
	s_barrier
	ds_read_b128 v[164:167], v147 offset:49152
	ds_read_b128 v[168:171], v147 offset:50176
	ds_read_b128 v[172:175], v147 offset:51200
	ds_read_b128 v[176:179], v147 offset:52224
	ds_read_b128 v[180:183], v147 offset:53248
	ds_read_b128 v[184:187], v147 offset:54272
	ds_read_b128 v[188:191], v147 offset:55296
	ds_read_b128 v[192:195], v147 offset:56320
	global_load_lds_dwordx4 v134, s[56:57]
	s_mov_b32 m0, s31
	s_nop 0
	global_load_lds_dwordx4 v130, s[56:57]
	s_barrier
	s_waitcnt lgkmcnt(0)
	s_waitcnt lgkmcnt(0)
	v_mfma_f32_16x16x32_bf16 v[60:63], v[148:151], v[164:167], v[60:63]
	v_mfma_f32_16x16x32_bf16 v[56:59], v[156:159], v[164:167], v[56:59]
	v_mfma_f32_16x16x32_bf16 v[52:55], v[148:151], v[172:175], v[52:55]
	v_mfma_f32_16x16x32_bf16 v[48:51], v[156:159], v[172:175], v[48:51]
	v_mfma_f32_16x16x32_bf16 v[36:39], v[148:151], v[180:183], v[36:39]
	v_mfma_f32_16x16x32_bf16 v[32:35], v[156:159], v[180:183], v[32:35]
	v_mfma_f32_16x16x32_bf16 v[20:23], v[148:151], v[188:191], v[20:23]
	v_mfma_f32_16x16x32_bf16 v[16:19], v[156:159], v[188:191], v[16:19]
	v_mfma_f32_16x16x32_bf16 v[60:63], v[152:155], v[168:171], v[60:63]
	v_mfma_f32_16x16x32_bf16 v[56:59], v[160:163], v[168:171], v[56:59]
	v_mfma_f32_16x16x32_bf16 v[52:55], v[152:155], v[176:179], v[52:55]
	v_mfma_f32_16x16x32_bf16 v[48:51], v[160:163], v[176:179], v[48:51]
	v_mfma_f32_16x16x32_bf16 v[36:39], v[152:155], v[184:187], v[36:39]
	v_mfma_f32_16x16x32_bf16 v[32:35], v[160:163], v[184:187], v[32:35]
	v_mfma_f32_16x16x32_bf16 v[20:23], v[152:155], v[192:195], v[20:23]
	v_mfma_f32_16x16x32_bf16 v[16:19], v[160:163], v[192:195], v[16:19]
	s_barrier
	s_add_u32 s54, s76, s54
	s_addc_u32 s55, s77, s55
	s_mov_b32 m0, s33
	s_nop 0
	global_load_lds_dwordx4 v132, s[54:55]
	s_mov_b32 m0, s53
	s_nop 0
	global_load_lds_dwordx4 v128, s[54:55]
	s_waitcnt vmcnt(6)
	s_barrier
	v_mfma_f32_16x16x32_bf16 v[44:47], v[196:199], v[164:167], v[44:47]
	v_mfma_f32_16x16x32_bf16 v[40:43], v[204:207], v[164:167], v[40:43]
	v_mfma_f32_16x16x32_bf16 v[28:31], v[196:199], v[172:175], v[28:31]
	v_mfma_f32_16x16x32_bf16 v[24:27], v[204:207], v[172:175], v[24:27]
	v_mfma_f32_16x16x32_bf16 v[12:15], v[196:199], v[180:183], v[12:15]
	v_mfma_f32_16x16x32_bf16 v[8:11], v[204:207], v[180:183], v[8:11]
	v_mfma_f32_16x16x32_bf16 v[4:7], v[196:199], v[188:191], v[4:7]
	v_mfma_f32_16x16x32_bf16 v[0:3], v[204:207], v[188:191], v[0:3]
	v_mfma_f32_16x16x32_bf16 v[44:47], v[200:203], v[168:171], v[44:47]
	v_mfma_f32_16x16x32_bf16 v[40:43], v[208:211], v[168:171], v[40:43]
	v_mfma_f32_16x16x32_bf16 v[28:31], v[200:203], v[176:179], v[28:31]
	v_mfma_f32_16x16x32_bf16 v[24:27], v[208:211], v[176:179], v[24:27]
	v_mfma_f32_16x16x32_bf16 v[12:15], v[200:203], v[184:187], v[12:15]
	v_mfma_f32_16x16x32_bf16 v[8:11], v[208:211], v[184:187], v[8:11]
	v_mfma_f32_16x16x32_bf16 v[4:7], v[200:203], v[192:195], v[4:7]
	v_mfma_f32_16x16x32_bf16 v[0:3], v[208:211], v[192:195], v[0:3]
	v_lshl_add_u64 v[140:141], v[140:141], 0, s[4:5]
	v_lshl_add_u64 v[142:143], v[142:143], 0, s[4:5]
	s_cmp_ge_u32 s11, s75
	s_mov_b32 s2, s11
	s_barrier
	s_cbranch_scc0 .LBB0_321
	s_andn2_b64 vcc, exec, s[8:9]
	s_cbranch_vccnz .LBB0_317
	s_bitset1_b32 s10, 7
	s_ashr_i32 s11, s10, 31
	s_lshl_b64 s[10:11], s[10:11], 11
	s_add_u32 s10, s16, s10
	s_addc_u32 s11, s17, s11
	v_lshl_add_u64 v[192:193], s[10:11], 0, v[134:135]
	s_mov_b32 m0, s62
	v_lshl_add_u64 v[192:193], v[192:193], 0, s[6:7]
	ds_read_b128 v[140:143], v146
	ds_read_b128 v[148:151], v146 offset:1024
	ds_read_b128 v[152:155], v146 offset:2048
	ds_read_b128 v[156:159], v146 offset:3072
	ds_read_b128 v[160:163], v147
	ds_read_b128 v[164:167], v147 offset:1024
	ds_read_b128 v[168:171], v147 offset:2048
	ds_read_b128 v[172:175], v147 offset:3072
	ds_read_b128 v[176:179], v147 offset:4096
	ds_read_b128 v[180:183], v147 offset:5120
	ds_read_b128 v[184:187], v147 offset:6144
	ds_read_b128 v[188:191], v147 offset:7168
	global_load_lds_dwordx4 v[192:193], off
	v_lshl_add_u64 v[192:193], s[10:11], 0, v[130:131]
	v_lshl_add_u64 v[192:193], v[192:193], 0, s[6:7]
	s_mov_b32 m0, s63
	s_nop 0
	global_load_lds_dwordx4 v[192:193], off
	s_barrier
	s_waitcnt lgkmcnt(0)
	s_waitcnt lgkmcnt(0)
	v_mfma_f32_16x16x32_bf16 v[124:127], v[140:143], v[160:163], v[124:127]
	v_mfma_f32_16x16x32_bf16 v[120:123], v[152:155], v[160:163], v[120:123]
	v_mfma_f32_16x16x32_bf16 v[116:119], v[140:143], v[168:171], v[116:119]
	v_mfma_f32_16x16x32_bf16 v[112:115], v[152:155], v[168:171], v[112:115]
	v_mfma_f32_16x16x32_bf16 v[100:103], v[140:143], v[176:179], v[100:103]
	v_mfma_f32_16x16x32_bf16 v[96:99], v[152:155], v[176:179], v[96:99]
	v_mfma_f32_16x16x32_bf16 v[84:87], v[140:143], v[184:187], v[84:87]
	v_mfma_f32_16x16x32_bf16 v[80:83], v[152:155], v[184:187], v[80:83]
	v_mfma_f32_16x16x32_bf16 v[124:127], v[148:151], v[164:167], v[124:127]
	v_mfma_f32_16x16x32_bf16 v[120:123], v[156:159], v[164:167], v[120:123]
	v_mfma_f32_16x16x32_bf16 v[116:119], v[148:151], v[172:175], v[116:119]
	v_mfma_f32_16x16x32_bf16 v[112:115], v[156:159], v[172:175], v[112:115]
	v_mfma_f32_16x16x32_bf16 v[100:103], v[148:151], v[180:183], v[100:103]
	v_mfma_f32_16x16x32_bf16 v[96:99], v[156:159], v[180:183], v[96:99]
	v_mfma_f32_16x16x32_bf16 v[84:87], v[148:151], v[188:191], v[84:87]
	v_mfma_f32_16x16x32_bf16 v[80:83], v[156:159], v[188:191], v[80:83]
	s_barrier
	ds_read_b128 v[192:195], v146 offset:16384
	ds_read_b128 v[196:199], v146 offset:17408
	ds_read_b128 v[200:203], v146 offset:18432
	ds_read_b128 v[204:207], v146 offset:19456
	s_barrier
	s_waitcnt lgkmcnt(0)
	s_waitcnt lgkmcnt(0)
	v_mfma_f32_16x16x32_bf16 v[108:111], v[192:195], v[160:163], v[108:111]
	v_mfma_f32_16x16x32_bf16 v[104:107], v[200:203], v[160:163], v[104:107]
	v_mfma_f32_16x16x32_bf16 v[92:95], v[192:195], v[168:171], v[92:95]
	v_mfma_f32_16x16x32_bf16 v[88:91], v[200:203], v[168:171], v[88:91]
	v_mfma_f32_16x16x32_bf16 v[76:79], v[192:195], v[176:179], v[76:79]
	v_mfma_f32_16x16x32_bf16 v[72:75], v[200:203], v[176:179], v[72:75]
	v_mfma_f32_16x16x32_bf16 v[68:71], v[192:195], v[184:187], v[68:71]
	v_mfma_f32_16x16x32_bf16 v[64:67], v[200:203], v[184:187], v[64:67]
	v_mfma_f32_16x16x32_bf16 v[108:111], v[196:199], v[164:167], v[108:111]
	v_mfma_f32_16x16x32_bf16 v[104:107], v[204:207], v[164:167], v[104:107]
	v_mfma_f32_16x16x32_bf16 v[92:95], v[196:199], v[172:175], v[92:95]
	v_mfma_f32_16x16x32_bf16 v[88:91], v[204:207], v[172:175], v[88:91]
	v_mfma_f32_16x16x32_bf16 v[76:79], v[196:199], v[180:183], v[76:79]
	v_mfma_f32_16x16x32_bf16 v[72:75], v[204:207], v[180:183], v[72:75]
	v_mfma_f32_16x16x32_bf16 v[68:71], v[196:199], v[188:191], v[68:71]
	v_mfma_f32_16x16x32_bf16 v[64:67], v[204:207], v[188:191], v[64:67]
	s_barrier
	ds_read_b128 v[160:163], v147 offset:16384
	ds_read_b128 v[164:167], v147 offset:17408
	ds_read_b128 v[168:171], v147 offset:18432
	ds_read_b128 v[172:175], v147 offset:19456
	ds_read_b128 v[176:179], v147 offset:20480
	ds_read_b128 v[180:183], v147 offset:21504
	ds_read_b128 v[184:187], v147 offset:22528
	ds_read_b128 v[188:191], v147 offset:23552
	s_waitcnt vmcnt(4)
	s_barrier
	s_waitcnt lgkmcnt(0)
	s_waitcnt lgkmcnt(0)
	v_mfma_f32_16x16x32_bf16 v[60:63], v[140:143], v[160:163], v[60:63]
	v_mfma_f32_16x16x32_bf16 v[56:59], v[152:155], v[160:163], v[56:59]
	v_mfma_f32_16x16x32_bf16 v[52:55], v[140:143], v[168:171], v[52:55]
	v_mfma_f32_16x16x32_bf16 v[48:51], v[152:155], v[168:171], v[48:51]
	v_mfma_f32_16x16x32_bf16 v[36:39], v[140:143], v[176:179], v[36:39]
	v_mfma_f32_16x16x32_bf16 v[32:35], v[152:155], v[176:179], v[32:35]
	v_mfma_f32_16x16x32_bf16 v[20:23], v[140:143], v[184:187], v[20:23]
	v_mfma_f32_16x16x32_bf16 v[16:19], v[152:155], v[184:187], v[16:19]
	v_mfma_f32_16x16x32_bf16 v[60:63], v[148:151], v[164:167], v[60:63]
	v_mfma_f32_16x16x32_bf16 v[56:59], v[156:159], v[164:167], v[56:59]
	v_mfma_f32_16x16x32_bf16 v[52:55], v[148:151], v[172:175], v[52:55]
	v_mfma_f32_16x16x32_bf16 v[48:51], v[156:159], v[172:175], v[48:51]
	v_mfma_f32_16x16x32_bf16 v[36:39], v[148:151], v[180:183], v[36:39]
	v_mfma_f32_16x16x32_bf16 v[32:35], v[156:159], v[180:183], v[32:35]
	v_mfma_f32_16x16x32_bf16 v[20:23], v[148:151], v[188:191], v[20:23]
	v_mfma_f32_16x16x32_bf16 v[16:19], v[156:159], v[188:191], v[16:19]
	v_mfma_f32_16x16x32_bf16 v[44:47], v[192:195], v[160:163], v[44:47]
	v_mfma_f32_16x16x32_bf16 v[40:43], v[200:203], v[160:163], v[40:43]
	v_mfma_f32_16x16x32_bf16 v[28:31], v[192:195], v[168:171], v[28:31]
	v_mfma_f32_16x16x32_bf16 v[24:27], v[200:203], v[168:171], v[24:27]
	v_mfma_f32_16x16x32_bf16 v[12:15], v[192:195], v[176:179], v[12:15]
	v_mfma_f32_16x16x32_bf16 v[8:11], v[200:203], v[176:179], v[8:11]
	v_mfma_f32_16x16x32_bf16 v[4:7], v[192:195], v[184:187], v[4:7]
	v_mfma_f32_16x16x32_bf16 v[0:3], v[200:203], v[184:187], v[0:3]
	v_mfma_f32_16x16x32_bf16 v[44:47], v[196:199], v[164:167], v[44:47]
	v_mfma_f32_16x16x32_bf16 v[40:43], v[204:207], v[164:167], v[40:43]
	v_mfma_f32_16x16x32_bf16 v[28:31], v[196:199], v[172:175], v[28:31]
	v_mfma_f32_16x16x32_bf16 v[24:27], v[204:207], v[172:175], v[24:27]
	v_mfma_f32_16x16x32_bf16 v[12:15], v[196:199], v[180:183], v[12:15]
	v_mfma_f32_16x16x32_bf16 v[8:11], v[204:207], v[180:183], v[8:11]
	v_mfma_f32_16x16x32_bf16 v[4:7], v[196:199], v[188:191], v[4:7]
	v_mfma_f32_16x16x32_bf16 v[0:3], v[204:207], v[188:191], v[0:3]
	s_barrier
	ds_read_b128 v[140:143], v146 offset:32768
	ds_read_b128 v[148:151], v146 offset:33792
	ds_read_b128 v[152:155], v146 offset:34816
	ds_read_b128 v[156:159], v146 offset:35840
	ds_read_b128 v[160:163], v147 offset:32768
	ds_read_b128 v[164:167], v147 offset:33792
	ds_read_b128 v[168:171], v147 offset:34816
	ds_read_b128 v[172:175], v147 offset:35840
	ds_read_b128 v[176:179], v147 offset:36864
	ds_read_b128 v[180:183], v147 offset:37888
	ds_read_b128 v[184:187], v147 offset:38912
	ds_read_b128 v[188:191], v147 offset:39936
	s_waitcnt vmcnt(2)
	s_barrier
	s_waitcnt lgkmcnt(0)
	s_waitcnt lgkmcnt(0)
	v_mfma_f32_16x16x32_bf16 v[124:127], v[140:143], v[160:163], v[124:127]
	v_mfma_f32_16x16x32_bf16 v[120:123], v[152:155], v[160:163], v[120:123]
	v_mfma_f32_16x16x32_bf16 v[116:119], v[140:143], v[168:171], v[116:119]
	v_mfma_f32_16x16x32_bf16 v[112:115], v[152:155], v[168:171], v[112:115]
	v_mfma_f32_16x16x32_bf16 v[100:103], v[140:143], v[176:179], v[100:103]
	v_mfma_f32_16x16x32_bf16 v[96:99], v[152:155], v[176:179], v[96:99]
	v_mfma_f32_16x16x32_bf16 v[84:87], v[140:143], v[184:187], v[84:87]
	v_mfma_f32_16x16x32_bf16 v[80:83], v[152:155], v[184:187], v[80:83]
	v_mfma_f32_16x16x32_bf16 v[124:127], v[148:151], v[164:167], v[124:127]
	v_mfma_f32_16x16x32_bf16 v[120:123], v[156:159], v[164:167], v[120:123]
	v_mfma_f32_16x16x32_bf16 v[116:119], v[148:151], v[172:175], v[116:119]
	v_mfma_f32_16x16x32_bf16 v[112:115], v[156:159], v[172:175], v[112:115]
	v_mfma_f32_16x16x32_bf16 v[100:103], v[148:151], v[180:183], v[100:103]
	v_mfma_f32_16x16x32_bf16 v[96:99], v[156:159], v[180:183], v[96:99]
	v_mfma_f32_16x16x32_bf16 v[84:87], v[148:151], v[188:191], v[84:87]
	v_mfma_f32_16x16x32_bf16 v[80:83], v[156:159], v[188:191], v[80:83]
	s_barrier
	ds_read_b128 v[192:195], v146 offset:49152
	ds_read_b128 v[196:199], v146 offset:50176
	ds_read_b128 v[200:203], v146 offset:51200
	ds_read_b128 v[204:207], v146 offset:52224
	s_waitcnt vmcnt(0)
	s_barrier
	s_waitcnt lgkmcnt(0)
	s_waitcnt lgkmcnt(0)
	v_mfma_f32_16x16x32_bf16 v[108:111], v[192:195], v[160:163], v[108:111]
	v_mfma_f32_16x16x32_bf16 v[104:107], v[200:203], v[160:163], v[104:107]
	v_mfma_f32_16x16x32_bf16 v[92:95], v[192:195], v[168:171], v[92:95]
	v_mfma_f32_16x16x32_bf16 v[88:91], v[200:203], v[168:171], v[88:91]
	v_mfma_f32_16x16x32_bf16 v[76:79], v[192:195], v[176:179], v[76:79]
	v_mfma_f32_16x16x32_bf16 v[72:75], v[200:203], v[176:179], v[72:75]
	v_mfma_f32_16x16x32_bf16 v[68:71], v[192:195], v[184:187], v[68:71]
	v_mfma_f32_16x16x32_bf16 v[64:67], v[200:203], v[184:187], v[64:67]
	v_mfma_f32_16x16x32_bf16 v[108:111], v[196:199], v[164:167], v[108:111]
	v_mfma_f32_16x16x32_bf16 v[104:107], v[204:207], v[164:167], v[104:107]
	v_mfma_f32_16x16x32_bf16 v[92:95], v[196:199], v[172:175], v[92:95]
	v_mfma_f32_16x16x32_bf16 v[88:91], v[204:207], v[172:175], v[88:91]
	v_mfma_f32_16x16x32_bf16 v[76:79], v[196:199], v[180:183], v[76:79]
	v_mfma_f32_16x16x32_bf16 v[72:75], v[204:207], v[180:183], v[72:75]
	v_mfma_f32_16x16x32_bf16 v[68:71], v[196:199], v[188:191], v[68:71]
	v_mfma_f32_16x16x32_bf16 v[64:67], v[204:207], v[188:191], v[64:67]
	s_barrier
	ds_read_b128 v[160:163], v147 offset:49152
	ds_read_b128 v[164:167], v147 offset:50176
	ds_read_b128 v[168:171], v147 offset:51200
	ds_read_b128 v[172:175], v147 offset:52224
	ds_read_b128 v[176:179], v147 offset:53248
	ds_read_b128 v[180:183], v147 offset:54272
	ds_read_b128 v[184:187], v147 offset:55296
	ds_read_b128 v[188:191], v147 offset:56320
	s_barrier
	s_waitcnt lgkmcnt(0)
	s_waitcnt lgkmcnt(0)
	v_mfma_f32_16x16x32_bf16 v[60:63], v[140:143], v[160:163], v[60:63]
	v_mfma_f32_16x16x32_bf16 v[56:59], v[152:155], v[160:163], v[56:59]
	v_mfma_f32_16x16x32_bf16 v[52:55], v[140:143], v[168:171], v[52:55]
	v_mfma_f32_16x16x32_bf16 v[48:51], v[152:155], v[168:171], v[48:51]
	v_mfma_f32_16x16x32_bf16 v[36:39], v[140:143], v[176:179], v[36:39]
	v_mfma_f32_16x16x32_bf16 v[32:35], v[152:155], v[176:179], v[32:35]
	v_mfma_f32_16x16x32_bf16 v[20:23], v[140:143], v[184:187], v[20:23]
	v_mfma_f32_16x16x32_bf16 v[16:19], v[152:155], v[184:187], v[16:19]
	v_mfma_f32_16x16x32_bf16 v[60:63], v[148:151], v[164:167], v[60:63]
	v_mfma_f32_16x16x32_bf16 v[56:59], v[156:159], v[164:167], v[56:59]
	v_mfma_f32_16x16x32_bf16 v[52:55], v[148:151], v[172:175], v[52:55]
	v_mfma_f32_16x16x32_bf16 v[48:51], v[156:159], v[172:175], v[48:51]
	v_mfma_f32_16x16x32_bf16 v[36:39], v[148:151], v[180:183], v[36:39]
	v_mfma_f32_16x16x32_bf16 v[32:35], v[156:159], v[180:183], v[32:35]
	v_mfma_f32_16x16x32_bf16 v[20:23], v[148:151], v[188:191], v[20:23]
	v_mfma_f32_16x16x32_bf16 v[16:19], v[156:159], v[188:191], v[16:19]
	v_mfma_f32_16x16x32_bf16 v[44:47], v[192:195], v[160:163], v[44:47]
	v_mfma_f32_16x16x32_bf16 v[40:43], v[200:203], v[160:163], v[40:43]
	v_mfma_f32_16x16x32_bf16 v[28:31], v[192:195], v[168:171], v[28:31]
	v_mfma_f32_16x16x32_bf16 v[24:27], v[200:203], v[168:171], v[24:27]
	v_mfma_f32_16x16x32_bf16 v[12:15], v[192:195], v[176:179], v[12:15]
	v_mfma_f32_16x16x32_bf16 v[8:11], v[200:203], v[176:179], v[8:11]
	v_mfma_f32_16x16x32_bf16 v[4:7], v[192:195], v[184:187], v[4:7]
	v_mfma_f32_16x16x32_bf16 v[0:3], v[200:203], v[184:187], v[0:3]
	v_mfma_f32_16x16x32_bf16 v[44:47], v[196:199], v[164:167], v[44:47]
	v_mfma_f32_16x16x32_bf16 v[40:43], v[204:207], v[164:167], v[40:43]
	v_mfma_f32_16x16x32_bf16 v[28:31], v[196:199], v[172:175], v[28:31]
	v_mfma_f32_16x16x32_bf16 v[24:27], v[204:207], v[172:175], v[24:27]
	v_mfma_f32_16x16x32_bf16 v[12:15], v[196:199], v[180:183], v[12:15]
	v_mfma_f32_16x16x32_bf16 v[8:11], v[204:207], v[180:183], v[8:11]
	v_mfma_f32_16x16x32_bf16 v[4:7], v[196:199], v[188:191], v[4:7]
	v_mfma_f32_16x16x32_bf16 v[0:3], v[204:207], v[188:191], v[0:3]
	s_barrier
	s_branch .LBB0_317

.LBB0_367:
	ds_read_b128 v[148:151], v146
	ds_read_b128 v[152:155], v146 offset:1024
	ds_read_b128 v[156:159], v146 offset:2048
	ds_read_b128 v[160:163], v146 offset:3072
	s_add_i32 s11, s2, 2
	s_cmp_gt_u32 s2, 13
	s_cselect_b32 s54, s64, s36
	s_cselect_b32 s38, s63, s10
	s_mov_b32 m0, s58
	ds_read_b128 v[164:167], v147
	ds_read_b128 v[168:171], v147 offset:1024
	ds_read_b128 v[172:175], v147 offset:2048
	ds_read_b128 v[176:179], v147 offset:3072
	ds_read_b128 v[180:183], v147 offset:4096
	ds_read_b128 v[184:187], v147 offset:5120
	ds_read_b128 v[188:191], v147 offset:6144
	ds_read_b128 v[192:195], v147 offset:7168
	global_load_lds_dwordx4 v[140:141], off
	s_mov_b32 m0, s59
	s_nop 0
	global_load_lds_dwordx4 v[142:143], off
	s_waitcnt lgkmcnt(8)
	s_barrier
	s_waitcnt lgkmcnt(0)
	s_waitcnt lgkmcnt(0)
	v_mfma_f32_16x16x32_bf16 v[124:127], v[148:151], v[164:167], v[124:127]
	v_mfma_f32_16x16x32_bf16 v[120:123], v[156:159], v[164:167], v[120:123]
	v_mfma_f32_16x16x32_bf16 v[108:111], v[148:151], v[172:175], v[108:111]
	v_mfma_f32_16x16x32_bf16 v[104:107], v[156:159], v[172:175], v[104:107]
	v_mfma_f32_16x16x32_bf16 v[92:95], v[148:151], v[180:183], v[92:95]
	v_mfma_f32_16x16x32_bf16 v[88:91], v[156:159], v[180:183], v[88:91]
	v_mfma_f32_16x16x32_bf16 v[76:79], v[148:151], v[188:191], v[76:79]
	v_mfma_f32_16x16x32_bf16 v[72:75], v[156:159], v[188:191], v[72:75]
	v_mfma_f32_16x16x32_bf16 v[124:127], v[152:155], v[168:171], v[124:127]
	v_mfma_f32_16x16x32_bf16 v[120:123], v[160:163], v[168:171], v[120:123]
	v_mfma_f32_16x16x32_bf16 v[108:111], v[152:155], v[176:179], v[108:111]
	v_mfma_f32_16x16x32_bf16 v[104:107], v[160:163], v[176:179], v[104:107]
	v_mfma_f32_16x16x32_bf16 v[92:95], v[152:155], v[184:187], v[92:95]
	v_mfma_f32_16x16x32_bf16 v[88:91], v[160:163], v[184:187], v[88:91]
	v_mfma_f32_16x16x32_bf16 v[76:79], v[152:155], v[192:195], v[76:79]
	v_mfma_f32_16x16x32_bf16 v[72:75], v[160:163], v[192:195], v[72:75]
	s_barrier
	s_cselect_b32 s2, 0, s11
	s_ashr_i32 s55, s54, 31
	s_lshl_b64 s[52:53], s[54:55], 11
	s_add_u32 s74, s18, s52
	s_addc_u32 s75, s19, s53
	s_lshl_b64 s[52:53], s[2:3], 7
	s_add_u32 s72, s74, s52
	s_addc_u32 s73, s75, s53
	s_mov_b32 m0, s21
	ds_read_b128 v[196:199], v146 offset:16384
	ds_read_b128 v[200:203], v146 offset:17408
	ds_read_b128 v[204:207], v146 offset:18432
	ds_read_b128 v[208:211], v146 offset:19456
	global_load_lds_dwordx4 v132, s[72:73]
	s_mov_b32 m0, s22
	s_nop 0
	global_load_lds_dwordx4 v128, s[72:73]
	s_barrier
	s_waitcnt lgkmcnt(0)
	s_waitcnt lgkmcnt(0)
	v_mfma_f32_16x16x32_bf16 v[116:119], v[196:199], v[164:167], v[116:119]
	v_mfma_f32_16x16x32_bf16 v[112:115], v[204:207], v[164:167], v[112:115]
	v_mfma_f32_16x16x32_bf16 v[100:103], v[196:199], v[172:175], v[100:103]
	v_mfma_f32_16x16x32_bf16 v[96:99], v[204:207], v[172:175], v[96:99]
	v_mfma_f32_16x16x32_bf16 v[84:87], v[196:199], v[180:183], v[84:87]
	v_mfma_f32_16x16x32_bf16 v[80:83], v[204:207], v[180:183], v[80:83]
	v_mfma_f32_16x16x32_bf16 v[68:71], v[196:199], v[188:191], v[68:71]
	v_mfma_f32_16x16x32_bf16 v[64:67], v[204:207], v[188:191], v[64:67]
	v_mfma_f32_16x16x32_bf16 v[116:119], v[200:203], v[168:171], v[116:119]
	v_mfma_f32_16x16x32_bf16 v[112:115], v[208:211], v[168:171], v[112:115]
	v_mfma_f32_16x16x32_bf16 v[100:103], v[200:203], v[176:179], v[100:103]
	v_mfma_f32_16x16x32_bf16 v[96:99], v[208:211], v[176:179], v[96:99]
	v_mfma_f32_16x16x32_bf16 v[84:87], v[200:203], v[184:187], v[84:87]
	v_mfma_f32_16x16x32_bf16 v[80:83], v[208:211], v[184:187], v[80:83]
	v_mfma_f32_16x16x32_bf16 v[68:71], v[200:203], v[192:195], v[68:71]
	v_mfma_f32_16x16x32_bf16 v[64:67], v[208:211], v[192:195], v[64:67]
	s_ashr_i32 s39, s38, 31
	s_lshl_b64 s[72:73], s[38:39], 11
	s_add_u32 s76, s16, s72
	s_addc_u32 s77, s17, s73
	s_add_u32 s72, s76, s52
	s_addc_u32 s73, s77, s53
	s_mov_b32 m0, s20
	s_barrier
	ds_read_b128 v[164:167], v147 offset:16384
	ds_read_b128 v[168:171], v147 offset:17408
	ds_read_b128 v[172:175], v147 offset:18432
	ds_read_b128 v[176:179], v147 offset:19456
	ds_read_b128 v[180:183], v147 offset:20480
	ds_read_b128 v[184:187], v147 offset:21504
	ds_read_b128 v[188:191], v147 offset:22528
	ds_read_b128 v[192:195], v147 offset:23552
	global_load_lds_dwordx4 v134, s[72:73]
	s_mov_b32 m0, s23
	s_nop 0
	global_load_lds_dwordx4 v130, s[72:73]
	s_barrier
	s_waitcnt lgkmcnt(0)
	s_waitcnt lgkmcnt(0)
	v_mfma_f32_16x16x32_bf16 v[60:63], v[148:151], v[164:167], v[60:63]
	v_mfma_f32_16x16x32_bf16 v[56:59], v[156:159], v[164:167], v[56:59]
	v_mfma_f32_16x16x32_bf16 v[44:47], v[148:151], v[172:175], v[44:47]
	v_mfma_f32_16x16x32_bf16 v[40:43], v[156:159], v[172:175], v[40:43]
	v_mfma_f32_16x16x32_bf16 v[28:31], v[148:151], v[180:183], v[28:31]
	v_mfma_f32_16x16x32_bf16 v[24:27], v[156:159], v[180:183], v[24:27]
	v_mfma_f32_16x16x32_bf16 v[12:15], v[148:151], v[188:191], v[12:15]
	v_mfma_f32_16x16x32_bf16 v[8:11], v[156:159], v[188:191], v[8:11]
	v_mfma_f32_16x16x32_bf16 v[60:63], v[152:155], v[168:171], v[60:63]
	v_mfma_f32_16x16x32_bf16 v[56:59], v[160:163], v[168:171], v[56:59]
	v_mfma_f32_16x16x32_bf16 v[44:47], v[152:155], v[176:179], v[44:47]
	v_mfma_f32_16x16x32_bf16 v[40:43], v[160:163], v[176:179], v[40:43]
	v_mfma_f32_16x16x32_bf16 v[28:31], v[152:155], v[184:187], v[28:31]
	v_mfma_f32_16x16x32_bf16 v[24:27], v[160:163], v[184:187], v[24:27]
	v_mfma_f32_16x16x32_bf16 v[12:15], v[152:155], v[192:195], v[12:15]
	v_mfma_f32_16x16x32_bf16 v[8:11], v[160:163], v[192:195], v[8:11]
	s_barrier
	s_bitset1_b32 s54, 7
	s_ashr_i32 s55, s54, 31
	s_lshl_b64 s[54:55], s[54:55], 11
	s_add_u32 s72, s18, s54
	s_addc_u32 s73, s19, s55
	s_add_u32 s54, s72, s52
	s_addc_u32 s55, s73, s53
	s_mov_b32 m0, s24
	s_nop 0
	global_load_lds_dwordx4 v132, s[54:55]
	s_mov_b32 m0, s25
	s_nop 0
	global_load_lds_dwordx4 v128, s[54:55]
	s_waitcnt vmcnt(6)
	s_barrier
	v_mfma_f32_16x16x32_bf16 v[52:55], v[196:199], v[164:167], v[52:55]
	v_mfma_f32_16x16x32_bf16 v[48:51], v[204:207], v[164:167], v[48:51]
	v_mfma_f32_16x16x32_bf16 v[36:39], v[196:199], v[172:175], v[36:39]
	v_mfma_f32_16x16x32_bf16 v[32:35], v[204:207], v[172:175], v[32:35]
	v_mfma_f32_16x16x32_bf16 v[20:23], v[196:199], v[180:183], v[20:23]
	v_mfma_f32_16x16x32_bf16 v[16:19], v[204:207], v[180:183], v[16:19]
	v_mfma_f32_16x16x32_bf16 v[4:7], v[196:199], v[188:191], v[4:7]
	v_mfma_f32_16x16x32_bf16 v[0:3], v[204:207], v[188:191], v[0:3]
	v_mfma_f32_16x16x32_bf16 v[52:55], v[200:203], v[168:171], v[52:55]
	v_mfma_f32_16x16x32_bf16 v[48:51], v[208:211], v[168:171], v[48:51]
	v_mfma_f32_16x16x32_bf16 v[36:39], v[200:203], v[176:179], v[36:39]
	v_mfma_f32_16x16x32_bf16 v[32:35], v[208:211], v[176:179], v[32:35]
	v_mfma_f32_16x16x32_bf16 v[20:23], v[200:203], v[184:187], v[20:23]
	v_mfma_f32_16x16x32_bf16 v[16:19], v[208:211], v[184:187], v[16:19]
	v_mfma_f32_16x16x32_bf16 v[4:7], v[200:203], v[192:195], v[4:7]
	v_mfma_f32_16x16x32_bf16 v[0:3], v[208:211], v[192:195], v[0:3]
	s_barrier
	ds_read_b128 v[148:151], v146 offset:32768
	ds_read_b128 v[152:155], v146 offset:33792
	ds_read_b128 v[156:159], v146 offset:34816
	ds_read_b128 v[160:163], v146 offset:35840
	s_bitset1_b32 s38, 7
	s_ashr_i32 s39, s38, 31
	s_lshl_b64 s[38:39], s[38:39], 11
	s_add_u32 s38, s16, s38
	s_addc_u32 s39, s17, s39
	s_add_u32 s38, s38, s52
	s_addc_u32 s39, s39, s53
	s_mov_b32 m0, s26
	ds_read_b128 v[164:167], v147 offset:32768
	ds_read_b128 v[168:171], v147 offset:33792
	ds_read_b128 v[172:175], v147 offset:34816
	ds_read_b128 v[176:179], v147 offset:35840
	ds_read_b128 v[180:183], v147 offset:36864
	ds_read_b128 v[184:187], v147 offset:37888
	ds_read_b128 v[188:191], v147 offset:38912
	ds_read_b128 v[192:195], v147 offset:39936
	global_load_lds_dwordx4 v134, s[38:39]
	s_mov_b32 m0, s27
	s_nop 0
	global_load_lds_dwordx4 v130, s[38:39]
	s_waitcnt lgkmcnt(8)
	s_barrier
	s_waitcnt lgkmcnt(0)
	s_waitcnt lgkmcnt(0)
	v_mfma_f32_16x16x32_bf16 v[124:127], v[148:151], v[164:167], v[124:127]
	v_mfma_f32_16x16x32_bf16 v[120:123], v[156:159], v[164:167], v[120:123]
	v_mfma_f32_16x16x32_bf16 v[108:111], v[148:151], v[172:175], v[108:111]
	v_mfma_f32_16x16x32_bf16 v[104:107], v[156:159], v[172:175], v[104:107]
	v_mfma_f32_16x16x32_bf16 v[92:95], v[148:151], v[180:183], v[92:95]
	v_mfma_f32_16x16x32_bf16 v[88:91], v[156:159], v[180:183], v[88:91]
	v_mfma_f32_16x16x32_bf16 v[76:79], v[148:151], v[188:191], v[76:79]
	v_mfma_f32_16x16x32_bf16 v[72:75], v[156:159], v[188:191], v[72:75]
	v_mfma_f32_16x16x32_bf16 v[124:127], v[152:155], v[168:171], v[124:127]
	v_mfma_f32_16x16x32_bf16 v[120:123], v[160:163], v[168:171], v[120:123]
	v_mfma_f32_16x16x32_bf16 v[108:111], v[152:155], v[176:179], v[108:111]
	v_mfma_f32_16x16x32_bf16 v[104:107], v[160:163], v[176:179], v[104:107]
	v_mfma_f32_16x16x32_bf16 v[92:95], v[152:155], v[184:187], v[92:95]
	v_mfma_f32_16x16x32_bf16 v[88:91], v[160:163], v[184:187], v[88:91]
	v_mfma_f32_16x16x32_bf16 v[76:79], v[152:155], v[192:195], v[76:79]
	v_mfma_f32_16x16x32_bf16 v[72:75], v[160:163], v[192:195], v[72:75]
	s_barrier
	s_or_b32 s2, s2, 1
	s_lshl_b64 s[38:39], s[2:3], 7
	s_add_u32 s52, s74, s38
	s_addc_u32 s53, s75, s39
	s_mov_b32 m0, s28
	ds_read_b128 v[196:199], v146 offset:49152
	ds_read_b128 v[200:203], v146 offset:50176
	ds_read_b128 v[204:207], v146 offset:51200
	ds_read_b128 v[208:211], v146 offset:52224
	global_load_lds_dwordx4 v132, s[52:53]
	s_mov_b32 m0, s29
	s_nop 0
	global_load_lds_dwordx4 v128, s[52:53]
	s_barrier
	s_waitcnt lgkmcnt(0)
	s_waitcnt lgkmcnt(0)
	v_mfma_f32_16x16x32_bf16 v[116:119], v[196:199], v[164:167], v[116:119]
	v_mfma_f32_16x16x32_bf16 v[112:115], v[204:207], v[164:167], v[112:115]
	v_mfma_f32_16x16x32_bf16 v[100:103], v[196:199], v[172:175], v[100:103]
	v_mfma_f32_16x16x32_bf16 v[96:99], v[204:207], v[172:175], v[96:99]
	v_mfma_f32_16x16x32_bf16 v[84:87], v[196:199], v[180:183], v[84:87]
	v_mfma_f32_16x16x32_bf16 v[80:83], v[204:207], v[180:183], v[80:83]
	v_mfma_f32_16x16x32_bf16 v[68:71], v[196:199], v[188:191], v[68:71]
	v_mfma_f32_16x16x32_bf16 v[64:67], v[204:207], v[188:191], v[64:67]
	v_mfma_f32_16x16x32_bf16 v[116:119], v[200:203], v[168:171], v[116:119]
	v_mfma_f32_16x16x32_bf16 v[112:115], v[208:211], v[168:171], v[112:115]
	v_mfma_f32_16x16x32_bf16 v[100:103], v[200:203], v[176:179], v[100:103]
	v_mfma_f32_16x16x32_bf16 v[96:99], v[208:211], v[176:179], v[96:99]
	v_mfma_f32_16x16x32_bf16 v[84:87], v[200:203], v[184:187], v[84:87]
	v_mfma_f32_16x16x32_bf16 v[80:83], v[208:211], v[184:187], v[80:83]
	v_mfma_f32_16x16x32_bf16 v[68:71], v[200:203], v[192:195], v[68:71]
	v_mfma_f32_16x16x32_bf16 v[64:67], v[208:211], v[192:195], v[64:67]
	s_add_u32 s52, s76, s38
	s_addc_u32 s53, s77, s39
	s_mov_b32 m0, s30
	s_barrier
	ds_read_b128 v[164:167], v147 offset:49152
	ds_read_b128 v[168:171], v147 offset:50176
	ds_read_b128 v[172:175], v147 offset:51200
	ds_read_b128 v[176:179], v147 offset:52224
	ds_read_b128 v[180:183], v147 offset:53248
	ds_read_b128 v[184:187], v147 offset:54272
	ds_read_b128 v[188:191], v147 offset:55296
	ds_read_b128 v[192:195], v147 offset:56320
	global_load_lds_dwordx4 v134, s[52:53]
	s_mov_b32 m0, s31
	s_nop 0
	global_load_lds_dwordx4 v130, s[52:53]
	s_barrier
	s_waitcnt lgkmcnt(0)
	s_waitcnt lgkmcnt(0)
	v_mfma_f32_16x16x32_bf16 v[60:63], v[148:151], v[164:167], v[60:63]
	v_mfma_f32_16x16x32_bf16 v[56:59], v[156:159], v[164:167], v[56:59]
	v_mfma_f32_16x16x32_bf16 v[44:47], v[148:151], v[172:175], v[44:47]
	v_mfma_f32_16x16x32_bf16 v[40:43], v[156:159], v[172:175], v[40:43]
	v_mfma_f32_16x16x32_bf16 v[28:31], v[148:151], v[180:183], v[28:31]
	v_mfma_f32_16x16x32_bf16 v[24:27], v[156:159], v[180:183], v[24:27]
	v_mfma_f32_16x16x32_bf16 v[12:15], v[148:151], v[188:191], v[12:15]
	v_mfma_f32_16x16x32_bf16 v[8:11], v[156:159], v[188:191], v[8:11]
	v_mfma_f32_16x16x32_bf16 v[60:63], v[152:155], v[168:171], v[60:63]
	v_mfma_f32_16x16x32_bf16 v[56:59], v[160:163], v[168:171], v[56:59]
	v_mfma_f32_16x16x32_bf16 v[44:47], v[152:155], v[176:179], v[44:47]
	v_mfma_f32_16x16x32_bf16 v[40:43], v[160:163], v[176:179], v[40:43]
	v_mfma_f32_16x16x32_bf16 v[28:31], v[152:155], v[184:187], v[28:31]
	v_mfma_f32_16x16x32_bf16 v[24:27], v[160:163], v[184:187], v[24:27]
	v_mfma_f32_16x16x32_bf16 v[12:15], v[152:155], v[192:195], v[12:15]
	v_mfma_f32_16x16x32_bf16 v[8:11], v[160:163], v[192:195], v[8:11]
	s_barrier
	s_add_u32 s38, s72, s38
	s_addc_u32 s39, s73, s39
	s_mov_b32 m0, s33
	s_nop 0
	global_load_lds_dwordx4 v132, s[38:39]
	s_mov_b32 m0, s37
	s_nop 0
	global_load_lds_dwordx4 v128, s[38:39]
	s_waitcnt vmcnt(6)
	s_barrier
	v_mfma_f32_16x16x32_bf16 v[52:55], v[196:199], v[164:167], v[52:55]
	v_mfma_f32_16x16x32_bf16 v[48:51], v[204:207], v[164:167], v[48:51]
	v_mfma_f32_16x16x32_bf16 v[36:39], v[196:199], v[172:175], v[36:39]
	v_mfma_f32_16x16x32_bf16 v[32:35], v[204:207], v[172:175], v[32:35]
	v_mfma_f32_16x16x32_bf16 v[20:23], v[196:199], v[180:183], v[20:23]
	v_mfma_f32_16x16x32_bf16 v[16:19], v[204:207], v[180:183], v[16:19]
	v_mfma_f32_16x16x32_bf16 v[4:7], v[196:199], v[188:191], v[4:7]
	v_mfma_f32_16x16x32_bf16 v[0:3], v[204:207], v[188:191], v[0:3]
	v_mfma_f32_16x16x32_bf16 v[52:55], v[200:203], v[168:171], v[52:55]
	v_mfma_f32_16x16x32_bf16 v[48:51], v[208:211], v[168:171], v[48:51]
	v_mfma_f32_16x16x32_bf16 v[36:39], v[200:203], v[176:179], v[36:39]
	v_mfma_f32_16x16x32_bf16 v[32:35], v[208:211], v[176:179], v[32:35]
	v_mfma_f32_16x16x32_bf16 v[20:23], v[200:203], v[184:187], v[20:23]
	v_mfma_f32_16x16x32_bf16 v[16:19], v[208:211], v[184:187], v[16:19]
	v_mfma_f32_16x16x32_bf16 v[4:7], v[200:203], v[192:195], v[4:7]
	v_mfma_f32_16x16x32_bf16 v[0:3], v[208:211], v[192:195], v[0:3]
	v_lshl_add_u64 v[140:141], v[140:141], 0, s[4:5]
	v_lshl_add_u64 v[142:143], v[142:143], 0, s[4:5]
	s_cmp_ge_u32 s11, s67
	s_mov_b32 s2, s11
	s_barrier
	s_cbranch_scc0 .LBB0_367
	s_andn2_b64 vcc, exec, s[8:9]
	s_cbranch_vccnz .LBB0_363
	s_bitset1_b32 s10, 7
	s_ashr_i32 s11, s10, 31
	s_lshl_b64 s[10:11], s[10:11], 11
	s_add_u32 s10, s16, s10
	s_addc_u32 s11, s17, s11
	v_lshl_add_u64 v[192:193], s[10:11], 0, v[134:135]
	s_mov_b32 m0, s58
	v_lshl_add_u64 v[192:193], v[192:193], 0, s[6:7]
	ds_read_b128 v[140:143], v146
	ds_read_b128 v[148:151], v146 offset:1024
	ds_read_b128 v[152:155], v146 offset:2048
	ds_read_b128 v[156:159], v146 offset:3072
	ds_read_b128 v[160:163], v147
	ds_read_b128 v[164:167], v147 offset:1024
	ds_read_b128 v[168:171], v147 offset:2048
	ds_read_b128 v[172:175], v147 offset:3072
	ds_read_b128 v[176:179], v147 offset:4096
	ds_read_b128 v[180:183], v147 offset:5120
	ds_read_b128 v[184:187], v147 offset:6144
	ds_read_b128 v[188:191], v147 offset:7168
	global_load_lds_dwordx4 v[192:193], off
	v_lshl_add_u64 v[192:193], s[10:11], 0, v[130:131]
	v_lshl_add_u64 v[192:193], v[192:193], 0, s[6:7]
	s_mov_b32 m0, s59
	s_nop 0
	global_load_lds_dwordx4 v[192:193], off
	s_barrier
	s_waitcnt lgkmcnt(0)
	s_waitcnt lgkmcnt(0)
	v_mfma_f32_16x16x32_bf16 v[124:127], v[140:143], v[160:163], v[124:127]
	v_mfma_f32_16x16x32_bf16 v[120:123], v[152:155], v[160:163], v[120:123]
	v_mfma_f32_16x16x32_bf16 v[108:111], v[140:143], v[168:171], v[108:111]
	v_mfma_f32_16x16x32_bf16 v[104:107], v[152:155], v[168:171], v[104:107]
	v_mfma_f32_16x16x32_bf16 v[92:95], v[140:143], v[176:179], v[92:95]
	v_mfma_f32_16x16x32_bf16 v[88:91], v[152:155], v[176:179], v[88:91]
	v_mfma_f32_16x16x32_bf16 v[76:79], v[140:143], v[184:187], v[76:79]
	v_mfma_f32_16x16x32_bf16 v[72:75], v[152:155], v[184:187], v[72:75]
	v_mfma_f32_16x16x32_bf16 v[124:127], v[148:151], v[164:167], v[124:127]
	v_mfma_f32_16x16x32_bf16 v[120:123], v[156:159], v[164:167], v[120:123]
	v_mfma_f32_16x16x32_bf16 v[108:111], v[148:151], v[172:175], v[108:111]
	v_mfma_f32_16x16x32_bf16 v[104:107], v[156:159], v[172:175], v[104:107]
	v_mfma_f32_16x16x32_bf16 v[92:95], v[148:151], v[180:183], v[92:95]
	v_mfma_f32_16x16x32_bf16 v[88:91], v[156:159], v[180:183], v[88:91]
	v_mfma_f32_16x16x32_bf16 v[76:79], v[148:151], v[188:191], v[76:79]
	v_mfma_f32_16x16x32_bf16 v[72:75], v[156:159], v[188:191], v[72:75]
	s_barrier
	ds_read_b128 v[192:195], v146 offset:16384
	ds_read_b128 v[196:199], v146 offset:17408
	ds_read_b128 v[200:203], v146 offset:18432
	ds_read_b128 v[204:207], v146 offset:19456
	s_barrier
	s_waitcnt lgkmcnt(0)
	s_waitcnt lgkmcnt(0)
	v_mfma_f32_16x16x32_bf16 v[116:119], v[192:195], v[160:163], v[116:119]
	v_mfma_f32_16x16x32_bf16 v[112:115], v[200:203], v[160:163], v[112:115]
	v_mfma_f32_16x16x32_bf16 v[100:103], v[192:195], v[168:171], v[100:103]
	v_mfma_f32_16x16x32_bf16 v[96:99], v[200:203], v[168:171], v[96:99]
	v_mfma_f32_16x16x32_bf16 v[84:87], v[192:195], v[176:179], v[84:87]
	v_mfma_f32_16x16x32_bf16 v[80:83], v[200:203], v[176:179], v[80:83]
	v_mfma_f32_16x16x32_bf16 v[68:71], v[192:195], v[184:187], v[68:71]
	v_mfma_f32_16x16x32_bf16 v[64:67], v[200:203], v[184:187], v[64:67]
	v_mfma_f32_16x16x32_bf16 v[116:119], v[196:199], v[164:167], v[116:119]
	v_mfma_f32_16x16x32_bf16 v[112:115], v[204:207], v[164:167], v[112:115]
	v_mfma_f32_16x16x32_bf16 v[100:103], v[196:199], v[172:175], v[100:103]
	v_mfma_f32_16x16x32_bf16 v[96:99], v[204:207], v[172:175], v[96:99]
	v_mfma_f32_16x16x32_bf16 v[84:87], v[196:199], v[180:183], v[84:87]
	v_mfma_f32_16x16x32_bf16 v[80:83], v[204:207], v[180:183], v[80:83]
	v_mfma_f32_16x16x32_bf16 v[68:71], v[196:199], v[188:191], v[68:71]
	v_mfma_f32_16x16x32_bf16 v[64:67], v[204:207], v[188:191], v[64:67]
	s_barrier
	ds_read_b128 v[160:163], v147 offset:16384
	ds_read_b128 v[164:167], v147 offset:17408
	ds_read_b128 v[168:171], v147 offset:18432
	ds_read_b128 v[172:175], v147 offset:19456
	ds_read_b128 v[176:179], v147 offset:20480
	ds_read_b128 v[180:183], v147 offset:21504
	ds_read_b128 v[184:187], v147 offset:22528
	ds_read_b128 v[188:191], v147 offset:23552
	s_waitcnt vmcnt(4)
	s_barrier
	s_waitcnt lgkmcnt(0)
	s_waitcnt lgkmcnt(0)
	v_mfma_f32_16x16x32_bf16 v[60:63], v[140:143], v[160:163], v[60:63]
	v_mfma_f32_16x16x32_bf16 v[56:59], v[152:155], v[160:163], v[56:59]
	v_mfma_f32_16x16x32_bf16 v[44:47], v[140:143], v[168:171], v[44:47]
	v_mfma_f32_16x16x32_bf16 v[40:43], v[152:155], v[168:171], v[40:43]
	v_mfma_f32_16x16x32_bf16 v[28:31], v[140:143], v[176:179], v[28:31]
	v_mfma_f32_16x16x32_bf16 v[24:27], v[152:155], v[176:179], v[24:27]
	v_mfma_f32_16x16x32_bf16 v[12:15], v[140:143], v[184:187], v[12:15]
	v_mfma_f32_16x16x32_bf16 v[8:11], v[152:155], v[184:187], v[8:11]
	v_mfma_f32_16x16x32_bf16 v[60:63], v[148:151], v[164:167], v[60:63]
	v_mfma_f32_16x16x32_bf16 v[56:59], v[156:159], v[164:167], v[56:59]
	v_mfma_f32_16x16x32_bf16 v[44:47], v[148:151], v[172:175], v[44:47]
	v_mfma_f32_16x16x32_bf16 v[40:43], v[156:159], v[172:175], v[40:43]
	v_mfma_f32_16x16x32_bf16 v[28:31], v[148:151], v[180:183], v[28:31]
	v_mfma_f32_16x16x32_bf16 v[24:27], v[156:159], v[180:183], v[24:27]
	v_mfma_f32_16x16x32_bf16 v[12:15], v[148:151], v[188:191], v[12:15]
	v_mfma_f32_16x16x32_bf16 v[8:11], v[156:159], v[188:191], v[8:11]
	v_mfma_f32_16x16x32_bf16 v[52:55], v[192:195], v[160:163], v[52:55]
	v_mfma_f32_16x16x32_bf16 v[48:51], v[200:203], v[160:163], v[48:51]
	v_mfma_f32_16x16x32_bf16 v[36:39], v[192:195], v[168:171], v[36:39]
	v_mfma_f32_16x16x32_bf16 v[32:35], v[200:203], v[168:171], v[32:35]
	v_mfma_f32_16x16x32_bf16 v[20:23], v[192:195], v[176:179], v[20:23]
	v_mfma_f32_16x16x32_bf16 v[16:19], v[200:203], v[176:179], v[16:19]
	v_mfma_f32_16x16x32_bf16 v[4:7], v[192:195], v[184:187], v[4:7]
	v_mfma_f32_16x16x32_bf16 v[0:3], v[200:203], v[184:187], v[0:3]
	v_mfma_f32_16x16x32_bf16 v[52:55], v[196:199], v[164:167], v[52:55]
	v_mfma_f32_16x16x32_bf16 v[48:51], v[204:207], v[164:167], v[48:51]
	v_mfma_f32_16x16x32_bf16 v[36:39], v[196:199], v[172:175], v[36:39]
	v_mfma_f32_16x16x32_bf16 v[32:35], v[204:207], v[172:175], v[32:35]
	v_mfma_f32_16x16x32_bf16 v[20:23], v[196:199], v[180:183], v[20:23]
	v_mfma_f32_16x16x32_bf16 v[16:19], v[204:207], v[180:183], v[16:19]
	v_mfma_f32_16x16x32_bf16 v[4:7], v[196:199], v[188:191], v[4:7]
	v_mfma_f32_16x16x32_bf16 v[0:3], v[204:207], v[188:191], v[0:3]
	s_barrier
	ds_read_b128 v[140:143], v146 offset:32768
	ds_read_b128 v[148:151], v146 offset:33792
	ds_read_b128 v[152:155], v146 offset:34816
	ds_read_b128 v[156:159], v146 offset:35840
	ds_read_b128 v[160:163], v147 offset:32768
	ds_read_b128 v[164:167], v147 offset:33792
	ds_read_b128 v[168:171], v147 offset:34816
	ds_read_b128 v[172:175], v147 offset:35840
	ds_read_b128 v[176:179], v147 offset:36864
	ds_read_b128 v[180:183], v147 offset:37888
	ds_read_b128 v[184:187], v147 offset:38912
	ds_read_b128 v[188:191], v147 offset:39936
	s_waitcnt vmcnt(2)
	s_barrier
	s_waitcnt lgkmcnt(0)
	s_waitcnt lgkmcnt(0)
	v_mfma_f32_16x16x32_bf16 v[124:127], v[140:143], v[160:163], v[124:127]
	v_mfma_f32_16x16x32_bf16 v[120:123], v[152:155], v[160:163], v[120:123]
	v_mfma_f32_16x16x32_bf16 v[108:111], v[140:143], v[168:171], v[108:111]
	v_mfma_f32_16x16x32_bf16 v[104:107], v[152:155], v[168:171], v[104:107]
	v_mfma_f32_16x16x32_bf16 v[92:95], v[140:143], v[176:179], v[92:95]
	v_mfma_f32_16x16x32_bf16 v[88:91], v[152:155], v[176:179], v[88:91]
	v_mfma_f32_16x16x32_bf16 v[76:79], v[140:143], v[184:187], v[76:79]
	v_mfma_f32_16x16x32_bf16 v[72:75], v[152:155], v[184:187], v[72:75]
	v_mfma_f32_16x16x32_bf16 v[124:127], v[148:151], v[164:167], v[124:127]
	v_mfma_f32_16x16x32_bf16 v[120:123], v[156:159], v[164:167], v[120:123]
	v_mfma_f32_16x16x32_bf16 v[108:111], v[148:151], v[172:175], v[108:111]
	v_mfma_f32_16x16x32_bf16 v[104:107], v[156:159], v[172:175], v[104:107]
	v_mfma_f32_16x16x32_bf16 v[92:95], v[148:151], v[180:183], v[92:95]
	v_mfma_f32_16x16x32_bf16 v[88:91], v[156:159], v[180:183], v[88:91]
	v_mfma_f32_16x16x32_bf16 v[76:79], v[148:151], v[188:191], v[76:79]
	v_mfma_f32_16x16x32_bf16 v[72:75], v[156:159], v[188:191], v[72:75]
	s_barrier
	ds_read_b128 v[192:195], v146 offset:49152
	ds_read_b128 v[196:199], v146 offset:50176
	ds_read_b128 v[200:203], v146 offset:51200
	ds_read_b128 v[204:207], v146 offset:52224
	s_waitcnt vmcnt(0)
	s_barrier
	s_waitcnt lgkmcnt(0)
	s_waitcnt lgkmcnt(0)
	v_mfma_f32_16x16x32_bf16 v[116:119], v[192:195], v[160:163], v[116:119]
	v_mfma_f32_16x16x32_bf16 v[112:115], v[200:203], v[160:163], v[112:115]
	v_mfma_f32_16x16x32_bf16 v[100:103], v[192:195], v[168:171], v[100:103]
	v_mfma_f32_16x16x32_bf16 v[96:99], v[200:203], v[168:171], v[96:99]
	v_mfma_f32_16x16x32_bf16 v[84:87], v[192:195], v[176:179], v[84:87]
	v_mfma_f32_16x16x32_bf16 v[80:83], v[200:203], v[176:179], v[80:83]
	v_mfma_f32_16x16x32_bf16 v[68:71], v[192:195], v[184:187], v[68:71]
	v_mfma_f32_16x16x32_bf16 v[64:67], v[200:203], v[184:187], v[64:67]
	v_mfma_f32_16x16x32_bf16 v[116:119], v[196:199], v[164:167], v[116:119]
	v_mfma_f32_16x16x32_bf16 v[112:115], v[204:207], v[164:167], v[112:115]
	v_mfma_f32_16x16x32_bf16 v[100:103], v[196:199], v[172:175], v[100:103]
	v_mfma_f32_16x16x32_bf16 v[96:99], v[204:207], v[172:175], v[96:99]
	v_mfma_f32_16x16x32_bf16 v[84:87], v[196:199], v[180:183], v[84:87]
	v_mfma_f32_16x16x32_bf16 v[80:83], v[204:207], v[180:183], v[80:83]
	v_mfma_f32_16x16x32_bf16 v[68:71], v[196:199], v[188:191], v[68:71]
	v_mfma_f32_16x16x32_bf16 v[64:67], v[204:207], v[188:191], v[64:67]
	s_barrier
	ds_read_b128 v[160:163], v147 offset:49152
	ds_read_b128 v[164:167], v147 offset:50176
	ds_read_b128 v[168:171], v147 offset:51200
	ds_read_b128 v[172:175], v147 offset:52224
	ds_read_b128 v[176:179], v147 offset:53248
	ds_read_b128 v[180:183], v147 offset:54272
	ds_read_b128 v[184:187], v147 offset:55296
	ds_read_b128 v[188:191], v147 offset:56320
	s_barrier
	s_waitcnt lgkmcnt(0)
	s_waitcnt lgkmcnt(0)
	v_mfma_f32_16x16x32_bf16 v[60:63], v[140:143], v[160:163], v[60:63]
	v_mfma_f32_16x16x32_bf16 v[56:59], v[152:155], v[160:163], v[56:59]
	v_mfma_f32_16x16x32_bf16 v[44:47], v[140:143], v[168:171], v[44:47]
	v_mfma_f32_16x16x32_bf16 v[40:43], v[152:155], v[168:171], v[40:43]
	v_mfma_f32_16x16x32_bf16 v[28:31], v[140:143], v[176:179], v[28:31]
	v_mfma_f32_16x16x32_bf16 v[24:27], v[152:155], v[176:179], v[24:27]
	v_mfma_f32_16x16x32_bf16 v[12:15], v[140:143], v[184:187], v[12:15]
	v_mfma_f32_16x16x32_bf16 v[8:11], v[152:155], v[184:187], v[8:11]
	v_mfma_f32_16x16x32_bf16 v[60:63], v[148:151], v[164:167], v[60:63]
	v_mfma_f32_16x16x32_bf16 v[56:59], v[156:159], v[164:167], v[56:59]
	v_mfma_f32_16x16x32_bf16 v[44:47], v[148:151], v[172:175], v[44:47]
	v_mfma_f32_16x16x32_bf16 v[40:43], v[156:159], v[172:175], v[40:43]
	v_mfma_f32_16x16x32_bf16 v[28:31], v[148:151], v[180:183], v[28:31]
	v_mfma_f32_16x16x32_bf16 v[24:27], v[156:159], v[180:183], v[24:27]
	v_mfma_f32_16x16x32_bf16 v[12:15], v[148:151], v[188:191], v[12:15]
	v_mfma_f32_16x16x32_bf16 v[8:11], v[156:159], v[188:191], v[8:11]
	v_mfma_f32_16x16x32_bf16 v[52:55], v[192:195], v[160:163], v[52:55]
	v_mfma_f32_16x16x32_bf16 v[48:51], v[200:203], v[160:163], v[48:51]
	v_mfma_f32_16x16x32_bf16 v[36:39], v[192:195], v[168:171], v[36:39]
	v_mfma_f32_16x16x32_bf16 v[32:35], v[200:203], v[168:171], v[32:35]
	v_mfma_f32_16x16x32_bf16 v[20:23], v[192:195], v[176:179], v[20:23]
	v_mfma_f32_16x16x32_bf16 v[16:19], v[200:203], v[176:179], v[16:19]
	v_mfma_f32_16x16x32_bf16 v[4:7], v[192:195], v[184:187], v[4:7]
	v_mfma_f32_16x16x32_bf16 v[0:3], v[200:203], v[184:187], v[0:3]
	v_mfma_f32_16x16x32_bf16 v[52:55], v[196:199], v[164:167], v[52:55]
	v_mfma_f32_16x16x32_bf16 v[48:51], v[204:207], v[164:167], v[48:51]
	v_mfma_f32_16x16x32_bf16 v[36:39], v[196:199], v[172:175], v[36:39]
	v_mfma_f32_16x16x32_bf16 v[32:35], v[204:207], v[172:175], v[32:35]
	v_mfma_f32_16x16x32_bf16 v[20:23], v[196:199], v[180:183], v[20:23]
	v_mfma_f32_16x16x32_bf16 v[16:19], v[204:207], v[180:183], v[16:19]
	v_mfma_f32_16x16x32_bf16 v[4:7], v[196:199], v[188:191], v[4:7]
	v_mfma_f32_16x16x32_bf16 v[0:3], v[204:207], v[188:191], v[0:3]
	s_barrier
	s_branch .LBB0_363

.LBB0_392:
	ds_read_b128 v[148:151], v146
	ds_read_b128 v[152:155], v146 offset:1024
	ds_read_b128 v[156:159], v146 offset:2048
	ds_read_b128 v[160:163], v146 offset:3072
	s_add_i32 s9, s2, 2
	s_cmp_gt_u32 s2, 61
	s_cselect_b32 s52, s64, s10
	s_cselect_b32 s36, s63, s8
	s_mov_b32 m0, s56
	ds_read_b128 v[164:167], v147
	ds_read_b128 v[168:171], v147 offset:1024
	ds_read_b128 v[172:175], v147 offset:2048
	ds_read_b128 v[176:179], v147 offset:3072
	ds_read_b128 v[180:183], v147 offset:4096
	ds_read_b128 v[184:187], v147 offset:5120
	ds_read_b128 v[188:191], v147 offset:6144
	ds_read_b128 v[192:195], v147 offset:7168
	global_load_lds_dwordx4 v[140:141], off
	s_mov_b32 m0, s57
	s_nop 0
	global_load_lds_dwordx4 v[142:143], off
	s_waitcnt lgkmcnt(8)
	s_barrier
	s_waitcnt lgkmcnt(0)
	s_waitcnt lgkmcnt(0)
	v_mfma_f32_16x16x32_bf16 v[124:127], v[148:151], v[164:167], v[124:127]
	v_mfma_f32_16x16x32_bf16 v[120:123], v[156:159], v[164:167], v[120:123]
	v_mfma_f32_16x16x32_bf16 v[116:119], v[148:151], v[172:175], v[116:119]
	v_mfma_f32_16x16x32_bf16 v[112:115], v[156:159], v[172:175], v[112:115]
	v_mfma_f32_16x16x32_bf16 v[100:103], v[148:151], v[180:183], v[100:103]
	v_mfma_f32_16x16x32_bf16 v[96:99], v[156:159], v[180:183], v[96:99]
	v_mfma_f32_16x16x32_bf16 v[84:87], v[148:151], v[188:191], v[84:87]
	v_mfma_f32_16x16x32_bf16 v[80:83], v[156:159], v[188:191], v[80:83]
	v_mfma_f32_16x16x32_bf16 v[124:127], v[152:155], v[168:171], v[124:127]
	v_mfma_f32_16x16x32_bf16 v[120:123], v[160:163], v[168:171], v[120:123]
	v_mfma_f32_16x16x32_bf16 v[116:119], v[152:155], v[176:179], v[116:119]
	v_mfma_f32_16x16x32_bf16 v[112:115], v[160:163], v[176:179], v[112:115]
	v_mfma_f32_16x16x32_bf16 v[100:103], v[152:155], v[184:187], v[100:103]
	v_mfma_f32_16x16x32_bf16 v[96:99], v[160:163], v[184:187], v[96:99]
	v_mfma_f32_16x16x32_bf16 v[84:87], v[152:155], v[192:195], v[84:87]
	v_mfma_f32_16x16x32_bf16 v[80:83], v[160:163], v[192:195], v[80:83]
	s_barrier
	s_cselect_b32 s2, 0, s9
	s_ashr_i32 s53, s52, 31
	s_lshl_b64 s[38:39], s[52:53], 13
	s_add_u32 s72, s18, s38
	s_addc_u32 s73, s19, s39
	s_lshl_b64 s[38:39], s[2:3], 7
	s_add_u32 s66, s72, s38
	s_addc_u32 s67, s73, s39
	s_mov_b32 m0, s11
	ds_read_b128 v[196:199], v146 offset:16384
	ds_read_b128 v[200:203], v146 offset:17408
	ds_read_b128 v[204:207], v146 offset:18432
	ds_read_b128 v[208:211], v146 offset:19456
	global_load_lds_dwordx4 v132, s[66:67]
	s_mov_b32 m0, s21
	s_nop 0
	global_load_lds_dwordx4 v128, s[66:67]
	s_barrier
	s_waitcnt lgkmcnt(0)
	s_waitcnt lgkmcnt(0)
	v_mfma_f32_16x16x32_bf16 v[108:111], v[196:199], v[164:167], v[108:111]
	v_mfma_f32_16x16x32_bf16 v[104:107], v[204:207], v[164:167], v[104:107]
	v_mfma_f32_16x16x32_bf16 v[92:95], v[196:199], v[172:175], v[92:95]
	v_mfma_f32_16x16x32_bf16 v[88:91], v[204:207], v[172:175], v[88:91]
	v_mfma_f32_16x16x32_bf16 v[76:79], v[196:199], v[180:183], v[76:79]
	v_mfma_f32_16x16x32_bf16 v[72:75], v[204:207], v[180:183], v[72:75]
	v_mfma_f32_16x16x32_bf16 v[68:71], v[196:199], v[188:191], v[68:71]
	v_mfma_f32_16x16x32_bf16 v[64:67], v[204:207], v[188:191], v[64:67]
	v_mfma_f32_16x16x32_bf16 v[108:111], v[200:203], v[168:171], v[108:111]
	v_mfma_f32_16x16x32_bf16 v[104:107], v[208:211], v[168:171], v[104:107]
	v_mfma_f32_16x16x32_bf16 v[92:95], v[200:203], v[176:179], v[92:95]
	v_mfma_f32_16x16x32_bf16 v[88:91], v[208:211], v[176:179], v[88:91]
	v_mfma_f32_16x16x32_bf16 v[76:79], v[200:203], v[184:187], v[76:79]
	v_mfma_f32_16x16x32_bf16 v[72:75], v[208:211], v[184:187], v[72:75]
	v_mfma_f32_16x16x32_bf16 v[68:71], v[200:203], v[192:195], v[68:71]
	v_mfma_f32_16x16x32_bf16 v[64:67], v[208:211], v[192:195], v[64:67]
	s_ashr_i32 s37, s36, 31
	s_lshl_b64 s[66:67], s[36:37], 13
	s_add_u32 s74, s16, s66
	s_addc_u32 s75, s17, s67
	s_add_u32 s66, s74, s38
	s_addc_u32 s67, s75, s39
	s_mov_b32 m0, s20
	s_barrier
	ds_read_b128 v[164:167], v147 offset:16384
	ds_read_b128 v[168:171], v147 offset:17408
	ds_read_b128 v[172:175], v147 offset:18432
	ds_read_b128 v[176:179], v147 offset:19456
	ds_read_b128 v[180:183], v147 offset:20480
	ds_read_b128 v[184:187], v147 offset:21504
	ds_read_b128 v[188:191], v147 offset:22528
	ds_read_b128 v[192:195], v147 offset:23552
	global_load_lds_dwordx4 v134, s[66:67]
	s_mov_b32 m0, s22
	s_nop 0
	global_load_lds_dwordx4 v130, s[66:67]
	s_barrier
	s_waitcnt lgkmcnt(0)
	s_waitcnt lgkmcnt(0)
	v_mfma_f32_16x16x32_bf16 v[60:63], v[148:151], v[164:167], v[60:63]
	v_mfma_f32_16x16x32_bf16 v[56:59], v[156:159], v[164:167], v[56:59]
	v_mfma_f32_16x16x32_bf16 v[52:55], v[148:151], v[172:175], v[52:55]
	v_mfma_f32_16x16x32_bf16 v[48:51], v[156:159], v[172:175], v[48:51]
	v_mfma_f32_16x16x32_bf16 v[36:39], v[148:151], v[180:183], v[36:39]
	v_mfma_f32_16x16x32_bf16 v[32:35], v[156:159], v[180:183], v[32:35]
	v_mfma_f32_16x16x32_bf16 v[20:23], v[148:151], v[188:191], v[20:23]
	v_mfma_f32_16x16x32_bf16 v[16:19], v[156:159], v[188:191], v[16:19]
	v_mfma_f32_16x16x32_bf16 v[60:63], v[152:155], v[168:171], v[60:63]
	v_mfma_f32_16x16x32_bf16 v[56:59], v[160:163], v[168:171], v[56:59]
	v_mfma_f32_16x16x32_bf16 v[52:55], v[152:155], v[176:179], v[52:55]
	v_mfma_f32_16x16x32_bf16 v[48:51], v[160:163], v[176:179], v[48:51]
	v_mfma_f32_16x16x32_bf16 v[36:39], v[152:155], v[184:187], v[36:39]
	v_mfma_f32_16x16x32_bf16 v[32:35], v[160:163], v[184:187], v[32:35]
	v_mfma_f32_16x16x32_bf16 v[20:23], v[152:155], v[192:195], v[20:23]
	v_mfma_f32_16x16x32_bf16 v[16:19], v[160:163], v[192:195], v[16:19]
	s_barrier
	s_bitset1_b32 s52, 7
	s_ashr_i32 s53, s52, 31
	s_lshl_b64 s[52:53], s[52:53], 13
	s_add_u32 s66, s18, s52
	s_addc_u32 s67, s19, s53
	s_add_u32 s52, s66, s38
	s_addc_u32 s53, s67, s39
	s_mov_b32 m0, s23
	s_nop 0
	global_load_lds_dwordx4 v132, s[52:53]
	s_mov_b32 m0, s24
	s_nop 0
	global_load_lds_dwordx4 v128, s[52:53]
	s_waitcnt vmcnt(6)
	s_barrier
	v_mfma_f32_16x16x32_bf16 v[44:47], v[196:199], v[164:167], v[44:47]
	v_mfma_f32_16x16x32_bf16 v[40:43], v[204:207], v[164:167], v[40:43]
	v_mfma_f32_16x16x32_bf16 v[28:31], v[196:199], v[172:175], v[28:31]
	v_mfma_f32_16x16x32_bf16 v[24:27], v[204:207], v[172:175], v[24:27]
	v_mfma_f32_16x16x32_bf16 v[12:15], v[196:199], v[180:183], v[12:15]
	v_mfma_f32_16x16x32_bf16 v[8:11], v[204:207], v[180:183], v[8:11]
	v_mfma_f32_16x16x32_bf16 v[4:7], v[196:199], v[188:191], v[4:7]
	v_mfma_f32_16x16x32_bf16 v[0:3], v[204:207], v[188:191], v[0:3]
	v_mfma_f32_16x16x32_bf16 v[44:47], v[200:203], v[168:171], v[44:47]
	v_mfma_f32_16x16x32_bf16 v[40:43], v[208:211], v[168:171], v[40:43]
	v_mfma_f32_16x16x32_bf16 v[28:31], v[200:203], v[176:179], v[28:31]
	v_mfma_f32_16x16x32_bf16 v[24:27], v[208:211], v[176:179], v[24:27]
	v_mfma_f32_16x16x32_bf16 v[12:15], v[200:203], v[184:187], v[12:15]
	v_mfma_f32_16x16x32_bf16 v[8:11], v[208:211], v[184:187], v[8:11]
	v_mfma_f32_16x16x32_bf16 v[4:7], v[200:203], v[192:195], v[4:7]
	v_mfma_f32_16x16x32_bf16 v[0:3], v[208:211], v[192:195], v[0:3]
	s_barrier
	ds_read_b128 v[148:151], v146 offset:32768
	ds_read_b128 v[152:155], v146 offset:33792
	ds_read_b128 v[156:159], v146 offset:34816
	ds_read_b128 v[160:163], v146 offset:35840
	s_bitset1_b32 s36, 7
	s_ashr_i32 s37, s36, 31
	s_lshl_b64 s[36:37], s[36:37], 13
	s_add_u32 s36, s16, s36
	s_addc_u32 s37, s17, s37
	s_add_u32 s36, s36, s38
	s_addc_u32 s37, s37, s39
	s_mov_b32 m0, s25
	ds_read_b128 v[164:167], v147 offset:32768
	ds_read_b128 v[168:171], v147 offset:33792
	ds_read_b128 v[172:175], v147 offset:34816
	ds_read_b128 v[176:179], v147 offset:35840
	ds_read_b128 v[180:183], v147 offset:36864
	ds_read_b128 v[184:187], v147 offset:37888
	ds_read_b128 v[188:191], v147 offset:38912
	ds_read_b128 v[192:195], v147 offset:39936
	global_load_lds_dwordx4 v134, s[36:37]
	s_mov_b32 m0, s26
	s_nop 0
	global_load_lds_dwordx4 v130, s[36:37]
	s_waitcnt lgkmcnt(8)
	s_barrier
	s_waitcnt lgkmcnt(0)
	s_waitcnt lgkmcnt(0)
	v_mfma_f32_16x16x32_bf16 v[124:127], v[148:151], v[164:167], v[124:127]
	v_mfma_f32_16x16x32_bf16 v[120:123], v[156:159], v[164:167], v[120:123]
	v_mfma_f32_16x16x32_bf16 v[116:119], v[148:151], v[172:175], v[116:119]
	v_mfma_f32_16x16x32_bf16 v[112:115], v[156:159], v[172:175], v[112:115]
	v_mfma_f32_16x16x32_bf16 v[100:103], v[148:151], v[180:183], v[100:103]
	v_mfma_f32_16x16x32_bf16 v[96:99], v[156:159], v[180:183], v[96:99]
	v_mfma_f32_16x16x32_bf16 v[84:87], v[148:151], v[188:191], v[84:87]
	v_mfma_f32_16x16x32_bf16 v[80:83], v[156:159], v[188:191], v[80:83]
	v_mfma_f32_16x16x32_bf16 v[124:127], v[152:155], v[168:171], v[124:127]
	v_mfma_f32_16x16x32_bf16 v[120:123], v[160:163], v[168:171], v[120:123]
	v_mfma_f32_16x16x32_bf16 v[116:119], v[152:155], v[176:179], v[116:119]
	v_mfma_f32_16x16x32_bf16 v[112:115], v[160:163], v[176:179], v[112:115]
	v_mfma_f32_16x16x32_bf16 v[100:103], v[152:155], v[184:187], v[100:103]
	v_mfma_f32_16x16x32_bf16 v[96:99], v[160:163], v[184:187], v[96:99]
	v_mfma_f32_16x16x32_bf16 v[84:87], v[152:155], v[192:195], v[84:87]
	v_mfma_f32_16x16x32_bf16 v[80:83], v[160:163], v[192:195], v[80:83]
	s_barrier
	s_or_b32 s2, s2, 1
	s_lshl_b64 s[36:37], s[2:3], 7
	s_add_u32 s38, s72, s36
	s_addc_u32 s39, s73, s37
	s_mov_b32 m0, s27
	ds_read_b128 v[196:199], v146 offset:49152
	ds_read_b128 v[200:203], v146 offset:50176
	ds_read_b128 v[204:207], v146 offset:51200
	ds_read_b128 v[208:211], v146 offset:52224
	global_load_lds_dwordx4 v132, s[38:39]
	s_mov_b32 m0, s28
	s_nop 0
	global_load_lds_dwordx4 v128, s[38:39]
	s_barrier
	s_waitcnt lgkmcnt(0)
	s_waitcnt lgkmcnt(0)
	v_mfma_f32_16x16x32_bf16 v[108:111], v[196:199], v[164:167], v[108:111]
	v_mfma_f32_16x16x32_bf16 v[104:107], v[204:207], v[164:167], v[104:107]
	v_mfma_f32_16x16x32_bf16 v[92:95], v[196:199], v[172:175], v[92:95]
	v_mfma_f32_16x16x32_bf16 v[88:91], v[204:207], v[172:175], v[88:91]
	v_mfma_f32_16x16x32_bf16 v[76:79], v[196:199], v[180:183], v[76:79]
	v_mfma_f32_16x16x32_bf16 v[72:75], v[204:207], v[180:183], v[72:75]
	v_mfma_f32_16x16x32_bf16 v[68:71], v[196:199], v[188:191], v[68:71]
	v_mfma_f32_16x16x32_bf16 v[64:67], v[204:207], v[188:191], v[64:67]
	v_mfma_f32_16x16x32_bf16 v[108:111], v[200:203], v[168:171], v[108:111]
	v_mfma_f32_16x16x32_bf16 v[104:107], v[208:211], v[168:171], v[104:107]
	v_mfma_f32_16x16x32_bf16 v[92:95], v[200:203], v[176:179], v[92:95]
	v_mfma_f32_16x16x32_bf16 v[88:91], v[208:211], v[176:179], v[88:91]
	v_mfma_f32_16x16x32_bf16 v[76:79], v[200:203], v[184:187], v[76:79]
	v_mfma_f32_16x16x32_bf16 v[72:75], v[208:211], v[184:187], v[72:75]
	v_mfma_f32_16x16x32_bf16 v[68:71], v[200:203], v[192:195], v[68:71]
	v_mfma_f32_16x16x32_bf16 v[64:67], v[208:211], v[192:195], v[64:67]
	s_add_u32 s38, s74, s36
	s_addc_u32 s39, s75, s37
	s_mov_b32 m0, s29
	s_barrier
	ds_read_b128 v[164:167], v147 offset:49152
	ds_read_b128 v[168:171], v147 offset:50176
	ds_read_b128 v[172:175], v147 offset:51200
	ds_read_b128 v[176:179], v147 offset:52224
	ds_read_b128 v[180:183], v147 offset:53248
	ds_read_b128 v[184:187], v147 offset:54272
	ds_read_b128 v[188:191], v147 offset:55296
	ds_read_b128 v[192:195], v147 offset:56320
	global_load_lds_dwordx4 v134, s[38:39]
	s_mov_b32 m0, s30
	s_nop 0
	global_load_lds_dwordx4 v130, s[38:39]
	s_barrier
	s_waitcnt lgkmcnt(0)
	s_waitcnt lgkmcnt(0)
	v_mfma_f32_16x16x32_bf16 v[60:63], v[148:151], v[164:167], v[60:63]
	v_mfma_f32_16x16x32_bf16 v[56:59], v[156:159], v[164:167], v[56:59]
	v_mfma_f32_16x16x32_bf16 v[52:55], v[148:151], v[172:175], v[52:55]
	v_mfma_f32_16x16x32_bf16 v[48:51], v[156:159], v[172:175], v[48:51]
	v_mfma_f32_16x16x32_bf16 v[36:39], v[148:151], v[180:183], v[36:39]
	v_mfma_f32_16x16x32_bf16 v[32:35], v[156:159], v[180:183], v[32:35]
	v_mfma_f32_16x16x32_bf16 v[20:23], v[148:151], v[188:191], v[20:23]
	v_mfma_f32_16x16x32_bf16 v[16:19], v[156:159], v[188:191], v[16:19]
	v_mfma_f32_16x16x32_bf16 v[60:63], v[152:155], v[168:171], v[60:63]
	v_mfma_f32_16x16x32_bf16 v[56:59], v[160:163], v[168:171], v[56:59]
	v_mfma_f32_16x16x32_bf16 v[52:55], v[152:155], v[176:179], v[52:55]
	v_mfma_f32_16x16x32_bf16 v[48:51], v[160:163], v[176:179], v[48:51]
	v_mfma_f32_16x16x32_bf16 v[36:39], v[152:155], v[184:187], v[36:39]
	v_mfma_f32_16x16x32_bf16 v[32:35], v[160:163], v[184:187], v[32:35]
	v_mfma_f32_16x16x32_bf16 v[20:23], v[152:155], v[192:195], v[20:23]
	v_mfma_f32_16x16x32_bf16 v[16:19], v[160:163], v[192:195], v[16:19]
	s_barrier
	s_add_u32 s36, s66, s36
	s_addc_u32 s37, s67, s37
	s_mov_b32 m0, s31
	s_nop 0
	global_load_lds_dwordx4 v132, s[36:37]
	s_mov_b32 m0, s33
	s_nop 0
	global_load_lds_dwordx4 v128, s[36:37]
	s_waitcnt vmcnt(6)
	s_barrier
	v_mfma_f32_16x16x32_bf16 v[44:47], v[196:199], v[164:167], v[44:47]
	v_mfma_f32_16x16x32_bf16 v[40:43], v[204:207], v[164:167], v[40:43]
	v_mfma_f32_16x16x32_bf16 v[28:31], v[196:199], v[172:175], v[28:31]
	v_mfma_f32_16x16x32_bf16 v[24:27], v[204:207], v[172:175], v[24:27]
	v_mfma_f32_16x16x32_bf16 v[12:15], v[196:199], v[180:183], v[12:15]
	v_mfma_f32_16x16x32_bf16 v[8:11], v[204:207], v[180:183], v[8:11]
	v_mfma_f32_16x16x32_bf16 v[4:7], v[196:199], v[188:191], v[4:7]
	v_mfma_f32_16x16x32_bf16 v[0:3], v[204:207], v[188:191], v[0:3]
	v_mfma_f32_16x16x32_bf16 v[44:47], v[200:203], v[168:171], v[44:47]
	v_mfma_f32_16x16x32_bf16 v[40:43], v[208:211], v[168:171], v[40:43]
	v_mfma_f32_16x16x32_bf16 v[28:31], v[200:203], v[176:179], v[28:31]
	v_mfma_f32_16x16x32_bf16 v[24:27], v[208:211], v[176:179], v[24:27]
	v_mfma_f32_16x16x32_bf16 v[12:15], v[200:203], v[184:187], v[12:15]
	v_mfma_f32_16x16x32_bf16 v[8:11], v[208:211], v[184:187], v[8:11]
	v_mfma_f32_16x16x32_bf16 v[4:7], v[200:203], v[192:195], v[4:7]
	v_mfma_f32_16x16x32_bf16 v[0:3], v[208:211], v[192:195], v[0:3]
	v_lshl_add_u64 v[140:141], v[140:141], 0, s[4:5]
	v_lshl_add_u64 v[142:143], v[142:143], 0, s[4:5]
	s_cmp_ge_u32 s9, s65
	s_mov_b32 s2, s9
	s_barrier
	s_cbranch_scc0 .LBB0_392
	s_andn2_b64 vcc, exec, s[6:7]
	s_cbranch_vccnz .LBB0_388
	s_bitset1_b32 s8, 7
	s_ashr_i32 s9, s8, 31
	s_lshl_b64 s[8:9], s[8:9], 13
	s_add_u32 s2, s16, s8
	s_addc_u32 s9, s17, s9
	s_add_u32 s8, s2, 0x1f80
	s_addc_u32 s9, s9, 0
	s_mov_b32 m0, s56
	ds_read_b128 v[140:143], v146
	ds_read_b128 v[148:151], v146 offset:1024
	ds_read_b128 v[152:155], v146 offset:2048
	ds_read_b128 v[156:159], v146 offset:3072
	ds_read_b128 v[160:163], v147
	ds_read_b128 v[164:167], v147 offset:1024
	ds_read_b128 v[168:171], v147 offset:2048
	ds_read_b128 v[172:175], v147 offset:3072
	ds_read_b128 v[176:179], v147 offset:4096
	ds_read_b128 v[180:183], v147 offset:5120
	ds_read_b128 v[184:187], v147 offset:6144
	ds_read_b128 v[188:191], v147 offset:7168
	global_load_lds_dwordx4 v134, s[8:9]
	s_mov_b32 m0, s57
	s_nop 0
	global_load_lds_dwordx4 v130, s[8:9]
	s_barrier
	s_waitcnt lgkmcnt(0)
	s_waitcnt lgkmcnt(0)
	v_mfma_f32_16x16x32_bf16 v[124:127], v[140:143], v[160:163], v[124:127]
	v_mfma_f32_16x16x32_bf16 v[120:123], v[152:155], v[160:163], v[120:123]
	v_mfma_f32_16x16x32_bf16 v[116:119], v[140:143], v[168:171], v[116:119]
	v_mfma_f32_16x16x32_bf16 v[112:115], v[152:155], v[168:171], v[112:115]
	v_mfma_f32_16x16x32_bf16 v[100:103], v[140:143], v[176:179], v[100:103]
	v_mfma_f32_16x16x32_bf16 v[96:99], v[152:155], v[176:179], v[96:99]
	v_mfma_f32_16x16x32_bf16 v[84:87], v[140:143], v[184:187], v[84:87]
	v_mfma_f32_16x16x32_bf16 v[80:83], v[152:155], v[184:187], v[80:83]
	v_mfma_f32_16x16x32_bf16 v[124:127], v[148:151], v[164:167], v[124:127]
	v_mfma_f32_16x16x32_bf16 v[120:123], v[156:159], v[164:167], v[120:123]
	v_mfma_f32_16x16x32_bf16 v[116:119], v[148:151], v[172:175], v[116:119]
	v_mfma_f32_16x16x32_bf16 v[112:115], v[156:159], v[172:175], v[112:115]
	v_mfma_f32_16x16x32_bf16 v[100:103], v[148:151], v[180:183], v[100:103]
	v_mfma_f32_16x16x32_bf16 v[96:99], v[156:159], v[180:183], v[96:99]
	v_mfma_f32_16x16x32_bf16 v[84:87], v[148:151], v[188:191], v[84:87]
	v_mfma_f32_16x16x32_bf16 v[80:83], v[156:159], v[188:191], v[80:83]
	s_barrier
	ds_read_b128 v[192:195], v146 offset:16384
	ds_read_b128 v[196:199], v146 offset:17408
	ds_read_b128 v[200:203], v146 offset:18432
	ds_read_b128 v[204:207], v146 offset:19456
	s_barrier
	s_waitcnt lgkmcnt(0)
	s_waitcnt lgkmcnt(0)
	v_mfma_f32_16x16x32_bf16 v[108:111], v[192:195], v[160:163], v[108:111]
	v_mfma_f32_16x16x32_bf16 v[104:107], v[200:203], v[160:163], v[104:107]
	v_mfma_f32_16x16x32_bf16 v[92:95], v[192:195], v[168:171], v[92:95]
	v_mfma_f32_16x16x32_bf16 v[88:91], v[200:203], v[168:171], v[88:91]
	v_mfma_f32_16x16x32_bf16 v[76:79], v[192:195], v[176:179], v[76:79]
	v_mfma_f32_16x16x32_bf16 v[72:75], v[200:203], v[176:179], v[72:75]
	v_mfma_f32_16x16x32_bf16 v[68:71], v[192:195], v[184:187], v[68:71]
	v_mfma_f32_16x16x32_bf16 v[64:67], v[200:203], v[184:187], v[64:67]
	v_mfma_f32_16x16x32_bf16 v[108:111], v[196:199], v[164:167], v[108:111]
	v_mfma_f32_16x16x32_bf16 v[104:107], v[204:207], v[164:167], v[104:107]
	v_mfma_f32_16x16x32_bf16 v[92:95], v[196:199], v[172:175], v[92:95]
	v_mfma_f32_16x16x32_bf16 v[88:91], v[204:207], v[172:175], v[88:91]
	v_mfma_f32_16x16x32_bf16 v[76:79], v[196:199], v[180:183], v[76:79]
	v_mfma_f32_16x16x32_bf16 v[72:75], v[204:207], v[180:183], v[72:75]
	v_mfma_f32_16x16x32_bf16 v[68:71], v[196:199], v[188:191], v[68:71]
	v_mfma_f32_16x16x32_bf16 v[64:67], v[204:207], v[188:191], v[64:67]
	s_barrier
	ds_read_b128 v[160:163], v147 offset:16384
	ds_read_b128 v[164:167], v147 offset:17408
	ds_read_b128 v[168:171], v147 offset:18432
	ds_read_b128 v[172:175], v147 offset:19456
	ds_read_b128 v[176:179], v147 offset:20480
	ds_read_b128 v[180:183], v147 offset:21504
	ds_read_b128 v[184:187], v147 offset:22528
	ds_read_b128 v[188:191], v147 offset:23552
	s_waitcnt vmcnt(4)
	s_barrier
	s_waitcnt lgkmcnt(0)
	s_waitcnt lgkmcnt(0)
	v_mfma_f32_16x16x32_bf16 v[60:63], v[140:143], v[160:163], v[60:63]
	v_mfma_f32_16x16x32_bf16 v[56:59], v[152:155], v[160:163], v[56:59]
	v_mfma_f32_16x16x32_bf16 v[52:55], v[140:143], v[168:171], v[52:55]
	v_mfma_f32_16x16x32_bf16 v[48:51], v[152:155], v[168:171], v[48:51]
	v_mfma_f32_16x16x32_bf16 v[36:39], v[140:143], v[176:179], v[36:39]
	v_mfma_f32_16x16x32_bf16 v[32:35], v[152:155], v[176:179], v[32:35]
	v_mfma_f32_16x16x32_bf16 v[20:23], v[140:143], v[184:187], v[20:23]
	v_mfma_f32_16x16x32_bf16 v[16:19], v[152:155], v[184:187], v[16:19]
	v_mfma_f32_16x16x32_bf16 v[60:63], v[148:151], v[164:167], v[60:63]
	v_mfma_f32_16x16x32_bf16 v[56:59], v[156:159], v[164:167], v[56:59]
	v_mfma_f32_16x16x32_bf16 v[52:55], v[148:151], v[172:175], v[52:55]
	v_mfma_f32_16x16x32_bf16 v[48:51], v[156:159], v[172:175], v[48:51]
	v_mfma_f32_16x16x32_bf16 v[36:39], v[148:151], v[180:183], v[36:39]
	v_mfma_f32_16x16x32_bf16 v[32:35], v[156:159], v[180:183], v[32:35]
	v_mfma_f32_16x16x32_bf16 v[20:23], v[148:151], v[188:191], v[20:23]
	v_mfma_f32_16x16x32_bf16 v[16:19], v[156:159], v[188:191], v[16:19]
	v_mfma_f32_16x16x32_bf16 v[44:47], v[192:195], v[160:163], v[44:47]
	v_mfma_f32_16x16x32_bf16 v[40:43], v[200:203], v[160:163], v[40:43]
	v_mfma_f32_16x16x32_bf16 v[28:31], v[192:195], v[168:171], v[28:31]
	v_mfma_f32_16x16x32_bf16 v[24:27], v[200:203], v[168:171], v[24:27]
	v_mfma_f32_16x16x32_bf16 v[12:15], v[192:195], v[176:179], v[12:15]
	v_mfma_f32_16x16x32_bf16 v[8:11], v[200:203], v[176:179], v[8:11]
	v_mfma_f32_16x16x32_bf16 v[4:7], v[192:195], v[184:187], v[4:7]
	v_mfma_f32_16x16x32_bf16 v[0:3], v[200:203], v[184:187], v[0:3]
	v_mfma_f32_16x16x32_bf16 v[44:47], v[196:199], v[164:167], v[44:47]
	v_mfma_f32_16x16x32_bf16 v[40:43], v[204:207], v[164:167], v[40:43]
	v_mfma_f32_16x16x32_bf16 v[28:31], v[196:199], v[172:175], v[28:31]
	v_mfma_f32_16x16x32_bf16 v[24:27], v[204:207], v[172:175], v[24:27]
	v_mfma_f32_16x16x32_bf16 v[12:15], v[196:199], v[180:183], v[12:15]
	v_mfma_f32_16x16x32_bf16 v[8:11], v[204:207], v[180:183], v[8:11]
	v_mfma_f32_16x16x32_bf16 v[4:7], v[196:199], v[188:191], v[4:7]
	v_mfma_f32_16x16x32_bf16 v[0:3], v[204:207], v[188:191], v[0:3]
	s_barrier
	ds_read_b128 v[140:143], v146 offset:32768
	ds_read_b128 v[148:151], v146 offset:33792
	ds_read_b128 v[152:155], v146 offset:34816
	ds_read_b128 v[156:159], v146 offset:35840
	ds_read_b128 v[160:163], v147 offset:32768
	ds_read_b128 v[164:167], v147 offset:33792
	ds_read_b128 v[168:171], v147 offset:34816
	ds_read_b128 v[172:175], v147 offset:35840
	ds_read_b128 v[176:179], v147 offset:36864
	ds_read_b128 v[180:183], v147 offset:37888
	ds_read_b128 v[184:187], v147 offset:38912
	ds_read_b128 v[188:191], v147 offset:39936
	s_waitcnt vmcnt(2)
	s_barrier
	s_waitcnt lgkmcnt(0)
	s_waitcnt lgkmcnt(0)
	v_mfma_f32_16x16x32_bf16 v[124:127], v[140:143], v[160:163], v[124:127]
	v_mfma_f32_16x16x32_bf16 v[120:123], v[152:155], v[160:163], v[120:123]
	v_mfma_f32_16x16x32_bf16 v[116:119], v[140:143], v[168:171], v[116:119]
	v_mfma_f32_16x16x32_bf16 v[112:115], v[152:155], v[168:171], v[112:115]
	v_mfma_f32_16x16x32_bf16 v[100:103], v[140:143], v[176:179], v[100:103]
	v_mfma_f32_16x16x32_bf16 v[96:99], v[152:155], v[176:179], v[96:99]
	v_mfma_f32_16x16x32_bf16 v[84:87], v[140:143], v[184:187], v[84:87]
	v_mfma_f32_16x16x32_bf16 v[80:83], v[152:155], v[184:187], v[80:83]
	v_mfma_f32_16x16x32_bf16 v[124:127], v[148:151], v[164:167], v[124:127]
	v_mfma_f32_16x16x32_bf16 v[120:123], v[156:159], v[164:167], v[120:123]
	v_mfma_f32_16x16x32_bf16 v[116:119], v[148:151], v[172:175], v[116:119]
	v_mfma_f32_16x16x32_bf16 v[112:115], v[156:159], v[172:175], v[112:115]
	v_mfma_f32_16x16x32_bf16 v[100:103], v[148:151], v[180:183], v[100:103]
	v_mfma_f32_16x16x32_bf16 v[96:99], v[156:159], v[180:183], v[96:99]
	v_mfma_f32_16x16x32_bf16 v[84:87], v[148:151], v[188:191], v[84:87]
	v_mfma_f32_16x16x32_bf16 v[80:83], v[156:159], v[188:191], v[80:83]
	s_barrier
	ds_read_b128 v[192:195], v146 offset:49152
	ds_read_b128 v[196:199], v146 offset:50176
	ds_read_b128 v[200:203], v146 offset:51200
	ds_read_b128 v[204:207], v146 offset:52224
	s_waitcnt vmcnt(0)
	s_barrier
	s_waitcnt lgkmcnt(0)
	s_waitcnt lgkmcnt(0)
	v_mfma_f32_16x16x32_bf16 v[108:111], v[192:195], v[160:163], v[108:111]
	v_mfma_f32_16x16x32_bf16 v[104:107], v[200:203], v[160:163], v[104:107]
	v_mfma_f32_16x16x32_bf16 v[92:95], v[192:195], v[168:171], v[92:95]
	v_mfma_f32_16x16x32_bf16 v[88:91], v[200:203], v[168:171], v[88:91]
	v_mfma_f32_16x16x32_bf16 v[76:79], v[192:195], v[176:179], v[76:79]
	v_mfma_f32_16x16x32_bf16 v[72:75], v[200:203], v[176:179], v[72:75]
	v_mfma_f32_16x16x32_bf16 v[68:71], v[192:195], v[184:187], v[68:71]
	v_mfma_f32_16x16x32_bf16 v[64:67], v[200:203], v[184:187], v[64:67]
	v_mfma_f32_16x16x32_bf16 v[108:111], v[196:199], v[164:167], v[108:111]
	v_mfma_f32_16x16x32_bf16 v[104:107], v[204:207], v[164:167], v[104:107]
	v_mfma_f32_16x16x32_bf16 v[92:95], v[196:199], v[172:175], v[92:95]
	v_mfma_f32_16x16x32_bf16 v[88:91], v[204:207], v[172:175], v[88:91]
	v_mfma_f32_16x16x32_bf16 v[76:79], v[196:199], v[180:183], v[76:79]
	v_mfma_f32_16x16x32_bf16 v[72:75], v[204:207], v[180:183], v[72:75]
	v_mfma_f32_16x16x32_bf16 v[68:71], v[196:199], v[188:191], v[68:71]
	v_mfma_f32_16x16x32_bf16 v[64:67], v[204:207], v[188:191], v[64:67]
	s_barrier
	ds_read_b128 v[160:163], v147 offset:49152
	ds_read_b128 v[164:167], v147 offset:50176
	ds_read_b128 v[168:171], v147 offset:51200
	ds_read_b128 v[172:175], v147 offset:52224
	ds_read_b128 v[176:179], v147 offset:53248
	ds_read_b128 v[180:183], v147 offset:54272
	ds_read_b128 v[184:187], v147 offset:55296
	ds_read_b128 v[188:191], v147 offset:56320
	s_barrier
	s_waitcnt lgkmcnt(0)
	s_waitcnt lgkmcnt(0)
	v_mfma_f32_16x16x32_bf16 v[60:63], v[140:143], v[160:163], v[60:63]
	v_mfma_f32_16x16x32_bf16 v[56:59], v[152:155], v[160:163], v[56:59]
	v_mfma_f32_16x16x32_bf16 v[52:55], v[140:143], v[168:171], v[52:55]
	v_mfma_f32_16x16x32_bf16 v[48:51], v[152:155], v[168:171], v[48:51]
	v_mfma_f32_16x16x32_bf16 v[36:39], v[140:143], v[176:179], v[36:39]
	v_mfma_f32_16x16x32_bf16 v[32:35], v[152:155], v[176:179], v[32:35]
	v_mfma_f32_16x16x32_bf16 v[20:23], v[140:143], v[184:187], v[20:23]
	v_mfma_f32_16x16x32_bf16 v[16:19], v[152:155], v[184:187], v[16:19]
	v_mfma_f32_16x16x32_bf16 v[60:63], v[148:151], v[164:167], v[60:63]
	v_mfma_f32_16x16x32_bf16 v[56:59], v[156:159], v[164:167], v[56:59]
	v_mfma_f32_16x16x32_bf16 v[52:55], v[148:151], v[172:175], v[52:55]
	v_mfma_f32_16x16x32_bf16 v[48:51], v[156:159], v[172:175], v[48:51]
	v_mfma_f32_16x16x32_bf16 v[36:39], v[148:151], v[180:183], v[36:39]
	v_mfma_f32_16x16x32_bf16 v[32:35], v[156:159], v[180:183], v[32:35]
	v_mfma_f32_16x16x32_bf16 v[20:23], v[148:151], v[188:191], v[20:23]
	v_mfma_f32_16x16x32_bf16 v[16:19], v[156:159], v[188:191], v[16:19]
	v_mfma_f32_16x16x32_bf16 v[44:47], v[192:195], v[160:163], v[44:47]
	v_mfma_f32_16x16x32_bf16 v[40:43], v[200:203], v[160:163], v[40:43]
	v_mfma_f32_16x16x32_bf16 v[28:31], v[192:195], v[168:171], v[28:31]
	v_mfma_f32_16x16x32_bf16 v[24:27], v[200:203], v[168:171], v[24:27]
	v_mfma_f32_16x16x32_bf16 v[12:15], v[192:195], v[176:179], v[12:15]
	v_mfma_f32_16x16x32_bf16 v[8:11], v[200:203], v[176:179], v[8:11]
	v_mfma_f32_16x16x32_bf16 v[4:7], v[192:195], v[184:187], v[4:7]
	v_mfma_f32_16x16x32_bf16 v[0:3], v[200:203], v[184:187], v[0:3]
	v_mfma_f32_16x16x32_bf16 v[44:47], v[196:199], v[164:167], v[44:47]
	v_mfma_f32_16x16x32_bf16 v[40:43], v[204:207], v[164:167], v[40:43]
	v_mfma_f32_16x16x32_bf16 v[28:31], v[196:199], v[172:175], v[28:31]
	v_mfma_f32_16x16x32_bf16 v[24:27], v[204:207], v[172:175], v[24:27]
	v_mfma_f32_16x16x32_bf16 v[12:15], v[196:199], v[180:183], v[12:15]
	v_mfma_f32_16x16x32_bf16 v[8:11], v[204:207], v[180:183], v[8:11]
	v_mfma_f32_16x16x32_bf16 v[4:7], v[196:199], v[188:191], v[4:7]
	v_mfma_f32_16x16x32_bf16 v[0:3], v[204:207], v[188:191], v[0:3]
	s_barrier
	s_branch .LBB0_388

.LBB0_461:
	ds_read_b128 v[146:149], v152
	ds_read_b128 v[154:157], v152 offset:1024
	ds_read_b128 v[158:161], v152 offset:2048
	ds_read_b128 v[162:165], v152 offset:3072
	s_add_i32 s62, s1, 2
	s_cmp_gt_u32 s1, 13
	s_cselect_b32 s40, s59, s2
	s_cselect_b32 s36, s58, s0
	s_mov_b32 m0, s53
	ds_read_b128 v[166:169], v153
	ds_read_b128 v[170:173], v153 offset:1024
	ds_read_b128 v[174:177], v153 offset:2048
	ds_read_b128 v[178:181], v153 offset:3072
	ds_read_b128 v[182:185], v153 offset:4096
	ds_read_b128 v[186:189], v153 offset:5120
	ds_read_b128 v[190:193], v153 offset:6144
	ds_read_b128 v[194:197], v153 offset:7168
	global_load_lds_dwordx4 v[142:143], off
	s_mov_b32 m0, s54
	s_nop 0
	global_load_lds_dwordx4 v[144:145], off
	s_waitcnt lgkmcnt(8)
	s_barrier
	s_waitcnt lgkmcnt(0)
	s_waitcnt lgkmcnt(0)
	v_mfma_f32_16x16x32_bf16 v[124:127], v[146:149], v[166:169], v[124:127]
	v_mfma_f32_16x16x32_bf16 v[120:123], v[158:161], v[166:169], v[120:123]
	v_mfma_f32_16x16x32_bf16 v[108:111], v[146:149], v[174:177], v[108:111]
	v_mfma_f32_16x16x32_bf16 v[104:107], v[158:161], v[174:177], v[104:107]
	v_mfma_f32_16x16x32_bf16 v[92:95], v[146:149], v[182:185], v[92:95]
	v_mfma_f32_16x16x32_bf16 v[88:91], v[158:161], v[182:185], v[88:91]
	v_mfma_f32_16x16x32_bf16 v[76:79], v[146:149], v[190:193], v[76:79]
	v_mfma_f32_16x16x32_bf16 v[72:75], v[158:161], v[190:193], v[72:75]
	v_mfma_f32_16x16x32_bf16 v[124:127], v[154:157], v[170:173], v[124:127]
	v_mfma_f32_16x16x32_bf16 v[120:123], v[162:165], v[170:173], v[120:123]
	v_mfma_f32_16x16x32_bf16 v[108:111], v[154:157], v[178:181], v[108:111]
	v_mfma_f32_16x16x32_bf16 v[104:107], v[162:165], v[178:181], v[104:107]
	v_mfma_f32_16x16x32_bf16 v[92:95], v[154:157], v[186:189], v[92:95]
	v_mfma_f32_16x16x32_bf16 v[88:91], v[162:165], v[186:189], v[88:91]
	v_mfma_f32_16x16x32_bf16 v[76:79], v[154:157], v[194:197], v[76:79]
	v_mfma_f32_16x16x32_bf16 v[72:75], v[162:165], v[194:197], v[72:75]
	s_barrier
	s_cselect_b32 s8, 0, s62
	s_ashr_i32 s41, s40, 31
	s_lshl_b64 s[38:39], s[40:41], 11
	s_add_u32 s1, s70, s38
	s_addc_u32 s63, s71, s39
	s_lshl_b64 s[38:39], s[8:9], 7
	s_add_u32 s64, s1, s38
	s_addc_u32 s65, s63, s39
	s_mov_b32 m0, s19
	ds_read_b128 v[198:201], v152 offset:16384
	ds_read_b128 v[202:205], v152 offset:17408
	ds_read_b128 v[206:209], v152 offset:18432
	ds_read_b128 v[210:213], v152 offset:19456
	global_load_lds_dwordx4 v132, s[64:65]
	s_mov_b32 m0, s22
	s_nop 0
	global_load_lds_dwordx4 v128, s[64:65]
	s_barrier
	s_waitcnt lgkmcnt(0)
	s_waitcnt lgkmcnt(0)
	v_mfma_f32_16x16x32_bf16 v[116:119], v[198:201], v[166:169], v[116:119]
	v_mfma_f32_16x16x32_bf16 v[112:115], v[206:209], v[166:169], v[112:115]
	v_mfma_f32_16x16x32_bf16 v[100:103], v[198:201], v[174:177], v[100:103]
	v_mfma_f32_16x16x32_bf16 v[96:99], v[206:209], v[174:177], v[96:99]
	v_mfma_f32_16x16x32_bf16 v[84:87], v[198:201], v[182:185], v[84:87]
	v_mfma_f32_16x16x32_bf16 v[80:83], v[206:209], v[182:185], v[80:83]
	v_mfma_f32_16x16x32_bf16 v[68:71], v[198:201], v[190:193], v[68:71]
	v_mfma_f32_16x16x32_bf16 v[64:67], v[206:209], v[190:193], v[64:67]
	v_mfma_f32_16x16x32_bf16 v[116:119], v[202:205], v[170:173], v[116:119]
	v_mfma_f32_16x16x32_bf16 v[112:115], v[210:213], v[170:173], v[112:115]
	v_mfma_f32_16x16x32_bf16 v[100:103], v[202:205], v[178:181], v[100:103]
	v_mfma_f32_16x16x32_bf16 v[96:99], v[210:213], v[178:181], v[96:99]
	v_mfma_f32_16x16x32_bf16 v[84:87], v[202:205], v[186:189], v[84:87]
	v_mfma_f32_16x16x32_bf16 v[80:83], v[210:213], v[186:189], v[80:83]
	v_mfma_f32_16x16x32_bf16 v[68:71], v[202:205], v[194:197], v[68:71]
	v_mfma_f32_16x16x32_bf16 v[64:67], v[210:213], v[194:197], v[64:67]
	s_ashr_i32 s37, s36, 31
	s_lshl_b64 s[64:65], s[36:37], 11
	s_add_u32 s66, s16, s64
	s_addc_u32 s67, s17, s65
	s_add_u32 s64, s66, s38
	s_addc_u32 s65, s67, s39
	s_mov_b32 m0, s18
	s_barrier
	ds_read_b128 v[166:169], v153 offset:16384
	ds_read_b128 v[170:173], v153 offset:17408
	ds_read_b128 v[174:177], v153 offset:18432
	ds_read_b128 v[178:181], v153 offset:19456
	ds_read_b128 v[182:185], v153 offset:20480
	ds_read_b128 v[186:189], v153 offset:21504
	ds_read_b128 v[190:193], v153 offset:22528
	ds_read_b128 v[194:197], v153 offset:23552
	global_load_lds_dwordx4 v134, s[64:65]
	s_mov_b32 m0, s23
	s_nop 0
	global_load_lds_dwordx4 v130, s[64:65]
	s_barrier
	s_waitcnt lgkmcnt(0)
	s_waitcnt lgkmcnt(0)
	v_mfma_f32_16x16x32_bf16 v[60:63], v[146:149], v[166:169], v[60:63]
	v_mfma_f32_16x16x32_bf16 v[56:59], v[158:161], v[166:169], v[56:59]
	v_mfma_f32_16x16x32_bf16 v[44:47], v[146:149], v[174:177], v[44:47]
	v_mfma_f32_16x16x32_bf16 v[40:43], v[158:161], v[174:177], v[40:43]
	v_mfma_f32_16x16x32_bf16 v[28:31], v[146:149], v[182:185], v[28:31]
	v_mfma_f32_16x16x32_bf16 v[24:27], v[158:161], v[182:185], v[24:27]
	v_mfma_f32_16x16x32_bf16 v[12:15], v[146:149], v[190:193], v[12:15]
	v_mfma_f32_16x16x32_bf16 v[8:11], v[158:161], v[190:193], v[8:11]
	v_mfma_f32_16x16x32_bf16 v[60:63], v[154:157], v[170:173], v[60:63]
	v_mfma_f32_16x16x32_bf16 v[56:59], v[162:165], v[170:173], v[56:59]
	v_mfma_f32_16x16x32_bf16 v[44:47], v[154:157], v[178:181], v[44:47]
	v_mfma_f32_16x16x32_bf16 v[40:43], v[162:165], v[178:181], v[40:43]
	v_mfma_f32_16x16x32_bf16 v[28:31], v[154:157], v[186:189], v[28:31]
	v_mfma_f32_16x16x32_bf16 v[24:27], v[162:165], v[186:189], v[24:27]
	v_mfma_f32_16x16x32_bf16 v[12:15], v[154:157], v[194:197], v[12:15]
	v_mfma_f32_16x16x32_bf16 v[8:11], v[162:165], v[194:197], v[8:11]
	s_barrier
	s_bitset1_b32 s40, 7
	s_ashr_i32 s41, s40, 31
	s_lshl_b64 s[40:41], s[40:41], 11
	s_add_u32 s64, s70, s40
	s_addc_u32 s65, s71, s41
	s_add_u32 s40, s64, s38
	s_addc_u32 s41, s65, s39
	s_mov_b32 m0, s24
	s_nop 0
	global_load_lds_dwordx4 v132, s[40:41]
	s_mov_b32 m0, s25
	s_nop 0
	global_load_lds_dwordx4 v128, s[40:41]
	s_waitcnt vmcnt(6)
	s_barrier
	v_mfma_f32_16x16x32_bf16 v[52:55], v[198:201], v[166:169], v[52:55]
	v_mfma_f32_16x16x32_bf16 v[48:51], v[206:209], v[166:169], v[48:51]
	v_mfma_f32_16x16x32_bf16 v[36:39], v[198:201], v[174:177], v[36:39]
	v_mfma_f32_16x16x32_bf16 v[32:35], v[206:209], v[174:177], v[32:35]
	v_mfma_f32_16x16x32_bf16 v[20:23], v[198:201], v[182:185], v[20:23]
	v_mfma_f32_16x16x32_bf16 v[16:19], v[206:209], v[182:185], v[16:19]
	v_mfma_f32_16x16x32_bf16 v[4:7], v[198:201], v[190:193], v[4:7]
	v_mfma_f32_16x16x32_bf16 v[0:3], v[206:209], v[190:193], v[0:3]
	v_mfma_f32_16x16x32_bf16 v[52:55], v[202:205], v[170:173], v[52:55]
	v_mfma_f32_16x16x32_bf16 v[48:51], v[210:213], v[170:173], v[48:51]
	v_mfma_f32_16x16x32_bf16 v[36:39], v[202:205], v[178:181], v[36:39]
	v_mfma_f32_16x16x32_bf16 v[32:35], v[210:213], v[178:181], v[32:35]
	v_mfma_f32_16x16x32_bf16 v[20:23], v[202:205], v[186:189], v[20:23]
	v_mfma_f32_16x16x32_bf16 v[16:19], v[210:213], v[186:189], v[16:19]
	v_mfma_f32_16x16x32_bf16 v[4:7], v[202:205], v[194:197], v[4:7]
	v_mfma_f32_16x16x32_bf16 v[0:3], v[210:213], v[194:197], v[0:3]
	s_barrier
	ds_read_b128 v[146:149], v152 offset:32768
	ds_read_b128 v[154:157], v152 offset:33792
	ds_read_b128 v[158:161], v152 offset:34816
	ds_read_b128 v[162:165], v152 offset:35840
	s_bitset1_b32 s36, 7
	s_ashr_i32 s37, s36, 31
	s_lshl_b64 s[36:37], s[36:37], 11
	s_add_u32 s36, s16, s36
	s_addc_u32 s37, s17, s37
	s_add_u32 s36, s36, s38
	s_addc_u32 s37, s37, s39
	s_mov_b32 m0, s27
	ds_read_b128 v[166:169], v153 offset:32768
	ds_read_b128 v[170:173], v153 offset:33792
	ds_read_b128 v[174:177], v153 offset:34816
	ds_read_b128 v[178:181], v153 offset:35840
	ds_read_b128 v[182:185], v153 offset:36864
	ds_read_b128 v[186:189], v153 offset:37888
	ds_read_b128 v[190:193], v153 offset:38912
	ds_read_b128 v[194:197], v153 offset:39936
	global_load_lds_dwordx4 v134, s[36:37]
	s_mov_b32 m0, s30
	s_nop 0
	global_load_lds_dwordx4 v130, s[36:37]
	s_waitcnt lgkmcnt(8)
	s_barrier
	s_waitcnt lgkmcnt(0)
	s_waitcnt lgkmcnt(0)
	v_mfma_f32_16x16x32_bf16 v[124:127], v[146:149], v[166:169], v[124:127]
	v_mfma_f32_16x16x32_bf16 v[120:123], v[158:161], v[166:169], v[120:123]
	v_mfma_f32_16x16x32_bf16 v[108:111], v[146:149], v[174:177], v[108:111]
	v_mfma_f32_16x16x32_bf16 v[104:107], v[158:161], v[174:177], v[104:107]
	v_mfma_f32_16x16x32_bf16 v[92:95], v[146:149], v[182:185], v[92:95]
	v_mfma_f32_16x16x32_bf16 v[88:91], v[158:161], v[182:185], v[88:91]
	v_mfma_f32_16x16x32_bf16 v[76:79], v[146:149], v[190:193], v[76:79]
	v_mfma_f32_16x16x32_bf16 v[72:75], v[158:161], v[190:193], v[72:75]
	v_mfma_f32_16x16x32_bf16 v[124:127], v[154:157], v[170:173], v[124:127]
	v_mfma_f32_16x16x32_bf16 v[120:123], v[162:165], v[170:173], v[120:123]
	v_mfma_f32_16x16x32_bf16 v[108:111], v[154:157], v[178:181], v[108:111]
	v_mfma_f32_16x16x32_bf16 v[104:107], v[162:165], v[178:181], v[104:107]
	v_mfma_f32_16x16x32_bf16 v[92:95], v[154:157], v[186:189], v[92:95]
	v_mfma_f32_16x16x32_bf16 v[88:91], v[162:165], v[186:189], v[88:91]
	v_mfma_f32_16x16x32_bf16 v[76:79], v[154:157], v[194:197], v[76:79]
	v_mfma_f32_16x16x32_bf16 v[72:75], v[162:165], v[194:197], v[72:75]
	s_barrier
	s_or_b32 s8, s8, 1
	s_lshl_b64 s[36:37], s[8:9], 7
	s_add_u32 s38, s1, s36
	s_addc_u32 s39, s63, s37
	s_mov_b32 m0, s31
	ds_read_b128 v[198:201], v152 offset:49152
	ds_read_b128 v[202:205], v152 offset:50176
	ds_read_b128 v[206:209], v152 offset:51200
	ds_read_b128 v[210:213], v152 offset:52224
	global_load_lds_dwordx4 v132, s[38:39]
	s_mov_b32 m0, s33
	s_nop 0
	global_load_lds_dwordx4 v128, s[38:39]
	s_barrier
	s_waitcnt lgkmcnt(0)
	s_waitcnt lgkmcnt(0)
	v_mfma_f32_16x16x32_bf16 v[116:119], v[198:201], v[166:169], v[116:119]
	v_mfma_f32_16x16x32_bf16 v[112:115], v[206:209], v[166:169], v[112:115]
	v_mfma_f32_16x16x32_bf16 v[100:103], v[198:201], v[174:177], v[100:103]
	v_mfma_f32_16x16x32_bf16 v[96:99], v[206:209], v[174:177], v[96:99]
	v_mfma_f32_16x16x32_bf16 v[84:87], v[198:201], v[182:185], v[84:87]
	v_mfma_f32_16x16x32_bf16 v[80:83], v[206:209], v[182:185], v[80:83]
	v_mfma_f32_16x16x32_bf16 v[68:71], v[198:201], v[190:193], v[68:71]
	v_mfma_f32_16x16x32_bf16 v[64:67], v[206:209], v[190:193], v[64:67]
	v_mfma_f32_16x16x32_bf16 v[116:119], v[202:205], v[170:173], v[116:119]
	v_mfma_f32_16x16x32_bf16 v[112:115], v[210:213], v[170:173], v[112:115]
	v_mfma_f32_16x16x32_bf16 v[100:103], v[202:205], v[178:181], v[100:103]
	v_mfma_f32_16x16x32_bf16 v[96:99], v[210:213], v[178:181], v[96:99]
	v_mfma_f32_16x16x32_bf16 v[84:87], v[202:205], v[186:189], v[84:87]
	v_mfma_f32_16x16x32_bf16 v[80:83], v[210:213], v[186:189], v[80:83]
	v_mfma_f32_16x16x32_bf16 v[68:71], v[202:205], v[194:197], v[68:71]
	v_mfma_f32_16x16x32_bf16 v[64:67], v[210:213], v[194:197], v[64:67]
	s_add_u32 s38, s66, s36
	s_addc_u32 s39, s67, s37
	s_mov_b32 m0, s42
	s_barrier
	ds_read_b128 v[166:169], v153 offset:49152
	ds_read_b128 v[170:173], v153 offset:50176
	ds_read_b128 v[174:177], v153 offset:51200
	ds_read_b128 v[178:181], v153 offset:52224
	ds_read_b128 v[182:185], v153 offset:53248
	ds_read_b128 v[186:189], v153 offset:54272
	ds_read_b128 v[190:193], v153 offset:55296
	ds_read_b128 v[194:197], v153 offset:56320
	global_load_lds_dwordx4 v134, s[38:39]
	s_mov_b32 m0, s43
	s_nop 0
	global_load_lds_dwordx4 v130, s[38:39]
	s_barrier
	s_waitcnt lgkmcnt(0)
	s_waitcnt lgkmcnt(0)
	v_mfma_f32_16x16x32_bf16 v[60:63], v[146:149], v[166:169], v[60:63]
	v_mfma_f32_16x16x32_bf16 v[56:59], v[158:161], v[166:169], v[56:59]
	v_mfma_f32_16x16x32_bf16 v[44:47], v[146:149], v[174:177], v[44:47]
	v_mfma_f32_16x16x32_bf16 v[40:43], v[158:161], v[174:177], v[40:43]
	v_mfma_f32_16x16x32_bf16 v[28:31], v[146:149], v[182:185], v[28:31]
	v_mfma_f32_16x16x32_bf16 v[24:27], v[158:161], v[182:185], v[24:27]
	v_mfma_f32_16x16x32_bf16 v[12:15], v[146:149], v[190:193], v[12:15]
	v_mfma_f32_16x16x32_bf16 v[8:11], v[158:161], v[190:193], v[8:11]
	v_mfma_f32_16x16x32_bf16 v[60:63], v[154:157], v[170:173], v[60:63]
	v_mfma_f32_16x16x32_bf16 v[56:59], v[162:165], v[170:173], v[56:59]
	v_mfma_f32_16x16x32_bf16 v[44:47], v[154:157], v[178:181], v[44:47]
	v_mfma_f32_16x16x32_bf16 v[40:43], v[162:165], v[178:181], v[40:43]
	v_mfma_f32_16x16x32_bf16 v[28:31], v[154:157], v[186:189], v[28:31]
	v_mfma_f32_16x16x32_bf16 v[24:27], v[162:165], v[186:189], v[24:27]
	v_mfma_f32_16x16x32_bf16 v[12:15], v[154:157], v[194:197], v[12:15]
	v_mfma_f32_16x16x32_bf16 v[8:11], v[162:165], v[194:197], v[8:11]
	s_barrier
	s_add_u32 s36, s64, s36
	s_addc_u32 s37, s65, s37
	s_mov_b32 m0, s46
	s_nop 0
	global_load_lds_dwordx4 v132, s[36:37]
	s_mov_b32 m0, s47
	s_nop 0
	global_load_lds_dwordx4 v128, s[36:37]
	s_waitcnt vmcnt(6)
	s_barrier
	v_mfma_f32_16x16x32_bf16 v[52:55], v[198:201], v[166:169], v[52:55]
	v_mfma_f32_16x16x32_bf16 v[48:51], v[206:209], v[166:169], v[48:51]
	v_mfma_f32_16x16x32_bf16 v[36:39], v[198:201], v[174:177], v[36:39]
	v_mfma_f32_16x16x32_bf16 v[32:35], v[206:209], v[174:177], v[32:35]
	v_mfma_f32_16x16x32_bf16 v[20:23], v[198:201], v[182:185], v[20:23]
	v_mfma_f32_16x16x32_bf16 v[16:19], v[206:209], v[182:185], v[16:19]
	v_mfma_f32_16x16x32_bf16 v[4:7], v[198:201], v[190:193], v[4:7]
	v_mfma_f32_16x16x32_bf16 v[0:3], v[206:209], v[190:193], v[0:3]
	v_mfma_f32_16x16x32_bf16 v[52:55], v[202:205], v[170:173], v[52:55]
	v_mfma_f32_16x16x32_bf16 v[48:51], v[210:213], v[170:173], v[48:51]
	v_mfma_f32_16x16x32_bf16 v[36:39], v[202:205], v[178:181], v[36:39]
	v_mfma_f32_16x16x32_bf16 v[32:35], v[210:213], v[178:181], v[32:35]
	v_mfma_f32_16x16x32_bf16 v[20:23], v[202:205], v[186:189], v[20:23]
	v_mfma_f32_16x16x32_bf16 v[16:19], v[210:213], v[186:189], v[16:19]
	v_mfma_f32_16x16x32_bf16 v[4:7], v[202:205], v[194:197], v[4:7]
	v_mfma_f32_16x16x32_bf16 v[0:3], v[210:213], v[194:197], v[0:3]
	v_lshl_add_u64 v[142:143], v[142:143], 0, s[10:11]
	v_lshl_add_u64 v[144:145], v[144:145], 0, s[10:11]
	s_cmp_ge_u32 s62, s3
	s_mov_b32 s1, s62
	s_barrier
	s_cbranch_scc0 .LBB0_461
	s_andn2_b64 vcc, exec, s[28:29]
	s_cbranch_vccnz .LBB0_464
	s_bitset1_b32 s0, 7
	s_ashr_i32 s1, s0, 31
	s_lshl_b64 s[0:1], s[0:1], 11
	s_add_u32 s0, s16, s0
	s_addc_u32 s1, s17, s1
	v_lshl_add_u64 v[194:195], s[0:1], 0, v[134:135]
	s_mov_b32 m0, s53
	v_lshl_add_u64 v[194:195], v[194:195], 0, s[20:21]
	ds_read_b128 v[142:145], v152
	ds_read_b128 v[146:149], v152 offset:1024
	ds_read_b128 v[154:157], v152 offset:2048
	ds_read_b128 v[158:161], v152 offset:3072
	ds_read_b128 v[162:165], v153
	ds_read_b128 v[166:169], v153 offset:1024
	ds_read_b128 v[170:173], v153 offset:2048
	ds_read_b128 v[174:177], v153 offset:3072
	ds_read_b128 v[178:181], v153 offset:4096
	ds_read_b128 v[182:185], v153 offset:5120
	ds_read_b128 v[186:189], v153 offset:6144
	ds_read_b128 v[190:193], v153 offset:7168
	global_load_lds_dwordx4 v[194:195], off
	v_lshl_add_u64 v[194:195], s[0:1], 0, v[130:131]
	v_lshl_add_u64 v[194:195], v[194:195], 0, s[20:21]
	s_mov_b32 m0, s54
	s_nop 0
	global_load_lds_dwordx4 v[194:195], off
	s_barrier
	s_waitcnt lgkmcnt(0)
	s_waitcnt lgkmcnt(0)
	v_mfma_f32_16x16x32_bf16 v[124:127], v[142:145], v[162:165], v[124:127]
	v_mfma_f32_16x16x32_bf16 v[120:123], v[154:157], v[162:165], v[120:123]
	v_mfma_f32_16x16x32_bf16 v[108:111], v[142:145], v[170:173], v[108:111]
	v_mfma_f32_16x16x32_bf16 v[104:107], v[154:157], v[170:173], v[104:107]
	v_mfma_f32_16x16x32_bf16 v[92:95], v[142:145], v[178:181], v[92:95]
	v_mfma_f32_16x16x32_bf16 v[88:91], v[154:157], v[178:181], v[88:91]
	v_mfma_f32_16x16x32_bf16 v[76:79], v[142:145], v[186:189], v[76:79]
	v_mfma_f32_16x16x32_bf16 v[72:75], v[154:157], v[186:189], v[72:75]
	v_mfma_f32_16x16x32_bf16 v[124:127], v[146:149], v[166:169], v[124:127]
	v_mfma_f32_16x16x32_bf16 v[120:123], v[158:161], v[166:169], v[120:123]
	v_mfma_f32_16x16x32_bf16 v[108:111], v[146:149], v[174:177], v[108:111]
	v_mfma_f32_16x16x32_bf16 v[104:107], v[158:161], v[174:177], v[104:107]
	v_mfma_f32_16x16x32_bf16 v[92:95], v[146:149], v[182:185], v[92:95]
	v_mfma_f32_16x16x32_bf16 v[88:91], v[158:161], v[182:185], v[88:91]
	v_mfma_f32_16x16x32_bf16 v[76:79], v[146:149], v[190:193], v[76:79]
	v_mfma_f32_16x16x32_bf16 v[72:75], v[158:161], v[190:193], v[72:75]
	s_barrier
	ds_read_b128 v[194:197], v152 offset:16384
	ds_read_b128 v[198:201], v152 offset:17408
	ds_read_b128 v[202:205], v152 offset:18432
	ds_read_b128 v[206:209], v152 offset:19456
	s_barrier
	s_waitcnt lgkmcnt(0)
	s_waitcnt lgkmcnt(0)
	v_mfma_f32_16x16x32_bf16 v[116:119], v[194:197], v[162:165], v[116:119]
	v_mfma_f32_16x16x32_bf16 v[112:115], v[202:205], v[162:165], v[112:115]
	v_mfma_f32_16x16x32_bf16 v[100:103], v[194:197], v[170:173], v[100:103]
	v_mfma_f32_16x16x32_bf16 v[96:99], v[202:205], v[170:173], v[96:99]
	v_mfma_f32_16x16x32_bf16 v[84:87], v[194:197], v[178:181], v[84:87]
	v_mfma_f32_16x16x32_bf16 v[80:83], v[202:205], v[178:181], v[80:83]
	v_mfma_f32_16x16x32_bf16 v[68:71], v[194:197], v[186:189], v[68:71]
	v_mfma_f32_16x16x32_bf16 v[64:67], v[202:205], v[186:189], v[64:67]
	v_mfma_f32_16x16x32_bf16 v[116:119], v[198:201], v[166:169], v[116:119]
	v_mfma_f32_16x16x32_bf16 v[112:115], v[206:209], v[166:169], v[112:115]
	v_mfma_f32_16x16x32_bf16 v[100:103], v[198:201], v[174:177], v[100:103]
	v_mfma_f32_16x16x32_bf16 v[96:99], v[206:209], v[174:177], v[96:99]
	v_mfma_f32_16x16x32_bf16 v[84:87], v[198:201], v[182:185], v[84:87]
	v_mfma_f32_16x16x32_bf16 v[80:83], v[206:209], v[182:185], v[80:83]
	v_mfma_f32_16x16x32_bf16 v[68:71], v[198:201], v[190:193], v[68:71]
	v_mfma_f32_16x16x32_bf16 v[64:67], v[206:209], v[190:193], v[64:67]
	s_barrier
	ds_read_b128 v[162:165], v153 offset:16384
	ds_read_b128 v[166:169], v153 offset:17408
	ds_read_b128 v[170:173], v153 offset:18432
	ds_read_b128 v[174:177], v153 offset:19456
	ds_read_b128 v[178:181], v153 offset:20480
	ds_read_b128 v[182:185], v153 offset:21504
	ds_read_b128 v[186:189], v153 offset:22528
	ds_read_b128 v[190:193], v153 offset:23552
	s_waitcnt vmcnt(4)
	s_barrier
	s_waitcnt lgkmcnt(0)
	s_waitcnt lgkmcnt(0)
	v_mfma_f32_16x16x32_bf16 v[60:63], v[142:145], v[162:165], v[60:63]
	v_mfma_f32_16x16x32_bf16 v[56:59], v[154:157], v[162:165], v[56:59]
	v_mfma_f32_16x16x32_bf16 v[44:47], v[142:145], v[170:173], v[44:47]
	v_mfma_f32_16x16x32_bf16 v[40:43], v[154:157], v[170:173], v[40:43]
	v_mfma_f32_16x16x32_bf16 v[28:31], v[142:145], v[178:181], v[28:31]
	v_mfma_f32_16x16x32_bf16 v[24:27], v[154:157], v[178:181], v[24:27]
	v_mfma_f32_16x16x32_bf16 v[12:15], v[142:145], v[186:189], v[12:15]
	v_mfma_f32_16x16x32_bf16 v[8:11], v[154:157], v[186:189], v[8:11]
	v_mfma_f32_16x16x32_bf16 v[60:63], v[146:149], v[166:169], v[60:63]
	v_mfma_f32_16x16x32_bf16 v[56:59], v[158:161], v[166:169], v[56:59]
	v_mfma_f32_16x16x32_bf16 v[44:47], v[146:149], v[174:177], v[44:47]
	v_mfma_f32_16x16x32_bf16 v[40:43], v[158:161], v[174:177], v[40:43]
	v_mfma_f32_16x16x32_bf16 v[28:31], v[146:149], v[182:185], v[28:31]
	v_mfma_f32_16x16x32_bf16 v[24:27], v[158:161], v[182:185], v[24:27]
	v_mfma_f32_16x16x32_bf16 v[12:15], v[146:149], v[190:193], v[12:15]
	v_mfma_f32_16x16x32_bf16 v[8:11], v[158:161], v[190:193], v[8:11]
	v_mfma_f32_16x16x32_bf16 v[52:55], v[194:197], v[162:165], v[52:55]
	v_mfma_f32_16x16x32_bf16 v[48:51], v[202:205], v[162:165], v[48:51]
	v_mfma_f32_16x16x32_bf16 v[36:39], v[194:197], v[170:173], v[36:39]
	v_mfma_f32_16x16x32_bf16 v[32:35], v[202:205], v[170:173], v[32:35]
	v_mfma_f32_16x16x32_bf16 v[20:23], v[194:197], v[178:181], v[20:23]
	v_mfma_f32_16x16x32_bf16 v[16:19], v[202:205], v[178:181], v[16:19]
	v_mfma_f32_16x16x32_bf16 v[4:7], v[194:197], v[186:189], v[4:7]
	v_mfma_f32_16x16x32_bf16 v[0:3], v[202:205], v[186:189], v[0:3]
	v_mfma_f32_16x16x32_bf16 v[52:55], v[198:201], v[166:169], v[52:55]
	v_mfma_f32_16x16x32_bf16 v[48:51], v[206:209], v[166:169], v[48:51]
	v_mfma_f32_16x16x32_bf16 v[36:39], v[198:201], v[174:177], v[36:39]
	v_mfma_f32_16x16x32_bf16 v[32:35], v[206:209], v[174:177], v[32:35]
	v_mfma_f32_16x16x32_bf16 v[20:23], v[198:201], v[182:185], v[20:23]
	v_mfma_f32_16x16x32_bf16 v[16:19], v[206:209], v[182:185], v[16:19]
	v_mfma_f32_16x16x32_bf16 v[4:7], v[198:201], v[190:193], v[4:7]
	v_mfma_f32_16x16x32_bf16 v[0:3], v[206:209], v[190:193], v[0:3]
	s_barrier
	ds_read_b128 v[142:145], v152 offset:32768
	ds_read_b128 v[146:149], v152 offset:33792
	ds_read_b128 v[154:157], v152 offset:34816
	ds_read_b128 v[158:161], v152 offset:35840
	ds_read_b128 v[162:165], v153 offset:32768
	ds_read_b128 v[166:169], v153 offset:33792
	ds_read_b128 v[170:173], v153 offset:34816
	ds_read_b128 v[174:177], v153 offset:35840
	ds_read_b128 v[178:181], v153 offset:36864
	ds_read_b128 v[182:185], v153 offset:37888
	ds_read_b128 v[186:189], v153 offset:38912
	ds_read_b128 v[190:193], v153 offset:39936
	s_waitcnt vmcnt(2)
	s_barrier
	s_waitcnt lgkmcnt(0)
	s_waitcnt lgkmcnt(0)
	v_mfma_f32_16x16x32_bf16 v[124:127], v[142:145], v[162:165], v[124:127]
	v_mfma_f32_16x16x32_bf16 v[120:123], v[154:157], v[162:165], v[120:123]
	v_mfma_f32_16x16x32_bf16 v[108:111], v[142:145], v[170:173], v[108:111]
	v_mfma_f32_16x16x32_bf16 v[104:107], v[154:157], v[170:173], v[104:107]
	v_mfma_f32_16x16x32_bf16 v[92:95], v[142:145], v[178:181], v[92:95]
	v_mfma_f32_16x16x32_bf16 v[88:91], v[154:157], v[178:181], v[88:91]
	v_mfma_f32_16x16x32_bf16 v[76:79], v[142:145], v[186:189], v[76:79]
	v_mfma_f32_16x16x32_bf16 v[72:75], v[154:157], v[186:189], v[72:75]
	v_mfma_f32_16x16x32_bf16 v[124:127], v[146:149], v[166:169], v[124:127]
	v_mfma_f32_16x16x32_bf16 v[120:123], v[158:161], v[166:169], v[120:123]
	v_mfma_f32_16x16x32_bf16 v[108:111], v[146:149], v[174:177], v[108:111]
	v_mfma_f32_16x16x32_bf16 v[104:107], v[158:161], v[174:177], v[104:107]
	v_mfma_f32_16x16x32_bf16 v[92:95], v[146:149], v[182:185], v[92:95]
	v_mfma_f32_16x16x32_bf16 v[88:91], v[158:161], v[182:185], v[88:91]
	v_mfma_f32_16x16x32_bf16 v[76:79], v[146:149], v[190:193], v[76:79]
	v_mfma_f32_16x16x32_bf16 v[72:75], v[158:161], v[190:193], v[72:75]
	s_barrier
	ds_read_b128 v[194:197], v152 offset:49152
	ds_read_b128 v[198:201], v152 offset:50176
	ds_read_b128 v[202:205], v152 offset:51200
	ds_read_b128 v[206:209], v152 offset:52224
	s_waitcnt vmcnt(0)
	s_barrier
	s_waitcnt lgkmcnt(0)
	s_waitcnt lgkmcnt(0)
	v_mfma_f32_16x16x32_bf16 v[116:119], v[194:197], v[162:165], v[116:119]
	v_mfma_f32_16x16x32_bf16 v[112:115], v[202:205], v[162:165], v[112:115]
	v_mfma_f32_16x16x32_bf16 v[100:103], v[194:197], v[170:173], v[100:103]
	v_mfma_f32_16x16x32_bf16 v[96:99], v[202:205], v[170:173], v[96:99]
	v_mfma_f32_16x16x32_bf16 v[84:87], v[194:197], v[178:181], v[84:87]
	v_mfma_f32_16x16x32_bf16 v[80:83], v[202:205], v[178:181], v[80:83]
	v_mfma_f32_16x16x32_bf16 v[68:71], v[194:197], v[186:189], v[68:71]
	v_mfma_f32_16x16x32_bf16 v[64:67], v[202:205], v[186:189], v[64:67]
	v_mfma_f32_16x16x32_bf16 v[116:119], v[198:201], v[166:169], v[116:119]
	v_mfma_f32_16x16x32_bf16 v[112:115], v[206:209], v[166:169], v[112:115]
	v_mfma_f32_16x16x32_bf16 v[100:103], v[198:201], v[174:177], v[100:103]
	v_mfma_f32_16x16x32_bf16 v[96:99], v[206:209], v[174:177], v[96:99]
	v_mfma_f32_16x16x32_bf16 v[84:87], v[198:201], v[182:185], v[84:87]
	v_mfma_f32_16x16x32_bf16 v[80:83], v[206:209], v[182:185], v[80:83]
	v_mfma_f32_16x16x32_bf16 v[68:71], v[198:201], v[190:193], v[68:71]
	v_mfma_f32_16x16x32_bf16 v[64:67], v[206:209], v[190:193], v[64:67]
	s_barrier
	ds_read_b128 v[162:165], v153 offset:49152
	ds_read_b128 v[166:169], v153 offset:50176
	ds_read_b128 v[170:173], v153 offset:51200
	ds_read_b128 v[174:177], v153 offset:52224
	ds_read_b128 v[178:181], v153 offset:53248
	ds_read_b128 v[182:185], v153 offset:54272
	ds_read_b128 v[186:189], v153 offset:55296
	ds_read_b128 v[190:193], v153 offset:56320
	s_barrier
	s_waitcnt lgkmcnt(0)
	s_waitcnt lgkmcnt(0)
	v_mfma_f32_16x16x32_bf16 v[60:63], v[142:145], v[162:165], v[60:63]
	v_mfma_f32_16x16x32_bf16 v[56:59], v[154:157], v[162:165], v[56:59]
	v_mfma_f32_16x16x32_bf16 v[44:47], v[142:145], v[170:173], v[44:47]
	v_mfma_f32_16x16x32_bf16 v[40:43], v[154:157], v[170:173], v[40:43]
	v_mfma_f32_16x16x32_bf16 v[28:31], v[142:145], v[178:181], v[28:31]
	v_mfma_f32_16x16x32_bf16 v[24:27], v[154:157], v[178:181], v[24:27]
	v_mfma_f32_16x16x32_bf16 v[12:15], v[142:145], v[186:189], v[12:15]
	v_mfma_f32_16x16x32_bf16 v[8:11], v[154:157], v[186:189], v[8:11]
	v_mfma_f32_16x16x32_bf16 v[60:63], v[146:149], v[166:169], v[60:63]
	v_mfma_f32_16x16x32_bf16 v[56:59], v[158:161], v[166:169], v[56:59]
	v_mfma_f32_16x16x32_bf16 v[44:47], v[146:149], v[174:177], v[44:47]
	v_mfma_f32_16x16x32_bf16 v[40:43], v[158:161], v[174:177], v[40:43]
	v_mfma_f32_16x16x32_bf16 v[28:31], v[146:149], v[182:185], v[28:31]
	v_mfma_f32_16x16x32_bf16 v[24:27], v[158:161], v[182:185], v[24:27]
	v_mfma_f32_16x16x32_bf16 v[12:15], v[146:149], v[190:193], v[12:15]
	v_mfma_f32_16x16x32_bf16 v[8:11], v[158:161], v[190:193], v[8:11]
	v_mfma_f32_16x16x32_bf16 v[52:55], v[194:197], v[162:165], v[52:55]
	v_mfma_f32_16x16x32_bf16 v[48:51], v[202:205], v[162:165], v[48:51]
	v_mfma_f32_16x16x32_bf16 v[36:39], v[194:197], v[170:173], v[36:39]
	v_mfma_f32_16x16x32_bf16 v[32:35], v[202:205], v[170:173], v[32:35]
	v_mfma_f32_16x16x32_bf16 v[20:23], v[194:197], v[178:181], v[20:23]
	v_mfma_f32_16x16x32_bf16 v[16:19], v[202:205], v[178:181], v[16:19]
	v_mfma_f32_16x16x32_bf16 v[4:7], v[194:197], v[186:189], v[4:7]
	v_mfma_f32_16x16x32_bf16 v[0:3], v[202:205], v[186:189], v[0:3]
	v_mfma_f32_16x16x32_bf16 v[52:55], v[198:201], v[166:169], v[52:55]
	v_mfma_f32_16x16x32_bf16 v[48:51], v[206:209], v[166:169], v[48:51]
	v_mfma_f32_16x16x32_bf16 v[36:39], v[198:201], v[174:177], v[36:39]
	v_mfma_f32_16x16x32_bf16 v[32:35], v[206:209], v[174:177], v[32:35]
	v_mfma_f32_16x16x32_bf16 v[20:23], v[198:201], v[182:185], v[20:23]
	v_mfma_f32_16x16x32_bf16 v[16:19], v[206:209], v[182:185], v[16:19]
	v_mfma_f32_16x16x32_bf16 v[4:7], v[198:201], v[190:193], v[4:7]
	v_mfma_f32_16x16x32_bf16 v[0:3], v[206:209], v[190:193], v[0:3]
	s_barrier

.LBB0_609:
	ds_read_b128 v[148:151], v146
	ds_read_b128 v[152:155], v146 offset:1024
	ds_read_b128 v[156:159], v146 offset:2048
	ds_read_b128 v[160:163], v146 offset:3072
	s_add_i32 s56, s21, 2
	s_cmp_eq_u32 s21, 0
	s_cselect_b32 s36, s26, s52
	s_cselect_b32 s28, s20, s51
	s_mov_b32 m0, s46
	ds_read_b128 v[164:167], v147
	ds_read_b128 v[168:171], v147 offset:1024
	ds_read_b128 v[172:175], v147 offset:2048
	ds_read_b128 v[176:179], v147 offset:3072
	ds_read_b128 v[180:183], v147 offset:4096
	ds_read_b128 v[184:187], v147 offset:5120
	ds_read_b128 v[188:191], v147 offset:6144
	ds_read_b128 v[192:195], v147 offset:7168
	global_load_lds_dwordx4 v[140:141], off
	s_mov_b32 m0, s47
	s_nop 0
	global_load_lds_dwordx4 v[142:143], off
	s_waitcnt lgkmcnt(8)
	s_barrier
	s_waitcnt lgkmcnt(0)
	s_waitcnt lgkmcnt(0)
	v_mfma_f32_16x16x32_bf16 v[124:127], v[148:151], v[164:167], v[124:127]
	v_mfma_f32_16x16x32_bf16 v[120:123], v[156:159], v[164:167], v[120:123]
	v_mfma_f32_16x16x32_bf16 v[116:119], v[148:151], v[172:175], v[116:119]
	v_mfma_f32_16x16x32_bf16 v[108:111], v[156:159], v[172:175], v[108:111]
	v_mfma_f32_16x16x32_bf16 v[100:103], v[148:151], v[180:183], v[100:103]
	v_mfma_f32_16x16x32_bf16 v[92:95], v[156:159], v[180:183], v[92:95]
	v_mfma_f32_16x16x32_bf16 v[84:87], v[148:151], v[188:191], v[84:87]
	v_mfma_f32_16x16x32_bf16 v[76:79], v[156:159], v[188:191], v[76:79]
	v_mfma_f32_16x16x32_bf16 v[124:127], v[152:155], v[168:171], v[124:127]
	v_mfma_f32_16x16x32_bf16 v[120:123], v[160:163], v[168:171], v[120:123]
	v_mfma_f32_16x16x32_bf16 v[116:119], v[152:155], v[176:179], v[116:119]
	v_mfma_f32_16x16x32_bf16 v[108:111], v[160:163], v[176:179], v[108:111]
	v_mfma_f32_16x16x32_bf16 v[100:103], v[152:155], v[184:187], v[100:103]
	v_mfma_f32_16x16x32_bf16 v[92:95], v[160:163], v[184:187], v[92:95]
	v_mfma_f32_16x16x32_bf16 v[84:87], v[152:155], v[192:195], v[84:87]
	v_mfma_f32_16x16x32_bf16 v[76:79], v[160:163], v[192:195], v[76:79]
	s_barrier
	s_cselect_b32 s21, 0x100, 0
	s_ashr_i32 s37, s36, 31
	s_lshl_b64 s[58:59], s[36:37], 9
	s_add_u32 s29, s17, s58
	s_addc_u32 s37, s18, s59
	s_add_u32 s58, s29, s21
	s_addc_u32 s59, s37, 0
	s_mov_b32 m0, s22
	v_lshl_add_u64 v[212:213], s[58:59], 0, v[132:133]
	ds_read_b128 v[196:199], v146 offset:16384
	ds_read_b128 v[200:203], v146 offset:17408
	ds_read_b128 v[204:207], v146 offset:18432
	ds_read_b128 v[208:211], v146 offset:19456
	global_load_lds_dwordx4 v[212:213], off
	v_lshl_add_u64 v[214:215], s[58:59], 0, v[128:129]
	s_mov_b32 m0, s23
	s_nop 0
	global_load_lds_dwordx4 v[214:215], off
	s_barrier
	s_waitcnt lgkmcnt(0)
	s_waitcnt lgkmcnt(0)
	v_mfma_f32_16x16x32_bf16 v[112:115], v[196:199], v[164:167], v[112:115]
	v_mfma_f32_16x16x32_bf16 v[104:107], v[204:207], v[164:167], v[104:107]
	v_mfma_f32_16x16x32_bf16 v[96:99], v[196:199], v[172:175], v[96:99]
	v_mfma_f32_16x16x32_bf16 v[88:91], v[204:207], v[172:175], v[88:91]
	v_mfma_f32_16x16x32_bf16 v[80:83], v[196:199], v[180:183], v[80:83]
	v_mfma_f32_16x16x32_bf16 v[72:75], v[204:207], v[180:183], v[72:75]
	v_mfma_f32_16x16x32_bf16 v[68:71], v[196:199], v[188:191], v[68:71]
	v_mfma_f32_16x16x32_bf16 v[64:67], v[204:207], v[188:191], v[64:67]
	v_mfma_f32_16x16x32_bf16 v[112:115], v[200:203], v[168:171], v[112:115]
	v_mfma_f32_16x16x32_bf16 v[104:107], v[208:211], v[168:171], v[104:107]
	v_mfma_f32_16x16x32_bf16 v[96:99], v[200:203], v[176:179], v[96:99]
	v_mfma_f32_16x16x32_bf16 v[88:91], v[208:211], v[176:179], v[88:91]
	v_mfma_f32_16x16x32_bf16 v[80:83], v[200:203], v[184:187], v[80:83]
	v_mfma_f32_16x16x32_bf16 v[72:75], v[208:211], v[184:187], v[72:75]
	v_mfma_f32_16x16x32_bf16 v[68:71], v[200:203], v[192:195], v[68:71]
	v_mfma_f32_16x16x32_bf16 v[64:67], v[208:211], v[192:195], v[64:67]
	s_ashr_i32 s29, s28, 31
	s_lshl_b64 s[58:59], s[28:29], 9
	s_add_u32 s29, s9, s58
	s_addc_u32 s37, s16, s59
	s_add_u32 s58, s29, s21
	s_addc_u32 s59, s37, 0
	s_mov_b32 m0, s19
	v_lshl_add_u64 v[216:217], s[58:59], 0, v[134:135]
	s_barrier
	ds_read_b128 v[164:167], v147 offset:16384
	ds_read_b128 v[168:171], v147 offset:17408
	ds_read_b128 v[172:175], v147 offset:18432
	ds_read_b128 v[176:179], v147 offset:19456
	ds_read_b128 v[180:183], v147 offset:20480
	ds_read_b128 v[184:187], v147 offset:21504
	ds_read_b128 v[188:191], v147 offset:22528
	ds_read_b128 v[192:195], v147 offset:23552
	global_load_lds_dwordx4 v[216:217], off
	v_lshl_add_u64 v[218:219], s[58:59], 0, v[130:131]
	s_mov_b32 m0, s24
	s_nop 0
	global_load_lds_dwordx4 v[218:219], off
	s_barrier
	s_waitcnt lgkmcnt(0)
	s_waitcnt lgkmcnt(0)
	v_mfma_f32_16x16x32_bf16 v[60:63], v[148:151], v[164:167], v[60:63]
	v_mfma_f32_16x16x32_bf16 v[56:59], v[156:159], v[164:167], v[56:59]
	v_mfma_f32_16x16x32_bf16 v[52:55], v[148:151], v[172:175], v[52:55]
	v_mfma_f32_16x16x32_bf16 v[44:47], v[156:159], v[172:175], v[44:47]
	v_mfma_f32_16x16x32_bf16 v[36:39], v[148:151], v[180:183], v[36:39]
	v_mfma_f32_16x16x32_bf16 v[28:31], v[156:159], v[180:183], v[28:31]
	v_mfma_f32_16x16x32_bf16 v[20:23], v[148:151], v[188:191], v[20:23]
	v_mfma_f32_16x16x32_bf16 v[12:15], v[156:159], v[188:191], v[12:15]
	v_mfma_f32_16x16x32_bf16 v[60:63], v[152:155], v[168:171], v[60:63]
	v_mfma_f32_16x16x32_bf16 v[56:59], v[160:163], v[168:171], v[56:59]
	v_mfma_f32_16x16x32_bf16 v[52:55], v[152:155], v[176:179], v[52:55]
	v_mfma_f32_16x16x32_bf16 v[44:47], v[160:163], v[176:179], v[44:47]
	v_mfma_f32_16x16x32_bf16 v[36:39], v[152:155], v[184:187], v[36:39]
	v_mfma_f32_16x16x32_bf16 v[28:31], v[160:163], v[184:187], v[28:31]
	v_mfma_f32_16x16x32_bf16 v[20:23], v[152:155], v[192:195], v[20:23]
	v_mfma_f32_16x16x32_bf16 v[12:15], v[160:163], v[192:195], v[12:15]
	s_barrier
	s_bitset1_b32 s36, 7
	s_ashr_i32 s37, s36, 31
	s_lshl_b64 s[36:37], s[36:37], 9
	s_add_u32 s29, s17, s36
	s_addc_u32 s37, s18, s37
	s_add_u32 s36, s29, s21
	s_addc_u32 s37, s37, 0
	s_mov_b32 m0, s25
	v_lshl_add_u64 v[220:221], s[36:37], 0, v[132:133]
	global_load_lds_dwordx4 v[220:221], off
	v_lshl_add_u64 v[222:223], s[36:37], 0, v[128:129]
	s_mov_b32 m0, s27
	s_nop 0
	global_load_lds_dwordx4 v[222:223], off
	s_waitcnt vmcnt(6)
	s_barrier
	v_mfma_f32_16x16x32_bf16 v[48:51], v[196:199], v[164:167], v[48:51]
	v_mfma_f32_16x16x32_bf16 v[40:43], v[204:207], v[164:167], v[40:43]
	v_mfma_f32_16x16x32_bf16 v[32:35], v[196:199], v[172:175], v[32:35]
	v_mfma_f32_16x16x32_bf16 v[24:27], v[204:207], v[172:175], v[24:27]
	v_mfma_f32_16x16x32_bf16 v[16:19], v[196:199], v[180:183], v[16:19]
	v_mfma_f32_16x16x32_bf16 v[8:11], v[204:207], v[180:183], v[8:11]
	v_mfma_f32_16x16x32_bf16 v[4:7], v[196:199], v[188:191], v[4:7]
	v_mfma_f32_16x16x32_bf16 v[0:3], v[204:207], v[188:191], v[0:3]
	v_mfma_f32_16x16x32_bf16 v[48:51], v[200:203], v[168:171], v[48:51]
	v_mfma_f32_16x16x32_bf16 v[40:43], v[208:211], v[168:171], v[40:43]
	v_mfma_f32_16x16x32_bf16 v[32:35], v[200:203], v[176:179], v[32:35]
	v_mfma_f32_16x16x32_bf16 v[24:27], v[208:211], v[176:179], v[24:27]
	v_mfma_f32_16x16x32_bf16 v[16:19], v[200:203], v[184:187], v[16:19]
	v_mfma_f32_16x16x32_bf16 v[8:11], v[208:211], v[184:187], v[8:11]
	v_mfma_f32_16x16x32_bf16 v[4:7], v[200:203], v[192:195], v[4:7]
	v_mfma_f32_16x16x32_bf16 v[0:3], v[208:211], v[192:195], v[0:3]
	s_barrier
	ds_read_b128 v[148:151], v146 offset:32768
	ds_read_b128 v[152:155], v146 offset:33792
	ds_read_b128 v[156:159], v146 offset:34816
	ds_read_b128 v[160:163], v146 offset:35840
	s_bitset1_b32 s28, 7
	s_ashr_i32 s29, s28, 31
	s_lshl_b64 s[28:29], s[28:29], 9
	s_add_u32 s28, s9, s28
	s_addc_u32 s29, s16, s29
	s_add_u32 s28, s28, s21
	s_addc_u32 s29, s29, 0
	s_mov_b32 m0, s30
	ds_read_b128 v[164:167], v147 offset:32768
	ds_read_b128 v[168:171], v147 offset:33792
	ds_read_b128 v[172:175], v147 offset:34816
	ds_read_b128 v[176:179], v147 offset:35840
	ds_read_b128 v[180:183], v147 offset:36864
	ds_read_b128 v[184:187], v147 offset:37888
	ds_read_b128 v[188:191], v147 offset:38912
	ds_read_b128 v[192:195], v147 offset:39936
	global_load_lds_dwordx4 v134, s[28:29]
	s_mov_b32 m0, s31
	s_nop 0
	global_load_lds_dwordx4 v130, s[28:29]
	s_waitcnt lgkmcnt(8)
	s_barrier
	s_waitcnt lgkmcnt(0)
	s_waitcnt lgkmcnt(0)
	v_mfma_f32_16x16x32_bf16 v[124:127], v[148:151], v[164:167], v[124:127]
	v_mfma_f32_16x16x32_bf16 v[120:123], v[156:159], v[164:167], v[120:123]
	v_mfma_f32_16x16x32_bf16 v[116:119], v[148:151], v[172:175], v[116:119]
	v_mfma_f32_16x16x32_bf16 v[108:111], v[156:159], v[172:175], v[108:111]
	v_mfma_f32_16x16x32_bf16 v[100:103], v[148:151], v[180:183], v[100:103]
	v_mfma_f32_16x16x32_bf16 v[92:95], v[156:159], v[180:183], v[92:95]
	v_mfma_f32_16x16x32_bf16 v[84:87], v[148:151], v[188:191], v[84:87]
	v_mfma_f32_16x16x32_bf16 v[76:79], v[156:159], v[188:191], v[76:79]
	v_mfma_f32_16x16x32_bf16 v[124:127], v[152:155], v[168:171], v[124:127]
	v_mfma_f32_16x16x32_bf16 v[120:123], v[160:163], v[168:171], v[120:123]
	v_mfma_f32_16x16x32_bf16 v[116:119], v[152:155], v[176:179], v[116:119]
	v_mfma_f32_16x16x32_bf16 v[108:111], v[160:163], v[176:179], v[108:111]
	v_mfma_f32_16x16x32_bf16 v[100:103], v[152:155], v[184:187], v[100:103]
	v_mfma_f32_16x16x32_bf16 v[92:95], v[160:163], v[184:187], v[92:95]
	v_mfma_f32_16x16x32_bf16 v[84:87], v[152:155], v[192:195], v[84:87]
	v_mfma_f32_16x16x32_bf16 v[76:79], v[160:163], v[192:195], v[76:79]
	s_barrier
	s_mov_b32 m0, s33
	v_lshl_add_u64 v[212:213], v[212:213], 0, s[0:1]
	ds_read_b128 v[196:199], v146 offset:49152
	ds_read_b128 v[200:203], v146 offset:50176
	ds_read_b128 v[204:207], v146 offset:51200
	ds_read_b128 v[208:211], v146 offset:52224
	global_load_lds_dwordx4 v[212:213], off
	v_lshl_add_u64 v[212:213], v[214:215], 0, s[0:1]
	s_mov_b32 m0, s38
	s_nop 0
	global_load_lds_dwordx4 v[212:213], off
	s_barrier
	s_waitcnt lgkmcnt(0)
	s_waitcnt lgkmcnt(0)
	v_mfma_f32_16x16x32_bf16 v[112:115], v[196:199], v[164:167], v[112:115]
	v_mfma_f32_16x16x32_bf16 v[104:107], v[204:207], v[164:167], v[104:107]
	v_mfma_f32_16x16x32_bf16 v[96:99], v[196:199], v[172:175], v[96:99]
	v_mfma_f32_16x16x32_bf16 v[88:91], v[204:207], v[172:175], v[88:91]
	v_mfma_f32_16x16x32_bf16 v[80:83], v[196:199], v[180:183], v[80:83]
	v_mfma_f32_16x16x32_bf16 v[72:75], v[204:207], v[180:183], v[72:75]
	v_mfma_f32_16x16x32_bf16 v[68:71], v[196:199], v[188:191], v[68:71]
	v_mfma_f32_16x16x32_bf16 v[64:67], v[204:207], v[188:191], v[64:67]
	v_mfma_f32_16x16x32_bf16 v[112:115], v[200:203], v[168:171], v[112:115]
	v_mfma_f32_16x16x32_bf16 v[104:107], v[208:211], v[168:171], v[104:107]
	v_mfma_f32_16x16x32_bf16 v[96:99], v[200:203], v[176:179], v[96:99]
	v_mfma_f32_16x16x32_bf16 v[88:91], v[208:211], v[176:179], v[88:91]
	v_mfma_f32_16x16x32_bf16 v[80:83], v[200:203], v[184:187], v[80:83]
	v_mfma_f32_16x16x32_bf16 v[72:75], v[208:211], v[184:187], v[72:75]
	v_mfma_f32_16x16x32_bf16 v[68:71], v[200:203], v[192:195], v[68:71]
	v_mfma_f32_16x16x32_bf16 v[64:67], v[208:211], v[192:195], v[64:67]
	s_mov_b32 m0, s39
	v_lshl_add_u64 v[212:213], v[216:217], 0, s[0:1]
	s_barrier
	ds_read_b128 v[164:167], v147 offset:49152
	ds_read_b128 v[168:171], v147 offset:50176
	ds_read_b128 v[172:175], v147 offset:51200
	ds_read_b128 v[176:179], v147 offset:52224
	ds_read_b128 v[180:183], v147 offset:53248
	ds_read_b128 v[184:187], v147 offset:54272
	ds_read_b128 v[188:191], v147 offset:55296
	ds_read_b128 v[192:195], v147 offset:56320
	global_load_lds_dwordx4 v[212:213], off
	v_lshl_add_u64 v[212:213], v[218:219], 0, s[0:1]
	s_mov_b32 m0, s40
	s_nop 0
	global_load_lds_dwordx4 v[212:213], off
	s_barrier
	s_waitcnt lgkmcnt(0)
	s_waitcnt lgkmcnt(0)
	v_mfma_f32_16x16x32_bf16 v[60:63], v[148:151], v[164:167], v[60:63]
	v_mfma_f32_16x16x32_bf16 v[56:59], v[156:159], v[164:167], v[56:59]
	v_mfma_f32_16x16x32_bf16 v[52:55], v[148:151], v[172:175], v[52:55]
	v_mfma_f32_16x16x32_bf16 v[44:47], v[156:159], v[172:175], v[44:47]
	v_mfma_f32_16x16x32_bf16 v[36:39], v[148:151], v[180:183], v[36:39]
	v_mfma_f32_16x16x32_bf16 v[28:31], v[156:159], v[180:183], v[28:31]
	v_mfma_f32_16x16x32_bf16 v[20:23], v[148:151], v[188:191], v[20:23]
	v_mfma_f32_16x16x32_bf16 v[12:15], v[156:159], v[188:191], v[12:15]
	v_mfma_f32_16x16x32_bf16 v[60:63], v[152:155], v[168:171], v[60:63]
	v_mfma_f32_16x16x32_bf16 v[56:59], v[160:163], v[168:171], v[56:59]
	v_mfma_f32_16x16x32_bf16 v[52:55], v[152:155], v[176:179], v[52:55]
	v_mfma_f32_16x16x32_bf16 v[44:47], v[160:163], v[176:179], v[44:47]
	v_mfma_f32_16x16x32_bf16 v[36:39], v[152:155], v[184:187], v[36:39]
	v_mfma_f32_16x16x32_bf16 v[28:31], v[160:163], v[184:187], v[28:31]
	v_mfma_f32_16x16x32_bf16 v[20:23], v[152:155], v[192:195], v[20:23]
	v_mfma_f32_16x16x32_bf16 v[12:15], v[160:163], v[192:195], v[12:15]
	s_barrier
	s_mov_b32 m0, s41
	v_lshl_add_u64 v[148:149], v[220:221], 0, s[0:1]
	global_load_lds_dwordx4 v[148:149], off
	v_lshl_add_u64 v[148:149], v[222:223], 0, s[0:1]
	s_mov_b32 m0, s42
	s_nop 0
	global_load_lds_dwordx4 v[148:149], off
	s_waitcnt vmcnt(6)
	s_barrier
	v_mfma_f32_16x16x32_bf16 v[48:51], v[196:199], v[164:167], v[48:51]
	v_mfma_f32_16x16x32_bf16 v[40:43], v[204:207], v[164:167], v[40:43]
	v_mfma_f32_16x16x32_bf16 v[32:35], v[196:199], v[172:175], v[32:35]
	v_mfma_f32_16x16x32_bf16 v[24:27], v[204:207], v[172:175], v[24:27]
	v_mfma_f32_16x16x32_bf16 v[16:19], v[196:199], v[180:183], v[16:19]
	v_mfma_f32_16x16x32_bf16 v[8:11], v[204:207], v[180:183], v[8:11]
	v_mfma_f32_16x16x32_bf16 v[4:7], v[196:199], v[188:191], v[4:7]
	v_mfma_f32_16x16x32_bf16 v[0:3], v[204:207], v[188:191], v[0:3]
	v_mfma_f32_16x16x32_bf16 v[48:51], v[200:203], v[168:171], v[48:51]
	v_mfma_f32_16x16x32_bf16 v[40:43], v[208:211], v[168:171], v[40:43]
	v_mfma_f32_16x16x32_bf16 v[32:35], v[200:203], v[176:179], v[32:35]
	v_mfma_f32_16x16x32_bf16 v[24:27], v[208:211], v[176:179], v[24:27]
	v_mfma_f32_16x16x32_bf16 v[16:19], v[200:203], v[184:187], v[16:19]
	v_mfma_f32_16x16x32_bf16 v[8:11], v[208:211], v[184:187], v[8:11]
	v_mfma_f32_16x16x32_bf16 v[4:7], v[200:203], v[192:195], v[4:7]
	v_mfma_f32_16x16x32_bf16 v[0:3], v[208:211], v[192:195], v[0:3]
	v_lshl_add_u64 v[140:141], v[140:141], 0, s[4:5]
	v_lshl_add_u64 v[142:143], v[142:143], 0, s[4:5]
	s_cmp_ge_u32 s56, s55
	s_mov_b32 s21, s56
	s_barrier
	s_cbranch_scc0 .LBB0_609
	s_andn2_b64 vcc, exec, s[10:11]
	s_cbranch_vccnz .LBB0_605
	s_bitset1_b32 s20, 7
	s_ashr_i32 s21, s20, 31
	s_lshl_b64 s[20:21], s[20:21], 9
	s_add_u32 s20, s9, s20
	s_addc_u32 s21, s16, s21
	v_lshl_add_u64 v[192:193], s[20:21], 0, v[134:135]
	s_mov_b32 m0, s46
	v_lshl_add_u64 v[192:193], v[192:193], 0, s[6:7]
	ds_read_b128 v[140:143], v146
	ds_read_b128 v[148:151], v146 offset:1024
	ds_read_b128 v[152:155], v146 offset:2048
	ds_read_b128 v[156:159], v146 offset:3072
	ds_read_b128 v[160:163], v147
	ds_read_b128 v[164:167], v147 offset:1024
	ds_read_b128 v[168:171], v147 offset:2048
	ds_read_b128 v[172:175], v147 offset:3072
	ds_read_b128 v[176:179], v147 offset:4096
	ds_read_b128 v[180:183], v147 offset:5120
	ds_read_b128 v[184:187], v147 offset:6144
	ds_read_b128 v[188:191], v147 offset:7168
	global_load_lds_dwordx4 v[192:193], off
	v_lshl_add_u64 v[192:193], s[20:21], 0, v[130:131]
	v_lshl_add_u64 v[192:193], v[192:193], 0, s[6:7]
	s_mov_b32 m0, s47
	s_nop 0
	global_load_lds_dwordx4 v[192:193], off
	s_barrier
	s_waitcnt lgkmcnt(0)
	s_waitcnt lgkmcnt(0)
	v_mfma_f32_16x16x32_bf16 v[124:127], v[140:143], v[160:163], v[124:127]
	v_mfma_f32_16x16x32_bf16 v[120:123], v[152:155], v[160:163], v[120:123]
	v_mfma_f32_16x16x32_bf16 v[116:119], v[140:143], v[168:171], v[116:119]
	v_mfma_f32_16x16x32_bf16 v[108:111], v[152:155], v[168:171], v[108:111]
	v_mfma_f32_16x16x32_bf16 v[100:103], v[140:143], v[176:179], v[100:103]
	v_mfma_f32_16x16x32_bf16 v[92:95], v[152:155], v[176:179], v[92:95]
	v_mfma_f32_16x16x32_bf16 v[84:87], v[140:143], v[184:187], v[84:87]
	v_mfma_f32_16x16x32_bf16 v[76:79], v[152:155], v[184:187], v[76:79]
	v_mfma_f32_16x16x32_bf16 v[124:127], v[148:151], v[164:167], v[124:127]
	v_mfma_f32_16x16x32_bf16 v[120:123], v[156:159], v[164:167], v[120:123]
	v_mfma_f32_16x16x32_bf16 v[116:119], v[148:151], v[172:175], v[116:119]
	v_mfma_f32_16x16x32_bf16 v[108:111], v[156:159], v[172:175], v[108:111]
	v_mfma_f32_16x16x32_bf16 v[100:103], v[148:151], v[180:183], v[100:103]
	v_mfma_f32_16x16x32_bf16 v[92:95], v[156:159], v[180:183], v[92:95]
	v_mfma_f32_16x16x32_bf16 v[84:87], v[148:151], v[188:191], v[84:87]
	v_mfma_f32_16x16x32_bf16 v[76:79], v[156:159], v[188:191], v[76:79]
	s_barrier
	ds_read_b128 v[192:195], v146 offset:16384
	ds_read_b128 v[196:199], v146 offset:17408
	ds_read_b128 v[200:203], v146 offset:18432
	ds_read_b128 v[204:207], v146 offset:19456
	s_barrier
	s_waitcnt lgkmcnt(0)
	s_waitcnt lgkmcnt(0)
	v_mfma_f32_16x16x32_bf16 v[112:115], v[192:195], v[160:163], v[112:115]
	v_mfma_f32_16x16x32_bf16 v[104:107], v[200:203], v[160:163], v[104:107]
	v_mfma_f32_16x16x32_bf16 v[96:99], v[192:195], v[168:171], v[96:99]
	v_mfma_f32_16x16x32_bf16 v[88:91], v[200:203], v[168:171], v[88:91]
	v_mfma_f32_16x16x32_bf16 v[80:83], v[192:195], v[176:179], v[80:83]
	v_mfma_f32_16x16x32_bf16 v[72:75], v[200:203], v[176:179], v[72:75]
	v_mfma_f32_16x16x32_bf16 v[68:71], v[192:195], v[184:187], v[68:71]
	v_mfma_f32_16x16x32_bf16 v[64:67], v[200:203], v[184:187], v[64:67]
	v_mfma_f32_16x16x32_bf16 v[112:115], v[196:199], v[164:167], v[112:115]
	v_mfma_f32_16x16x32_bf16 v[104:107], v[204:207], v[164:167], v[104:107]
	v_mfma_f32_16x16x32_bf16 v[96:99], v[196:199], v[172:175], v[96:99]
	v_mfma_f32_16x16x32_bf16 v[88:91], v[204:207], v[172:175], v[88:91]
	v_mfma_f32_16x16x32_bf16 v[80:83], v[196:199], v[180:183], v[80:83]
	v_mfma_f32_16x16x32_bf16 v[72:75], v[204:207], v[180:183], v[72:75]
	v_mfma_f32_16x16x32_bf16 v[68:71], v[196:199], v[188:191], v[68:71]
	v_mfma_f32_16x16x32_bf16 v[64:67], v[204:207], v[188:191], v[64:67]
	s_barrier
	ds_read_b128 v[160:163], v147 offset:16384
	ds_read_b128 v[164:167], v147 offset:17408
	ds_read_b128 v[168:171], v147 offset:18432
	ds_read_b128 v[172:175], v147 offset:19456
	ds_read_b128 v[176:179], v147 offset:20480
	ds_read_b128 v[180:183], v147 offset:21504
	ds_read_b128 v[184:187], v147 offset:22528
	ds_read_b128 v[188:191], v147 offset:23552
	s_waitcnt vmcnt(4)
	s_barrier
	s_waitcnt lgkmcnt(0)
	s_waitcnt lgkmcnt(0)
	v_mfma_f32_16x16x32_bf16 v[60:63], v[140:143], v[160:163], v[60:63]
	v_mfma_f32_16x16x32_bf16 v[56:59], v[152:155], v[160:163], v[56:59]
	v_mfma_f32_16x16x32_bf16 v[52:55], v[140:143], v[168:171], v[52:55]
	v_mfma_f32_16x16x32_bf16 v[44:47], v[152:155], v[168:171], v[44:47]
	v_mfma_f32_16x16x32_bf16 v[36:39], v[140:143], v[176:179], v[36:39]
	v_mfma_f32_16x16x32_bf16 v[28:31], v[152:155], v[176:179], v[28:31]
	v_mfma_f32_16x16x32_bf16 v[20:23], v[140:143], v[184:187], v[20:23]
	v_mfma_f32_16x16x32_bf16 v[12:15], v[152:155], v[184:187], v[12:15]
	v_mfma_f32_16x16x32_bf16 v[60:63], v[148:151], v[164:167], v[60:63]
	v_mfma_f32_16x16x32_bf16 v[56:59], v[156:159], v[164:167], v[56:59]
	v_mfma_f32_16x16x32_bf16 v[52:55], v[148:151], v[172:175], v[52:55]
	v_mfma_f32_16x16x32_bf16 v[44:47], v[156:159], v[172:175], v[44:47]
	v_mfma_f32_16x16x32_bf16 v[36:39], v[148:151], v[180:183], v[36:39]
	v_mfma_f32_16x16x32_bf16 v[28:31], v[156:159], v[180:183], v[28:31]
	v_mfma_f32_16x16x32_bf16 v[20:23], v[148:151], v[188:191], v[20:23]
	v_mfma_f32_16x16x32_bf16 v[12:15], v[156:159], v[188:191], v[12:15]
	v_mfma_f32_16x16x32_bf16 v[48:51], v[192:195], v[160:163], v[48:51]
	v_mfma_f32_16x16x32_bf16 v[40:43], v[200:203], v[160:163], v[40:43]
	v_mfma_f32_16x16x32_bf16 v[32:35], v[192:195], v[168:171], v[32:35]
	v_mfma_f32_16x16x32_bf16 v[24:27], v[200:203], v[168:171], v[24:27]
	v_mfma_f32_16x16x32_bf16 v[16:19], v[192:195], v[176:179], v[16:19]
	v_mfma_f32_16x16x32_bf16 v[8:11], v[200:203], v[176:179], v[8:11]
	v_mfma_f32_16x16x32_bf16 v[4:7], v[192:195], v[184:187], v[4:7]
	v_mfma_f32_16x16x32_bf16 v[0:3], v[200:203], v[184:187], v[0:3]
	v_mfma_f32_16x16x32_bf16 v[48:51], v[196:199], v[164:167], v[48:51]
	v_mfma_f32_16x16x32_bf16 v[40:43], v[204:207], v[164:167], v[40:43]
	v_mfma_f32_16x16x32_bf16 v[32:35], v[196:199], v[172:175], v[32:35]
	v_mfma_f32_16x16x32_bf16 v[24:27], v[204:207], v[172:175], v[24:27]
	v_mfma_f32_16x16x32_bf16 v[16:19], v[196:199], v[180:183], v[16:19]
	v_mfma_f32_16x16x32_bf16 v[8:11], v[204:207], v[180:183], v[8:11]
	v_mfma_f32_16x16x32_bf16 v[4:7], v[196:199], v[188:191], v[4:7]
	v_mfma_f32_16x16x32_bf16 v[0:3], v[204:207], v[188:191], v[0:3]
	s_barrier
	ds_read_b128 v[140:143], v146 offset:32768
	ds_read_b128 v[148:151], v146 offset:33792
	ds_read_b128 v[152:155], v146 offset:34816
	ds_read_b128 v[156:159], v146 offset:35840
	ds_read_b128 v[160:163], v147 offset:32768
	ds_read_b128 v[164:167], v147 offset:33792
	ds_read_b128 v[168:171], v147 offset:34816
	ds_read_b128 v[172:175], v147 offset:35840
	ds_read_b128 v[176:179], v147 offset:36864
	ds_read_b128 v[180:183], v147 offset:37888
	ds_read_b128 v[184:187], v147 offset:38912
	ds_read_b128 v[188:191], v147 offset:39936
	s_waitcnt vmcnt(2)
	s_barrier
	s_waitcnt lgkmcnt(0)
	s_waitcnt lgkmcnt(0)
	v_mfma_f32_16x16x32_bf16 v[124:127], v[140:143], v[160:163], v[124:127]
	v_mfma_f32_16x16x32_bf16 v[120:123], v[152:155], v[160:163], v[120:123]
	v_mfma_f32_16x16x32_bf16 v[116:119], v[140:143], v[168:171], v[116:119]
	v_mfma_f32_16x16x32_bf16 v[108:111], v[152:155], v[168:171], v[108:111]
	v_mfma_f32_16x16x32_bf16 v[100:103], v[140:143], v[176:179], v[100:103]
	v_mfma_f32_16x16x32_bf16 v[92:95], v[152:155], v[176:179], v[92:95]
	v_mfma_f32_16x16x32_bf16 v[84:87], v[140:143], v[184:187], v[84:87]
	v_mfma_f32_16x16x32_bf16 v[76:79], v[152:155], v[184:187], v[76:79]
	v_mfma_f32_16x16x32_bf16 v[124:127], v[148:151], v[164:167], v[124:127]
	v_mfma_f32_16x16x32_bf16 v[120:123], v[156:159], v[164:167], v[120:123]
	v_mfma_f32_16x16x32_bf16 v[116:119], v[148:151], v[172:175], v[116:119]
	v_mfma_f32_16x16x32_bf16 v[108:111], v[156:159], v[172:175], v[108:111]
	v_mfma_f32_16x16x32_bf16 v[100:103], v[148:151], v[180:183], v[100:103]
	v_mfma_f32_16x16x32_bf16 v[92:95], v[156:159], v[180:183], v[92:95]
	v_mfma_f32_16x16x32_bf16 v[84:87], v[148:151], v[188:191], v[84:87]
	v_mfma_f32_16x16x32_bf16 v[76:79], v[156:159], v[188:191], v[76:79]
	s_barrier
	ds_read_b128 v[192:195], v146 offset:49152
	ds_read_b128 v[196:199], v146 offset:50176
	ds_read_b128 v[200:203], v146 offset:51200
	ds_read_b128 v[204:207], v146 offset:52224
	s_waitcnt vmcnt(0)
	s_barrier
	s_waitcnt lgkmcnt(0)
	s_waitcnt lgkmcnt(0)
	v_mfma_f32_16x16x32_bf16 v[112:115], v[192:195], v[160:163], v[112:115]
	v_mfma_f32_16x16x32_bf16 v[104:107], v[200:203], v[160:163], v[104:107]
	v_mfma_f32_16x16x32_bf16 v[96:99], v[192:195], v[168:171], v[96:99]
	v_mfma_f32_16x16x32_bf16 v[88:91], v[200:203], v[168:171], v[88:91]
	v_mfma_f32_16x16x32_bf16 v[80:83], v[192:195], v[176:179], v[80:83]
	v_mfma_f32_16x16x32_bf16 v[72:75], v[200:203], v[176:179], v[72:75]
	v_mfma_f32_16x16x32_bf16 v[68:71], v[192:195], v[184:187], v[68:71]
	v_mfma_f32_16x16x32_bf16 v[64:67], v[200:203], v[184:187], v[64:67]
	v_mfma_f32_16x16x32_bf16 v[112:115], v[196:199], v[164:167], v[112:115]
	v_mfma_f32_16x16x32_bf16 v[104:107], v[204:207], v[164:167], v[104:107]
	v_mfma_f32_16x16x32_bf16 v[96:99], v[196:199], v[172:175], v[96:99]
	v_mfma_f32_16x16x32_bf16 v[88:91], v[204:207], v[172:175], v[88:91]
	v_mfma_f32_16x16x32_bf16 v[80:83], v[196:199], v[180:183], v[80:83]
	v_mfma_f32_16x16x32_bf16 v[72:75], v[204:207], v[180:183], v[72:75]
	v_mfma_f32_16x16x32_bf16 v[68:71], v[196:199], v[188:191], v[68:71]
	v_mfma_f32_16x16x32_bf16 v[64:67], v[204:207], v[188:191], v[64:67]
	s_barrier
	ds_read_b128 v[160:163], v147 offset:49152
	ds_read_b128 v[164:167], v147 offset:50176
	ds_read_b128 v[168:171], v147 offset:51200
	ds_read_b128 v[172:175], v147 offset:52224
	ds_read_b128 v[176:179], v147 offset:53248
	ds_read_b128 v[180:183], v147 offset:54272
	ds_read_b128 v[184:187], v147 offset:55296
	ds_read_b128 v[188:191], v147 offset:56320
	s_barrier
	s_waitcnt lgkmcnt(0)
	s_waitcnt lgkmcnt(0)
	v_mfma_f32_16x16x32_bf16 v[60:63], v[140:143], v[160:163], v[60:63]
	v_mfma_f32_16x16x32_bf16 v[56:59], v[152:155], v[160:163], v[56:59]
	v_mfma_f32_16x16x32_bf16 v[52:55], v[140:143], v[168:171], v[52:55]
	v_mfma_f32_16x16x32_bf16 v[44:47], v[152:155], v[168:171], v[44:47]
	v_mfma_f32_16x16x32_bf16 v[36:39], v[140:143], v[176:179], v[36:39]
	v_mfma_f32_16x16x32_bf16 v[28:31], v[152:155], v[176:179], v[28:31]
	v_mfma_f32_16x16x32_bf16 v[20:23], v[140:143], v[184:187], v[20:23]
	v_mfma_f32_16x16x32_bf16 v[12:15], v[152:155], v[184:187], v[12:15]
	v_mfma_f32_16x16x32_bf16 v[60:63], v[148:151], v[164:167], v[60:63]
	v_mfma_f32_16x16x32_bf16 v[56:59], v[156:159], v[164:167], v[56:59]
	v_mfma_f32_16x16x32_bf16 v[52:55], v[148:151], v[172:175], v[52:55]
	v_mfma_f32_16x16x32_bf16 v[44:47], v[156:159], v[172:175], v[44:47]
	v_mfma_f32_16x16x32_bf16 v[36:39], v[148:151], v[180:183], v[36:39]
	v_mfma_f32_16x16x32_bf16 v[28:31], v[156:159], v[180:183], v[28:31]
	v_mfma_f32_16x16x32_bf16 v[20:23], v[148:151], v[188:191], v[20:23]
	v_mfma_f32_16x16x32_bf16 v[12:15], v[156:159], v[188:191], v[12:15]
	v_mfma_f32_16x16x32_bf16 v[48:51], v[192:195], v[160:163], v[48:51]
	v_mfma_f32_16x16x32_bf16 v[40:43], v[200:203], v[160:163], v[40:43]
	v_mfma_f32_16x16x32_bf16 v[32:35], v[192:195], v[168:171], v[32:35]
	v_mfma_f32_16x16x32_bf16 v[24:27], v[200:203], v[168:171], v[24:27]
	v_mfma_f32_16x16x32_bf16 v[16:19], v[192:195], v[176:179], v[16:19]
	v_mfma_f32_16x16x32_bf16 v[8:11], v[200:203], v[176:179], v[8:11]
	v_mfma_f32_16x16x32_bf16 v[4:7], v[192:195], v[184:187], v[4:7]
	v_mfma_f32_16x16x32_bf16 v[0:3], v[200:203], v[184:187], v[0:3]
	v_mfma_f32_16x16x32_bf16 v[48:51], v[196:199], v[164:167], v[48:51]
	v_mfma_f32_16x16x32_bf16 v[40:43], v[204:207], v[164:167], v[40:43]
	v_mfma_f32_16x16x32_bf16 v[32:35], v[196:199], v[172:175], v[32:35]
	v_mfma_f32_16x16x32_bf16 v[24:27], v[204:207], v[172:175], v[24:27]
	v_mfma_f32_16x16x32_bf16 v[16:19], v[196:199], v[180:183], v[16:19]
	v_mfma_f32_16x16x32_bf16 v[8:11], v[204:207], v[180:183], v[8:11]
	v_mfma_f32_16x16x32_bf16 v[4:7], v[196:199], v[188:191], v[4:7]
	v_mfma_f32_16x16x32_bf16 v[0:3], v[204:207], v[188:191], v[0:3]
	s_barrier
	s_branch .LBB0_605

.LBB0_622:
	s_or_b64 exec, exec, s[8:9]
	s_add_i32 s42, s42, s13
	s_cmpk_gt_i32 s42, 0x2ff
	s_cselect_b64 s[8:9], -1, 0
	s_and_b64 vcc, exec, s[8:9]
	s_cbranch_vccnz .LBB0_617
	s_ashr_i32 s11, s42, 31
	s_lshr_b32 s11, s11, 29
	s_add_i32 s11, s42, s11
	s_ashr_i32 s21, s11, 3
	s_and_b32 s11, s11, -8
	s_sub_i32 s11, s42, s11
	s_cmp_lt_i32 s11, 0
	s_cselect_b32 s43, s23, 0x60
	s_mul_i32 s11, s43, s11
	s_add_i32 s11, s11, s21
	s_ashr_i32 s21, s11, 31
	s_lshr_b32 s21, s21, 27
	s_add_i32 s21, s11, s21
	s_and_b32 s43, s21, 0xffe0
	s_sub_i32 s11, s11, s43
	s_bfe_i32 s43, s11, 0x80000
	s_bfe_u32 s43, s43, 0x3000c
	s_add_i32 s43, s11, s43
	s_bfe_i32 s44, s43, 0x80000
	s_and_b32 s43, s43, 0xf8
	s_sub_i32 s11, s11, s43
	s_sext_i32_i8 s11, s11
	s_lshl_b32 s21, s21, 6
	s_sext_i32_i16 s45, s44
	s_and_b32 s21, s21, 0xfffff800
	s_lshl_b32 s11, s11, 8
	s_add_i32 s44, s11, s21
	s_lshl_b32 s11, s45, 5
	s_and_b32 s46, s11, 0xffffff00
	s_ashr_i32 s47, s46, 31
	s_lshl_b64 s[48:49], s[46:47], 8
	s_add_u32 s48, s18, s48
	s_addc_u32 s49, s19, s49
	s_mov_b32 m0, s24
	v_lshl_add_u64 v[136:137], s[48:49], 0, v[132:133]
	s_ashr_i32 s45, s44, 31
	global_load_lds_dwordx4 v[136:137], off
	v_lshl_add_u64 v[136:137], s[48:49], 0, v[128:129]
	s_lshl_b64 s[48:49], s[44:45], 8
	s_add_u32 s48, s16, s48
	s_addc_u32 s49, s17, s49
	s_bitset1_b32 s46, 7
	s_ashr_i32 s47, s46, 31
	s_lshl_b64 s[46:47], s[46:47], 8
	s_add_u32 s46, s18, s46
	s_mov_b32 m0, s25
	s_addc_u32 s47, s19, s47
	s_bitset1_b32 s44, 7
	global_load_lds_dwordx4 v[136:137], off
	v_lshl_add_u64 v[136:137], s[48:49], 0, v[134:135]
	s_mov_b32 m0, s22
	s_ashr_i32 s45, s44, 31
	global_load_lds_dwordx4 v[136:137], off
	v_lshl_add_u64 v[136:137], s[48:49], 0, v[130:131]
	s_mov_b32 m0, s26
	s_lshl_b64 s[44:45], s[44:45], 8
	global_load_lds_dwordx4 v[136:137], off
	v_lshl_add_u64 v[136:137], s[46:47], 0, v[132:133]
	s_mov_b32 m0, s27
	s_add_u32 s44, s16, s44
	global_load_lds_dwordx4 v[136:137], off
	v_lshl_add_u64 v[136:137], s[46:47], 0, v[128:129]
	s_mov_b32 m0, s28
	s_addc_u32 s45, s17, s45
	global_load_lds_dwordx4 v[136:137], off
	s_mov_b32 m0, s29
	s_nop 0
	global_load_lds_dwordx4 v134, s[44:45]
	s_mov_b32 m0, s30
	s_nop 0
	global_load_lds_dwordx4 v130, s[44:45]
	s_branch .LBB0_617

.LBB0_700:
	ds_read_b128 v[148:151], v146
	ds_read_b128 v[152:155], v146 offset:1024
	ds_read_b128 v[156:159], v146 offset:2048
	ds_read_b128 v[160:163], v146 offset:3072
	s_add_i32 s11, s2, 2
	s_cmp_gt_u32 s2, 13
	s_cselect_b32 s26, s54, s16
	s_cselect_b32 s18, s53, s10
	s_mov_b32 m0, s46
	ds_read_b128 v[164:167], v147
	ds_read_b128 v[168:171], v147 offset:1024
	ds_read_b128 v[172:175], v147 offset:2048
	ds_read_b128 v[176:179], v147 offset:3072
	ds_read_b128 v[180:183], v147 offset:4096
	ds_read_b128 v[184:187], v147 offset:5120
	ds_read_b128 v[188:191], v147 offset:6144
	ds_read_b128 v[192:195], v147 offset:7168
	global_load_lds_dwordx4 v[140:141], off
	s_mov_b32 m0, s47
	s_nop 0
	global_load_lds_dwordx4 v[142:143], off
	s_waitcnt lgkmcnt(8)
	s_barrier
	s_waitcnt lgkmcnt(0)
	s_waitcnt lgkmcnt(0)
	v_mfma_f32_16x16x32_bf16 v[124:127], v[148:151], v[164:167], v[124:127]
	v_mfma_f32_16x16x32_bf16 v[120:123], v[156:159], v[164:167], v[120:123]
	v_mfma_f32_16x16x32_bf16 v[116:119], v[148:151], v[172:175], v[116:119]
	v_mfma_f32_16x16x32_bf16 v[112:115], v[156:159], v[172:175], v[112:115]
	v_mfma_f32_16x16x32_bf16 v[100:103], v[148:151], v[180:183], v[100:103]
	v_mfma_f32_16x16x32_bf16 v[96:99], v[156:159], v[180:183], v[96:99]
	v_mfma_f32_16x16x32_bf16 v[84:87], v[148:151], v[188:191], v[84:87]
	v_mfma_f32_16x16x32_bf16 v[80:83], v[156:159], v[188:191], v[80:83]
	v_mfma_f32_16x16x32_bf16 v[124:127], v[152:155], v[168:171], v[124:127]
	v_mfma_f32_16x16x32_bf16 v[120:123], v[160:163], v[168:171], v[120:123]
	v_mfma_f32_16x16x32_bf16 v[116:119], v[152:155], v[176:179], v[116:119]
	v_mfma_f32_16x16x32_bf16 v[112:115], v[160:163], v[176:179], v[112:115]
	v_mfma_f32_16x16x32_bf16 v[100:103], v[152:155], v[184:187], v[100:103]
	v_mfma_f32_16x16x32_bf16 v[96:99], v[160:163], v[184:187], v[96:99]
	v_mfma_f32_16x16x32_bf16 v[84:87], v[152:155], v[192:195], v[84:87]
	v_mfma_f32_16x16x32_bf16 v[80:83], v[160:163], v[192:195], v[80:83]
	s_barrier
	s_cselect_b32 s2, 0, s11
	s_ashr_i32 s27, s26, 31
	s_lshl_b64 s[20:21], s[26:27], 11
	s_add_u32 s58, s24, s20
	s_addc_u32 s59, s25, s21
	s_lshl_b64 s[20:21], s[2:3], 7
	s_add_u32 s56, s58, s20
	s_addc_u32 s57, s59, s21
	s_mov_b32 m0, s17
	ds_read_b128 v[196:199], v146 offset:16384
	ds_read_b128 v[200:203], v146 offset:17408
	ds_read_b128 v[204:207], v146 offset:18432
	ds_read_b128 v[208:211], v146 offset:19456
	global_load_lds_dwordx4 v132, s[56:57]
	s_mov_b32 m0, s29
	s_nop 0
	global_load_lds_dwordx4 v128, s[56:57]
	s_barrier
	s_waitcnt lgkmcnt(0)
	s_waitcnt lgkmcnt(0)
	v_mfma_f32_16x16x32_bf16 v[108:111], v[196:199], v[164:167], v[108:111]
	v_mfma_f32_16x16x32_bf16 v[104:107], v[204:207], v[164:167], v[104:107]
	v_mfma_f32_16x16x32_bf16 v[92:95], v[196:199], v[172:175], v[92:95]
	v_mfma_f32_16x16x32_bf16 v[88:91], v[204:207], v[172:175], v[88:91]
	v_mfma_f32_16x16x32_bf16 v[76:79], v[196:199], v[180:183], v[76:79]
	v_mfma_f32_16x16x32_bf16 v[72:75], v[204:207], v[180:183], v[72:75]
	v_mfma_f32_16x16x32_bf16 v[68:71], v[196:199], v[188:191], v[68:71]
	v_mfma_f32_16x16x32_bf16 v[64:67], v[204:207], v[188:191], v[64:67]
	v_mfma_f32_16x16x32_bf16 v[108:111], v[200:203], v[168:171], v[108:111]
	v_mfma_f32_16x16x32_bf16 v[104:107], v[208:211], v[168:171], v[104:107]
	v_mfma_f32_16x16x32_bf16 v[92:95], v[200:203], v[176:179], v[92:95]
	v_mfma_f32_16x16x32_bf16 v[88:91], v[208:211], v[176:179], v[88:91]
	v_mfma_f32_16x16x32_bf16 v[76:79], v[200:203], v[184:187], v[76:79]
	v_mfma_f32_16x16x32_bf16 v[72:75], v[208:211], v[184:187], v[72:75]
	v_mfma_f32_16x16x32_bf16 v[68:71], v[200:203], v[192:195], v[68:71]
	v_mfma_f32_16x16x32_bf16 v[64:67], v[208:211], v[192:195], v[64:67]
	s_ashr_i32 s19, s18, 31
	s_lshl_b64 s[56:57], s[18:19], 11
	s_add_u32 s60, s22, s56
	s_addc_u32 s61, s23, s57
	s_add_u32 s56, s60, s20
	s_addc_u32 s57, s61, s21
	s_mov_b32 m0, s28
	s_barrier
	ds_read_b128 v[164:167], v147 offset:16384
	ds_read_b128 v[168:171], v147 offset:17408
	ds_read_b128 v[172:175], v147 offset:18432
	ds_read_b128 v[176:179], v147 offset:19456
	ds_read_b128 v[180:183], v147 offset:20480
	ds_read_b128 v[184:187], v147 offset:21504
	ds_read_b128 v[188:191], v147 offset:22528
	ds_read_b128 v[192:195], v147 offset:23552
	global_load_lds_dwordx4 v134, s[56:57]
	s_mov_b32 m0, s30
	s_nop 0
	global_load_lds_dwordx4 v130, s[56:57]
	s_barrier
	s_waitcnt lgkmcnt(0)
	s_waitcnt lgkmcnt(0)
	v_mfma_f32_16x16x32_bf16 v[60:63], v[148:151], v[164:167], v[60:63]
	v_mfma_f32_16x16x32_bf16 v[56:59], v[156:159], v[164:167], v[56:59]
	v_mfma_f32_16x16x32_bf16 v[52:55], v[148:151], v[172:175], v[52:55]
	v_mfma_f32_16x16x32_bf16 v[48:51], v[156:159], v[172:175], v[48:51]
	v_mfma_f32_16x16x32_bf16 v[36:39], v[148:151], v[180:183], v[36:39]
	v_mfma_f32_16x16x32_bf16 v[32:35], v[156:159], v[180:183], v[32:35]
	v_mfma_f32_16x16x32_bf16 v[20:23], v[148:151], v[188:191], v[20:23]
	v_mfma_f32_16x16x32_bf16 v[16:19], v[156:159], v[188:191], v[16:19]
	v_mfma_f32_16x16x32_bf16 v[60:63], v[152:155], v[168:171], v[60:63]
	v_mfma_f32_16x16x32_bf16 v[56:59], v[160:163], v[168:171], v[56:59]
	v_mfma_f32_16x16x32_bf16 v[52:55], v[152:155], v[176:179], v[52:55]
	v_mfma_f32_16x16x32_bf16 v[48:51], v[160:163], v[176:179], v[48:51]
	v_mfma_f32_16x16x32_bf16 v[36:39], v[152:155], v[184:187], v[36:39]
	v_mfma_f32_16x16x32_bf16 v[32:35], v[160:163], v[184:187], v[32:35]
	v_mfma_f32_16x16x32_bf16 v[20:23], v[152:155], v[192:195], v[20:23]
	v_mfma_f32_16x16x32_bf16 v[16:19], v[160:163], v[192:195], v[16:19]
	s_barrier
	s_bitset1_b32 s26, 7
	s_ashr_i32 s27, s26, 31
	s_lshl_b64 s[26:27], s[26:27], 11
	s_add_u32 s56, s24, s26
	s_addc_u32 s57, s25, s27
	s_add_u32 s26, s56, s20
	s_addc_u32 s27, s57, s21
	s_mov_b32 m0, s31
	s_nop 0
	global_load_lds_dwordx4 v132, s[26:27]
	s_mov_b32 m0, s33
	s_nop 0
	global_load_lds_dwordx4 v128, s[26:27]
	s_waitcnt vmcnt(6)
	s_barrier
	v_mfma_f32_16x16x32_bf16 v[44:47], v[196:199], v[164:167], v[44:47]
	v_mfma_f32_16x16x32_bf16 v[40:43], v[204:207], v[164:167], v[40:43]
	v_mfma_f32_16x16x32_bf16 v[28:31], v[196:199], v[172:175], v[28:31]
	v_mfma_f32_16x16x32_bf16 v[24:27], v[204:207], v[172:175], v[24:27]
	v_mfma_f32_16x16x32_bf16 v[12:15], v[196:199], v[180:183], v[12:15]
	v_mfma_f32_16x16x32_bf16 v[8:11], v[204:207], v[180:183], v[8:11]
	v_mfma_f32_16x16x32_bf16 v[4:7], v[196:199], v[188:191], v[4:7]
	v_mfma_f32_16x16x32_bf16 v[0:3], v[204:207], v[188:191], v[0:3]
	v_mfma_f32_16x16x32_bf16 v[44:47], v[200:203], v[168:171], v[44:47]
	v_mfma_f32_16x16x32_bf16 v[40:43], v[208:211], v[168:171], v[40:43]
	v_mfma_f32_16x16x32_bf16 v[28:31], v[200:203], v[176:179], v[28:31]
	v_mfma_f32_16x16x32_bf16 v[24:27], v[208:211], v[176:179], v[24:27]
	v_mfma_f32_16x16x32_bf16 v[12:15], v[200:203], v[184:187], v[12:15]
	v_mfma_f32_16x16x32_bf16 v[8:11], v[208:211], v[184:187], v[8:11]
	v_mfma_f32_16x16x32_bf16 v[4:7], v[200:203], v[192:195], v[4:7]
	v_mfma_f32_16x16x32_bf16 v[0:3], v[208:211], v[192:195], v[0:3]
	s_barrier
	ds_read_b128 v[148:151], v146 offset:32768
	ds_read_b128 v[152:155], v146 offset:33792
	ds_read_b128 v[156:159], v146 offset:34816
	ds_read_b128 v[160:163], v146 offset:35840
	s_bitset1_b32 s18, 7
	s_ashr_i32 s19, s18, 31
	s_lshl_b64 s[18:19], s[18:19], 11
	s_add_u32 s18, s22, s18
	s_addc_u32 s19, s23, s19
	s_add_u32 s18, s18, s20
	s_addc_u32 s19, s19, s21
	s_mov_b32 m0, s36
	ds_read_b128 v[164:167], v147 offset:32768
	ds_read_b128 v[168:171], v147 offset:33792
	ds_read_b128 v[172:175], v147 offset:34816
	ds_read_b128 v[176:179], v147 offset:35840
	ds_read_b128 v[180:183], v147 offset:36864
	ds_read_b128 v[184:187], v147 offset:37888
	ds_read_b128 v[188:191], v147 offset:38912
	ds_read_b128 v[192:195], v147 offset:39936
	global_load_lds_dwordx4 v134, s[18:19]
	s_mov_b32 m0, s37
	s_nop 0
	global_load_lds_dwordx4 v130, s[18:19]
	s_waitcnt lgkmcnt(8)
	s_barrier
	s_waitcnt lgkmcnt(0)
	s_waitcnt lgkmcnt(0)
	v_mfma_f32_16x16x32_bf16 v[124:127], v[148:151], v[164:167], v[124:127]
	v_mfma_f32_16x16x32_bf16 v[120:123], v[156:159], v[164:167], v[120:123]
	v_mfma_f32_16x16x32_bf16 v[116:119], v[148:151], v[172:175], v[116:119]
	v_mfma_f32_16x16x32_bf16 v[112:115], v[156:159], v[172:175], v[112:115]
	v_mfma_f32_16x16x32_bf16 v[100:103], v[148:151], v[180:183], v[100:103]
	v_mfma_f32_16x16x32_bf16 v[96:99], v[156:159], v[180:183], v[96:99]
	v_mfma_f32_16x16x32_bf16 v[84:87], v[148:151], v[188:191], v[84:87]
	v_mfma_f32_16x16x32_bf16 v[80:83], v[156:159], v[188:191], v[80:83]
	v_mfma_f32_16x16x32_bf16 v[124:127], v[152:155], v[168:171], v[124:127]
	v_mfma_f32_16x16x32_bf16 v[120:123], v[160:163], v[168:171], v[120:123]
	v_mfma_f32_16x16x32_bf16 v[116:119], v[152:155], v[176:179], v[116:119]
	v_mfma_f32_16x16x32_bf16 v[112:115], v[160:163], v[176:179], v[112:115]
	v_mfma_f32_16x16x32_bf16 v[100:103], v[152:155], v[184:187], v[100:103]
	v_mfma_f32_16x16x32_bf16 v[96:99], v[160:163], v[184:187], v[96:99]
	v_mfma_f32_16x16x32_bf16 v[84:87], v[152:155], v[192:195], v[84:87]
	v_mfma_f32_16x16x32_bf16 v[80:83], v[160:163], v[192:195], v[80:83]
	s_barrier
	s_or_b32 s2, s2, 1
	s_lshl_b64 s[18:19], s[2:3], 7
	s_add_u32 s20, s58, s18
	s_addc_u32 s21, s59, s19
	s_mov_b32 m0, s38
	ds_read_b128 v[196:199], v146 offset:49152
	ds_read_b128 v[200:203], v146 offset:50176
	ds_read_b128 v[204:207], v146 offset:51200
	ds_read_b128 v[208:211], v146 offset:52224
	global_load_lds_dwordx4 v132, s[20:21]
	s_mov_b32 m0, s39
	s_nop 0
	global_load_lds_dwordx4 v128, s[20:21]
	s_barrier
	s_waitcnt lgkmcnt(0)
	s_waitcnt lgkmcnt(0)
	v_mfma_f32_16x16x32_bf16 v[108:111], v[196:199], v[164:167], v[108:111]
	v_mfma_f32_16x16x32_bf16 v[104:107], v[204:207], v[164:167], v[104:107]
	v_mfma_f32_16x16x32_bf16 v[92:95], v[196:199], v[172:175], v[92:95]
	v_mfma_f32_16x16x32_bf16 v[88:91], v[204:207], v[172:175], v[88:91]
	v_mfma_f32_16x16x32_bf16 v[76:79], v[196:199], v[180:183], v[76:79]
	v_mfma_f32_16x16x32_bf16 v[72:75], v[204:207], v[180:183], v[72:75]
	v_mfma_f32_16x16x32_bf16 v[68:71], v[196:199], v[188:191], v[68:71]
	v_mfma_f32_16x16x32_bf16 v[64:67], v[204:207], v[188:191], v[64:67]
	v_mfma_f32_16x16x32_bf16 v[108:111], v[200:203], v[168:171], v[108:111]
	v_mfma_f32_16x16x32_bf16 v[104:107], v[208:211], v[168:171], v[104:107]
	v_mfma_f32_16x16x32_bf16 v[92:95], v[200:203], v[176:179], v[92:95]
	v_mfma_f32_16x16x32_bf16 v[88:91], v[208:211], v[176:179], v[88:91]
	v_mfma_f32_16x16x32_bf16 v[76:79], v[200:203], v[184:187], v[76:79]
	v_mfma_f32_16x16x32_bf16 v[72:75], v[208:211], v[184:187], v[72:75]
	v_mfma_f32_16x16x32_bf16 v[68:71], v[200:203], v[192:195], v[68:71]
	v_mfma_f32_16x16x32_bf16 v[64:67], v[208:211], v[192:195], v[64:67]
	s_add_u32 s20, s60, s18
	s_addc_u32 s21, s61, s19
	s_mov_b32 m0, s40
	s_barrier
	ds_read_b128 v[164:167], v147 offset:49152
	ds_read_b128 v[168:171], v147 offset:50176
	ds_read_b128 v[172:175], v147 offset:51200
	ds_read_b128 v[176:179], v147 offset:52224
	ds_read_b128 v[180:183], v147 offset:53248
	ds_read_b128 v[184:187], v147 offset:54272
	ds_read_b128 v[188:191], v147 offset:55296
	ds_read_b128 v[192:195], v147 offset:56320
	global_load_lds_dwordx4 v134, s[20:21]
	s_mov_b32 m0, s41
	s_nop 0
	global_load_lds_dwordx4 v130, s[20:21]
	s_barrier
	s_waitcnt lgkmcnt(0)
	s_waitcnt lgkmcnt(0)
	v_mfma_f32_16x16x32_bf16 v[60:63], v[148:151], v[164:167], v[60:63]
	v_mfma_f32_16x16x32_bf16 v[56:59], v[156:159], v[164:167], v[56:59]
	v_mfma_f32_16x16x32_bf16 v[52:55], v[148:151], v[172:175], v[52:55]
	v_mfma_f32_16x16x32_bf16 v[48:51], v[156:159], v[172:175], v[48:51]
	v_mfma_f32_16x16x32_bf16 v[36:39], v[148:151], v[180:183], v[36:39]
	v_mfma_f32_16x16x32_bf16 v[32:35], v[156:159], v[180:183], v[32:35]
	v_mfma_f32_16x16x32_bf16 v[20:23], v[148:151], v[188:191], v[20:23]
	v_mfma_f32_16x16x32_bf16 v[16:19], v[156:159], v[188:191], v[16:19]
	v_mfma_f32_16x16x32_bf16 v[60:63], v[152:155], v[168:171], v[60:63]
	v_mfma_f32_16x16x32_bf16 v[56:59], v[160:163], v[168:171], v[56:59]
	v_mfma_f32_16x16x32_bf16 v[52:55], v[152:155], v[176:179], v[52:55]
	v_mfma_f32_16x16x32_bf16 v[48:51], v[160:163], v[176:179], v[48:51]
	v_mfma_f32_16x16x32_bf16 v[36:39], v[152:155], v[184:187], v[36:39]
	v_mfma_f32_16x16x32_bf16 v[32:35], v[160:163], v[184:187], v[32:35]
	v_mfma_f32_16x16x32_bf16 v[20:23], v[152:155], v[192:195], v[20:23]
	v_mfma_f32_16x16x32_bf16 v[16:19], v[160:163], v[192:195], v[16:19]
	s_barrier
	s_add_u32 s18, s56, s18
	s_addc_u32 s19, s57, s19
	s_mov_b32 m0, s42
	s_nop 0
	global_load_lds_dwordx4 v132, s[18:19]
	s_mov_b32 m0, s43
	s_nop 0
	global_load_lds_dwordx4 v128, s[18:19]
	s_waitcnt vmcnt(6)
	s_barrier
	v_mfma_f32_16x16x32_bf16 v[44:47], v[196:199], v[164:167], v[44:47]
	v_mfma_f32_16x16x32_bf16 v[40:43], v[204:207], v[164:167], v[40:43]
	v_mfma_f32_16x16x32_bf16 v[28:31], v[196:199], v[172:175], v[28:31]
	v_mfma_f32_16x16x32_bf16 v[24:27], v[204:207], v[172:175], v[24:27]
	v_mfma_f32_16x16x32_bf16 v[12:15], v[196:199], v[180:183], v[12:15]
	v_mfma_f32_16x16x32_bf16 v[8:11], v[204:207], v[180:183], v[8:11]
	v_mfma_f32_16x16x32_bf16 v[4:7], v[196:199], v[188:191], v[4:7]
	v_mfma_f32_16x16x32_bf16 v[0:3], v[204:207], v[188:191], v[0:3]
	v_mfma_f32_16x16x32_bf16 v[44:47], v[200:203], v[168:171], v[44:47]
	v_mfma_f32_16x16x32_bf16 v[40:43], v[208:211], v[168:171], v[40:43]
	v_mfma_f32_16x16x32_bf16 v[28:31], v[200:203], v[176:179], v[28:31]
	v_mfma_f32_16x16x32_bf16 v[24:27], v[208:211], v[176:179], v[24:27]
	v_mfma_f32_16x16x32_bf16 v[12:15], v[200:203], v[184:187], v[12:15]
	v_mfma_f32_16x16x32_bf16 v[8:11], v[208:211], v[184:187], v[8:11]
	v_mfma_f32_16x16x32_bf16 v[4:7], v[200:203], v[192:195], v[4:7]
	v_mfma_f32_16x16x32_bf16 v[0:3], v[208:211], v[192:195], v[0:3]
	v_lshl_add_u64 v[140:141], v[140:141], 0, s[4:5]
	v_lshl_add_u64 v[142:143], v[142:143], 0, s[4:5]
	s_cmp_ge_u32 s11, s55
	s_mov_b32 s2, s11
	s_barrier
	s_cbranch_scc0 .LBB0_700
	s_andn2_b64 vcc, exec, s[8:9]
	s_cbranch_vccnz .LBB0_696
	s_bitset1_b32 s10, 7
	s_ashr_i32 s11, s10, 31
	s_lshl_b64 s[10:11], s[10:11], 11
	s_add_u32 s10, s22, s10
	s_addc_u32 s11, s23, s11
	v_lshl_add_u64 v[192:193], s[10:11], 0, v[134:135]
	s_mov_b32 m0, s46
	v_lshl_add_u64 v[192:193], v[192:193], 0, s[6:7]
	ds_read_b128 v[140:143], v146
	ds_read_b128 v[148:151], v146 offset:1024
	ds_read_b128 v[152:155], v146 offset:2048
	ds_read_b128 v[156:159], v146 offset:3072
	ds_read_b128 v[160:163], v147
	ds_read_b128 v[164:167], v147 offset:1024
	ds_read_b128 v[168:171], v147 offset:2048
	ds_read_b128 v[172:175], v147 offset:3072
	ds_read_b128 v[176:179], v147 offset:4096
	ds_read_b128 v[180:183], v147 offset:5120
	ds_read_b128 v[184:187], v147 offset:6144
	ds_read_b128 v[188:191], v147 offset:7168
	global_load_lds_dwordx4 v[192:193], off
	v_lshl_add_u64 v[192:193], s[10:11], 0, v[130:131]
	v_lshl_add_u64 v[192:193], v[192:193], 0, s[6:7]
	s_mov_b32 m0, s47
	s_nop 0
	global_load_lds_dwordx4 v[192:193], off
	s_barrier
	s_waitcnt lgkmcnt(0)
	s_waitcnt lgkmcnt(0)
	v_mfma_f32_16x16x32_bf16 v[124:127], v[140:143], v[160:163], v[124:127]
	v_mfma_f32_16x16x32_bf16 v[120:123], v[152:155], v[160:163], v[120:123]
	v_mfma_f32_16x16x32_bf16 v[116:119], v[140:143], v[168:171], v[116:119]
	v_mfma_f32_16x16x32_bf16 v[112:115], v[152:155], v[168:171], v[112:115]
	v_mfma_f32_16x16x32_bf16 v[100:103], v[140:143], v[176:179], v[100:103]
	v_mfma_f32_16x16x32_bf16 v[96:99], v[152:155], v[176:179], v[96:99]
	v_mfma_f32_16x16x32_bf16 v[84:87], v[140:143], v[184:187], v[84:87]
	v_mfma_f32_16x16x32_bf16 v[80:83], v[152:155], v[184:187], v[80:83]
	v_mfma_f32_16x16x32_bf16 v[124:127], v[148:151], v[164:167], v[124:127]
	v_mfma_f32_16x16x32_bf16 v[120:123], v[156:159], v[164:167], v[120:123]
	v_mfma_f32_16x16x32_bf16 v[116:119], v[148:151], v[172:175], v[116:119]
	v_mfma_f32_16x16x32_bf16 v[112:115], v[156:159], v[172:175], v[112:115]
	v_mfma_f32_16x16x32_bf16 v[100:103], v[148:151], v[180:183], v[100:103]
	v_mfma_f32_16x16x32_bf16 v[96:99], v[156:159], v[180:183], v[96:99]
	v_mfma_f32_16x16x32_bf16 v[84:87], v[148:151], v[188:191], v[84:87]
	v_mfma_f32_16x16x32_bf16 v[80:83], v[156:159], v[188:191], v[80:83]
	s_barrier
	ds_read_b128 v[192:195], v146 offset:16384
	ds_read_b128 v[196:199], v146 offset:17408
	ds_read_b128 v[200:203], v146 offset:18432
	ds_read_b128 v[204:207], v146 offset:19456
	s_barrier
	s_waitcnt lgkmcnt(0)
	s_waitcnt lgkmcnt(0)
	v_mfma_f32_16x16x32_bf16 v[108:111], v[192:195], v[160:163], v[108:111]
	v_mfma_f32_16x16x32_bf16 v[104:107], v[200:203], v[160:163], v[104:107]
	v_mfma_f32_16x16x32_bf16 v[92:95], v[192:195], v[168:171], v[92:95]
	v_mfma_f32_16x16x32_bf16 v[88:91], v[200:203], v[168:171], v[88:91]
	v_mfma_f32_16x16x32_bf16 v[76:79], v[192:195], v[176:179], v[76:79]
	v_mfma_f32_16x16x32_bf16 v[72:75], v[200:203], v[176:179], v[72:75]
	v_mfma_f32_16x16x32_bf16 v[68:71], v[192:195], v[184:187], v[68:71]
	v_mfma_f32_16x16x32_bf16 v[64:67], v[200:203], v[184:187], v[64:67]
	v_mfma_f32_16x16x32_bf16 v[108:111], v[196:199], v[164:167], v[108:111]
	v_mfma_f32_16x16x32_bf16 v[104:107], v[204:207], v[164:167], v[104:107]
	v_mfma_f32_16x16x32_bf16 v[92:95], v[196:199], v[172:175], v[92:95]
	v_mfma_f32_16x16x32_bf16 v[88:91], v[204:207], v[172:175], v[88:91]
	v_mfma_f32_16x16x32_bf16 v[76:79], v[196:199], v[180:183], v[76:79]
	v_mfma_f32_16x16x32_bf16 v[72:75], v[204:207], v[180:183], v[72:75]
	v_mfma_f32_16x16x32_bf16 v[68:71], v[196:199], v[188:191], v[68:71]
	v_mfma_f32_16x16x32_bf16 v[64:67], v[204:207], v[188:191], v[64:67]
	s_barrier
	ds_read_b128 v[160:163], v147 offset:16384
	ds_read_b128 v[164:167], v147 offset:17408
	ds_read_b128 v[168:171], v147 offset:18432
	ds_read_b128 v[172:175], v147 offset:19456
	ds_read_b128 v[176:179], v147 offset:20480
	ds_read_b128 v[180:183], v147 offset:21504
	ds_read_b128 v[184:187], v147 offset:22528
	ds_read_b128 v[188:191], v147 offset:23552
	s_waitcnt vmcnt(4)
	s_barrier
	s_waitcnt lgkmcnt(0)
	s_waitcnt lgkmcnt(0)
	v_mfma_f32_16x16x32_bf16 v[60:63], v[140:143], v[160:163], v[60:63]
	v_mfma_f32_16x16x32_bf16 v[56:59], v[152:155], v[160:163], v[56:59]
	v_mfma_f32_16x16x32_bf16 v[52:55], v[140:143], v[168:171], v[52:55]
	v_mfma_f32_16x16x32_bf16 v[48:51], v[152:155], v[168:171], v[48:51]
	v_mfma_f32_16x16x32_bf16 v[36:39], v[140:143], v[176:179], v[36:39]
	v_mfma_f32_16x16x32_bf16 v[32:35], v[152:155], v[176:179], v[32:35]
	v_mfma_f32_16x16x32_bf16 v[20:23], v[140:143], v[184:187], v[20:23]
	v_mfma_f32_16x16x32_bf16 v[16:19], v[152:155], v[184:187], v[16:19]
	v_mfma_f32_16x16x32_bf16 v[60:63], v[148:151], v[164:167], v[60:63]
	v_mfma_f32_16x16x32_bf16 v[56:59], v[156:159], v[164:167], v[56:59]
	v_mfma_f32_16x16x32_bf16 v[52:55], v[148:151], v[172:175], v[52:55]
	v_mfma_f32_16x16x32_bf16 v[48:51], v[156:159], v[172:175], v[48:51]
	v_mfma_f32_16x16x32_bf16 v[36:39], v[148:151], v[180:183], v[36:39]
	v_mfma_f32_16x16x32_bf16 v[32:35], v[156:159], v[180:183], v[32:35]
	v_mfma_f32_16x16x32_bf16 v[20:23], v[148:151], v[188:191], v[20:23]
	v_mfma_f32_16x16x32_bf16 v[16:19], v[156:159], v[188:191], v[16:19]
	v_mfma_f32_16x16x32_bf16 v[44:47], v[192:195], v[160:163], v[44:47]
	v_mfma_f32_16x16x32_bf16 v[40:43], v[200:203], v[160:163], v[40:43]
	v_mfma_f32_16x16x32_bf16 v[28:31], v[192:195], v[168:171], v[28:31]
	v_mfma_f32_16x16x32_bf16 v[24:27], v[200:203], v[168:171], v[24:27]
	v_mfma_f32_16x16x32_bf16 v[12:15], v[192:195], v[176:179], v[12:15]
	v_mfma_f32_16x16x32_bf16 v[8:11], v[200:203], v[176:179], v[8:11]
	v_mfma_f32_16x16x32_bf16 v[4:7], v[192:195], v[184:187], v[4:7]
	v_mfma_f32_16x16x32_bf16 v[0:3], v[200:203], v[184:187], v[0:3]
	v_mfma_f32_16x16x32_bf16 v[44:47], v[196:199], v[164:167], v[44:47]
	v_mfma_f32_16x16x32_bf16 v[40:43], v[204:207], v[164:167], v[40:43]
	v_mfma_f32_16x16x32_bf16 v[28:31], v[196:199], v[172:175], v[28:31]
	v_mfma_f32_16x16x32_bf16 v[24:27], v[204:207], v[172:175], v[24:27]
	v_mfma_f32_16x16x32_bf16 v[12:15], v[196:199], v[180:183], v[12:15]
	v_mfma_f32_16x16x32_bf16 v[8:11], v[204:207], v[180:183], v[8:11]
	v_mfma_f32_16x16x32_bf16 v[4:7], v[196:199], v[188:191], v[4:7]
	v_mfma_f32_16x16x32_bf16 v[0:3], v[204:207], v[188:191], v[0:3]
	s_barrier
	ds_read_b128 v[140:143], v146 offset:32768
	ds_read_b128 v[148:151], v146 offset:33792
	ds_read_b128 v[152:155], v146 offset:34816
	ds_read_b128 v[156:159], v146 offset:35840
	ds_read_b128 v[160:163], v147 offset:32768
	ds_read_b128 v[164:167], v147 offset:33792
	ds_read_b128 v[168:171], v147 offset:34816
	ds_read_b128 v[172:175], v147 offset:35840
	ds_read_b128 v[176:179], v147 offset:36864
	ds_read_b128 v[180:183], v147 offset:37888
	ds_read_b128 v[184:187], v147 offset:38912
	ds_read_b128 v[188:191], v147 offset:39936
	s_waitcnt vmcnt(2)
	s_barrier
	s_waitcnt lgkmcnt(0)
	s_waitcnt lgkmcnt(0)
	v_mfma_f32_16x16x32_bf16 v[124:127], v[140:143], v[160:163], v[124:127]
	v_mfma_f32_16x16x32_bf16 v[120:123], v[152:155], v[160:163], v[120:123]
	v_mfma_f32_16x16x32_bf16 v[116:119], v[140:143], v[168:171], v[116:119]
	v_mfma_f32_16x16x32_bf16 v[112:115], v[152:155], v[168:171], v[112:115]
	v_mfma_f32_16x16x32_bf16 v[100:103], v[140:143], v[176:179], v[100:103]
	v_mfma_f32_16x16x32_bf16 v[96:99], v[152:155], v[176:179], v[96:99]
	v_mfma_f32_16x16x32_bf16 v[84:87], v[140:143], v[184:187], v[84:87]
	v_mfma_f32_16x16x32_bf16 v[80:83], v[152:155], v[184:187], v[80:83]
	v_mfma_f32_16x16x32_bf16 v[124:127], v[148:151], v[164:167], v[124:127]
	v_mfma_f32_16x16x32_bf16 v[120:123], v[156:159], v[164:167], v[120:123]
	v_mfma_f32_16x16x32_bf16 v[116:119], v[148:151], v[172:175], v[116:119]
	v_mfma_f32_16x16x32_bf16 v[112:115], v[156:159], v[172:175], v[112:115]
	v_mfma_f32_16x16x32_bf16 v[100:103], v[148:151], v[180:183], v[100:103]
	v_mfma_f32_16x16x32_bf16 v[96:99], v[156:159], v[180:183], v[96:99]
	v_mfma_f32_16x16x32_bf16 v[84:87], v[148:151], v[188:191], v[84:87]
	v_mfma_f32_16x16x32_bf16 v[80:83], v[156:159], v[188:191], v[80:83]
	s_barrier
	ds_read_b128 v[192:195], v146 offset:49152
	ds_read_b128 v[196:199], v146 offset:50176
	ds_read_b128 v[200:203], v146 offset:51200
	ds_read_b128 v[204:207], v146 offset:52224
	s_waitcnt vmcnt(0)
	s_barrier
	s_waitcnt lgkmcnt(0)
	s_waitcnt lgkmcnt(0)
	v_mfma_f32_16x16x32_bf16 v[108:111], v[192:195], v[160:163], v[108:111]
	v_mfma_f32_16x16x32_bf16 v[104:107], v[200:203], v[160:163], v[104:107]
	v_mfma_f32_16x16x32_bf16 v[92:95], v[192:195], v[168:171], v[92:95]
	v_mfma_f32_16x16x32_bf16 v[88:91], v[200:203], v[168:171], v[88:91]
	v_mfma_f32_16x16x32_bf16 v[76:79], v[192:195], v[176:179], v[76:79]
	v_mfma_f32_16x16x32_bf16 v[72:75], v[200:203], v[176:179], v[72:75]
	v_mfma_f32_16x16x32_bf16 v[68:71], v[192:195], v[184:187], v[68:71]
	v_mfma_f32_16x16x32_bf16 v[64:67], v[200:203], v[184:187], v[64:67]
	v_mfma_f32_16x16x32_bf16 v[108:111], v[196:199], v[164:167], v[108:111]
	v_mfma_f32_16x16x32_bf16 v[104:107], v[204:207], v[164:167], v[104:107]
	v_mfma_f32_16x16x32_bf16 v[92:95], v[196:199], v[172:175], v[92:95]
	v_mfma_f32_16x16x32_bf16 v[88:91], v[204:207], v[172:175], v[88:91]
	v_mfma_f32_16x16x32_bf16 v[76:79], v[196:199], v[180:183], v[76:79]
	v_mfma_f32_16x16x32_bf16 v[72:75], v[204:207], v[180:183], v[72:75]
	v_mfma_f32_16x16x32_bf16 v[68:71], v[196:199], v[188:191], v[68:71]
	v_mfma_f32_16x16x32_bf16 v[64:67], v[204:207], v[188:191], v[64:67]
	s_barrier
	ds_read_b128 v[160:163], v147 offset:49152
	ds_read_b128 v[164:167], v147 offset:50176
	ds_read_b128 v[168:171], v147 offset:51200
	ds_read_b128 v[172:175], v147 offset:52224
	ds_read_b128 v[176:179], v147 offset:53248
	ds_read_b128 v[180:183], v147 offset:54272
	ds_read_b128 v[184:187], v147 offset:55296
	ds_read_b128 v[188:191], v147 offset:56320
	s_barrier
	s_waitcnt lgkmcnt(0)
	s_waitcnt lgkmcnt(0)
	v_mfma_f32_16x16x32_bf16 v[60:63], v[140:143], v[160:163], v[60:63]
	v_mfma_f32_16x16x32_bf16 v[56:59], v[152:155], v[160:163], v[56:59]
	v_mfma_f32_16x16x32_bf16 v[52:55], v[140:143], v[168:171], v[52:55]
	v_mfma_f32_16x16x32_bf16 v[48:51], v[152:155], v[168:171], v[48:51]
	v_mfma_f32_16x16x32_bf16 v[36:39], v[140:143], v[176:179], v[36:39]
	v_mfma_f32_16x16x32_bf16 v[32:35], v[152:155], v[176:179], v[32:35]
	v_mfma_f32_16x16x32_bf16 v[20:23], v[140:143], v[184:187], v[20:23]
	v_mfma_f32_16x16x32_bf16 v[16:19], v[152:155], v[184:187], v[16:19]
	v_mfma_f32_16x16x32_bf16 v[60:63], v[148:151], v[164:167], v[60:63]
	v_mfma_f32_16x16x32_bf16 v[56:59], v[156:159], v[164:167], v[56:59]
	v_mfma_f32_16x16x32_bf16 v[52:55], v[148:151], v[172:175], v[52:55]
	v_mfma_f32_16x16x32_bf16 v[48:51], v[156:159], v[172:175], v[48:51]
	v_mfma_f32_16x16x32_bf16 v[36:39], v[148:151], v[180:183], v[36:39]
	v_mfma_f32_16x16x32_bf16 v[32:35], v[156:159], v[180:183], v[32:35]
	v_mfma_f32_16x16x32_bf16 v[20:23], v[148:151], v[188:191], v[20:23]
	v_mfma_f32_16x16x32_bf16 v[16:19], v[156:159], v[188:191], v[16:19]
	v_mfma_f32_16x16x32_bf16 v[44:47], v[192:195], v[160:163], v[44:47]
	v_mfma_f32_16x16x32_bf16 v[40:43], v[200:203], v[160:163], v[40:43]
	v_mfma_f32_16x16x32_bf16 v[28:31], v[192:195], v[168:171], v[28:31]
	v_mfma_f32_16x16x32_bf16 v[24:27], v[200:203], v[168:171], v[24:27]
	v_mfma_f32_16x16x32_bf16 v[12:15], v[192:195], v[176:179], v[12:15]
	v_mfma_f32_16x16x32_bf16 v[8:11], v[200:203], v[176:179], v[8:11]
	v_mfma_f32_16x16x32_bf16 v[4:7], v[192:195], v[184:187], v[4:7]
	v_mfma_f32_16x16x32_bf16 v[0:3], v[200:203], v[184:187], v[0:3]
	v_mfma_f32_16x16x32_bf16 v[44:47], v[196:199], v[164:167], v[44:47]
	v_mfma_f32_16x16x32_bf16 v[40:43], v[204:207], v[164:167], v[40:43]
	v_mfma_f32_16x16x32_bf16 v[28:31], v[196:199], v[172:175], v[28:31]
	v_mfma_f32_16x16x32_bf16 v[24:27], v[204:207], v[172:175], v[24:27]
	v_mfma_f32_16x16x32_bf16 v[12:15], v[196:199], v[180:183], v[12:15]
	v_mfma_f32_16x16x32_bf16 v[8:11], v[204:207], v[180:183], v[8:11]
	v_mfma_f32_16x16x32_bf16 v[4:7], v[196:199], v[188:191], v[4:7]
	v_mfma_f32_16x16x32_bf16 v[0:3], v[204:207], v[188:191], v[0:3]
	s_barrier
	s_branch .LBB0_696

.LBB0_738:
	ds_read_b128 v[148:151], v146
	ds_read_b128 v[152:155], v146 offset:1024
	ds_read_b128 v[156:159], v146 offset:2048
	ds_read_b128 v[160:163], v146 offset:3072
	s_add_i32 s11, s2, 2
	s_cmp_gt_u32 s2, 13
	s_cselect_b32 s22, s52, s16
	s_cselect_b32 s18, s51, s10
	s_mov_b32 m0, s46
	ds_read_b128 v[164:167], v147
	ds_read_b128 v[168:171], v147 offset:1024
	ds_read_b128 v[172:175], v147 offset:2048
	ds_read_b128 v[176:179], v147 offset:3072
	ds_read_b128 v[180:183], v147 offset:4096
	ds_read_b128 v[184:187], v147 offset:5120
	ds_read_b128 v[188:191], v147 offset:6144
	ds_read_b128 v[192:195], v147 offset:7168
	global_load_lds_dwordx4 v[140:141], off
	s_mov_b32 m0, s47
	s_nop 0
	global_load_lds_dwordx4 v[142:143], off
	s_waitcnt lgkmcnt(8)
	s_barrier
	s_waitcnt lgkmcnt(0)
	s_waitcnt lgkmcnt(0)
	v_mfma_f32_16x16x32_bf16 v[124:127], v[148:151], v[164:167], v[124:127]
	v_mfma_f32_16x16x32_bf16 v[120:123], v[156:159], v[164:167], v[120:123]
	v_mfma_f32_16x16x32_bf16 v[108:111], v[148:151], v[172:175], v[108:111]
	v_mfma_f32_16x16x32_bf16 v[104:107], v[156:159], v[172:175], v[104:107]
	v_mfma_f32_16x16x32_bf16 v[92:95], v[148:151], v[180:183], v[92:95]
	v_mfma_f32_16x16x32_bf16 v[88:91], v[156:159], v[180:183], v[88:91]
	v_mfma_f32_16x16x32_bf16 v[76:79], v[148:151], v[188:191], v[76:79]
	v_mfma_f32_16x16x32_bf16 v[72:75], v[156:159], v[188:191], v[72:75]
	v_mfma_f32_16x16x32_bf16 v[124:127], v[152:155], v[168:171], v[124:127]
	v_mfma_f32_16x16x32_bf16 v[120:123], v[160:163], v[168:171], v[120:123]
	v_mfma_f32_16x16x32_bf16 v[108:111], v[152:155], v[176:179], v[108:111]
	v_mfma_f32_16x16x32_bf16 v[104:107], v[160:163], v[176:179], v[104:107]
	v_mfma_f32_16x16x32_bf16 v[92:95], v[152:155], v[184:187], v[92:95]
	v_mfma_f32_16x16x32_bf16 v[88:91], v[160:163], v[184:187], v[88:91]
	v_mfma_f32_16x16x32_bf16 v[76:79], v[152:155], v[192:195], v[76:79]
	v_mfma_f32_16x16x32_bf16 v[72:75], v[160:163], v[192:195], v[72:75]
	s_barrier
	s_cselect_b32 s2, 0, s11
	s_ashr_i32 s23, s22, 31
	s_lshl_b64 s[20:21], s[22:23], 11
	s_add_u32 s58, s26, s20
	s_addc_u32 s59, s27, s21
	s_lshl_b64 s[20:21], s[2:3], 7
	s_add_u32 s56, s58, s20
	s_addc_u32 s57, s59, s21
	s_mov_b32 m0, s17
	ds_read_b128 v[196:199], v146 offset:16384
	ds_read_b128 v[200:203], v146 offset:17408
	ds_read_b128 v[204:207], v146 offset:18432
	ds_read_b128 v[208:211], v146 offset:19456
	global_load_lds_dwordx4 v132, s[56:57]
	s_mov_b32 m0, s29
	s_nop 0
	global_load_lds_dwordx4 v128, s[56:57]
	s_barrier
	s_waitcnt lgkmcnt(0)
	s_waitcnt lgkmcnt(0)
	v_mfma_f32_16x16x32_bf16 v[116:119], v[196:199], v[164:167], v[116:119]
	v_mfma_f32_16x16x32_bf16 v[112:115], v[204:207], v[164:167], v[112:115]
	v_mfma_f32_16x16x32_bf16 v[100:103], v[196:199], v[172:175], v[100:103]
	v_mfma_f32_16x16x32_bf16 v[96:99], v[204:207], v[172:175], v[96:99]
	v_mfma_f32_16x16x32_bf16 v[84:87], v[196:199], v[180:183], v[84:87]
	v_mfma_f32_16x16x32_bf16 v[80:83], v[204:207], v[180:183], v[80:83]
	v_mfma_f32_16x16x32_bf16 v[68:71], v[196:199], v[188:191], v[68:71]
	v_mfma_f32_16x16x32_bf16 v[64:67], v[204:207], v[188:191], v[64:67]
	v_mfma_f32_16x16x32_bf16 v[116:119], v[200:203], v[168:171], v[116:119]
	v_mfma_f32_16x16x32_bf16 v[112:115], v[208:211], v[168:171], v[112:115]
	v_mfma_f32_16x16x32_bf16 v[100:103], v[200:203], v[176:179], v[100:103]
	v_mfma_f32_16x16x32_bf16 v[96:99], v[208:211], v[176:179], v[96:99]
	v_mfma_f32_16x16x32_bf16 v[84:87], v[200:203], v[184:187], v[84:87]
	v_mfma_f32_16x16x32_bf16 v[80:83], v[208:211], v[184:187], v[80:83]
	v_mfma_f32_16x16x32_bf16 v[68:71], v[200:203], v[192:195], v[68:71]
	v_mfma_f32_16x16x32_bf16 v[64:67], v[208:211], v[192:195], v[64:67]
	s_ashr_i32 s19, s18, 31
	s_lshl_b64 s[56:57], s[18:19], 11
	s_add_u32 s60, s24, s56
	s_addc_u32 s61, s25, s57
	s_add_u32 s56, s60, s20
	s_addc_u32 s57, s61, s21
	s_mov_b32 m0, s28
	s_barrier
	ds_read_b128 v[164:167], v147 offset:16384
	ds_read_b128 v[168:171], v147 offset:17408
	ds_read_b128 v[172:175], v147 offset:18432
	ds_read_b128 v[176:179], v147 offset:19456
	ds_read_b128 v[180:183], v147 offset:20480
	ds_read_b128 v[184:187], v147 offset:21504
	ds_read_b128 v[188:191], v147 offset:22528
	ds_read_b128 v[192:195], v147 offset:23552
	global_load_lds_dwordx4 v134, s[56:57]
	s_mov_b32 m0, s30
	s_nop 0
	global_load_lds_dwordx4 v130, s[56:57]
	s_barrier
	s_waitcnt lgkmcnt(0)
	s_waitcnt lgkmcnt(0)
	v_mfma_f32_16x16x32_bf16 v[60:63], v[148:151], v[164:167], v[60:63]
	v_mfma_f32_16x16x32_bf16 v[56:59], v[156:159], v[164:167], v[56:59]
	v_mfma_f32_16x16x32_bf16 v[44:47], v[148:151], v[172:175], v[44:47]
	v_mfma_f32_16x16x32_bf16 v[40:43], v[156:159], v[172:175], v[40:43]
	v_mfma_f32_16x16x32_bf16 v[28:31], v[148:151], v[180:183], v[28:31]
	v_mfma_f32_16x16x32_bf16 v[24:27], v[156:159], v[180:183], v[24:27]
	v_mfma_f32_16x16x32_bf16 v[12:15], v[148:151], v[188:191], v[12:15]
	v_mfma_f32_16x16x32_bf16 v[8:11], v[156:159], v[188:191], v[8:11]
	v_mfma_f32_16x16x32_bf16 v[60:63], v[152:155], v[168:171], v[60:63]
	v_mfma_f32_16x16x32_bf16 v[56:59], v[160:163], v[168:171], v[56:59]
	v_mfma_f32_16x16x32_bf16 v[44:47], v[152:155], v[176:179], v[44:47]
	v_mfma_f32_16x16x32_bf16 v[40:43], v[160:163], v[176:179], v[40:43]
	v_mfma_f32_16x16x32_bf16 v[28:31], v[152:155], v[184:187], v[28:31]
	v_mfma_f32_16x16x32_bf16 v[24:27], v[160:163], v[184:187], v[24:27]
	v_mfma_f32_16x16x32_bf16 v[12:15], v[152:155], v[192:195], v[12:15]
	v_mfma_f32_16x16x32_bf16 v[8:11], v[160:163], v[192:195], v[8:11]
	s_barrier
	s_bitset1_b32 s22, 7
	s_ashr_i32 s23, s22, 31
	s_lshl_b64 s[22:23], s[22:23], 11
	s_add_u32 s56, s26, s22
	s_addc_u32 s57, s27, s23
	s_add_u32 s22, s56, s20
	s_addc_u32 s23, s57, s21
	s_mov_b32 m0, s31
	s_nop 0
	global_load_lds_dwordx4 v132, s[22:23]
	s_mov_b32 m0, s33
	s_nop 0
	global_load_lds_dwordx4 v128, s[22:23]
	s_waitcnt vmcnt(6)
	s_barrier
	v_mfma_f32_16x16x32_bf16 v[52:55], v[196:199], v[164:167], v[52:55]
	v_mfma_f32_16x16x32_bf16 v[48:51], v[204:207], v[164:167], v[48:51]
	v_mfma_f32_16x16x32_bf16 v[36:39], v[196:199], v[172:175], v[36:39]
	v_mfma_f32_16x16x32_bf16 v[32:35], v[204:207], v[172:175], v[32:35]
	v_mfma_f32_16x16x32_bf16 v[20:23], v[196:199], v[180:183], v[20:23]
	v_mfma_f32_16x16x32_bf16 v[16:19], v[204:207], v[180:183], v[16:19]
	v_mfma_f32_16x16x32_bf16 v[4:7], v[196:199], v[188:191], v[4:7]
	v_mfma_f32_16x16x32_bf16 v[0:3], v[204:207], v[188:191], v[0:3]
	v_mfma_f32_16x16x32_bf16 v[52:55], v[200:203], v[168:171], v[52:55]
	v_mfma_f32_16x16x32_bf16 v[48:51], v[208:211], v[168:171], v[48:51]
	v_mfma_f32_16x16x32_bf16 v[36:39], v[200:203], v[176:179], v[36:39]
	v_mfma_f32_16x16x32_bf16 v[32:35], v[208:211], v[176:179], v[32:35]
	v_mfma_f32_16x16x32_bf16 v[20:23], v[200:203], v[184:187], v[20:23]
	v_mfma_f32_16x16x32_bf16 v[16:19], v[208:211], v[184:187], v[16:19]
	v_mfma_f32_16x16x32_bf16 v[4:7], v[200:203], v[192:195], v[4:7]
	v_mfma_f32_16x16x32_bf16 v[0:3], v[208:211], v[192:195], v[0:3]
	s_barrier
	ds_read_b128 v[148:151], v146 offset:32768
	ds_read_b128 v[152:155], v146 offset:33792
	ds_read_b128 v[156:159], v146 offset:34816
	ds_read_b128 v[160:163], v146 offset:35840
	s_bitset1_b32 s18, 7
	s_ashr_i32 s19, s18, 31
	s_lshl_b64 s[18:19], s[18:19], 11
	s_add_u32 s18, s24, s18
	s_addc_u32 s19, s25, s19
	s_add_u32 s18, s18, s20
	s_addc_u32 s19, s19, s21
	s_mov_b32 m0, s36
	ds_read_b128 v[164:167], v147 offset:32768
	ds_read_b128 v[168:171], v147 offset:33792
	ds_read_b128 v[172:175], v147 offset:34816
	ds_read_b128 v[176:179], v147 offset:35840
	ds_read_b128 v[180:183], v147 offset:36864
	ds_read_b128 v[184:187], v147 offset:37888
	ds_read_b128 v[188:191], v147 offset:38912
	ds_read_b128 v[192:195], v147 offset:39936
	global_load_lds_dwordx4 v134, s[18:19]
	s_mov_b32 m0, s37
	s_nop 0
	global_load_lds_dwordx4 v130, s[18:19]
	s_waitcnt lgkmcnt(8)
	s_barrier
	s_waitcnt lgkmcnt(0)
	s_waitcnt lgkmcnt(0)
	v_mfma_f32_16x16x32_bf16 v[124:127], v[148:151], v[164:167], v[124:127]
	v_mfma_f32_16x16x32_bf16 v[120:123], v[156:159], v[164:167], v[120:123]
	v_mfma_f32_16x16x32_bf16 v[108:111], v[148:151], v[172:175], v[108:111]
	v_mfma_f32_16x16x32_bf16 v[104:107], v[156:159], v[172:175], v[104:107]
	v_mfma_f32_16x16x32_bf16 v[92:95], v[148:151], v[180:183], v[92:95]
	v_mfma_f32_16x16x32_bf16 v[88:91], v[156:159], v[180:183], v[88:91]
	v_mfma_f32_16x16x32_bf16 v[76:79], v[148:151], v[188:191], v[76:79]
	v_mfma_f32_16x16x32_bf16 v[72:75], v[156:159], v[188:191], v[72:75]
	v_mfma_f32_16x16x32_bf16 v[124:127], v[152:155], v[168:171], v[124:127]
	v_mfma_f32_16x16x32_bf16 v[120:123], v[160:163], v[168:171], v[120:123]
	v_mfma_f32_16x16x32_bf16 v[108:111], v[152:155], v[176:179], v[108:111]
	v_mfma_f32_16x16x32_bf16 v[104:107], v[160:163], v[176:179], v[104:107]
	v_mfma_f32_16x16x32_bf16 v[92:95], v[152:155], v[184:187], v[92:95]
	v_mfma_f32_16x16x32_bf16 v[88:91], v[160:163], v[184:187], v[88:91]
	v_mfma_f32_16x16x32_bf16 v[76:79], v[152:155], v[192:195], v[76:79]
	v_mfma_f32_16x16x32_bf16 v[72:75], v[160:163], v[192:195], v[72:75]
	s_barrier
	s_or_b32 s2, s2, 1
	s_lshl_b64 s[18:19], s[2:3], 7
	s_add_u32 s20, s58, s18
	s_addc_u32 s21, s59, s19
	s_mov_b32 m0, s38
	ds_read_b128 v[196:199], v146 offset:49152
	ds_read_b128 v[200:203], v146 offset:50176
	ds_read_b128 v[204:207], v146 offset:51200
	ds_read_b128 v[208:211], v146 offset:52224
	global_load_lds_dwordx4 v132, s[20:21]
	s_mov_b32 m0, s39
	s_nop 0
	global_load_lds_dwordx4 v128, s[20:21]
	s_barrier
	s_waitcnt lgkmcnt(0)
	s_waitcnt lgkmcnt(0)
	v_mfma_f32_16x16x32_bf16 v[116:119], v[196:199], v[164:167], v[116:119]
	v_mfma_f32_16x16x32_bf16 v[112:115], v[204:207], v[164:167], v[112:115]
	v_mfma_f32_16x16x32_bf16 v[100:103], v[196:199], v[172:175], v[100:103]
	v_mfma_f32_16x16x32_bf16 v[96:99], v[204:207], v[172:175], v[96:99]
	v_mfma_f32_16x16x32_bf16 v[84:87], v[196:199], v[180:183], v[84:87]
	v_mfma_f32_16x16x32_bf16 v[80:83], v[204:207], v[180:183], v[80:83]
	v_mfma_f32_16x16x32_bf16 v[68:71], v[196:199], v[188:191], v[68:71]
	v_mfma_f32_16x16x32_bf16 v[64:67], v[204:207], v[188:191], v[64:67]
	v_mfma_f32_16x16x32_bf16 v[116:119], v[200:203], v[168:171], v[116:119]
	v_mfma_f32_16x16x32_bf16 v[112:115], v[208:211], v[168:171], v[112:115]
	v_mfma_f32_16x16x32_bf16 v[100:103], v[200:203], v[176:179], v[100:103]
	v_mfma_f32_16x16x32_bf16 v[96:99], v[208:211], v[176:179], v[96:99]
	v_mfma_f32_16x16x32_bf16 v[84:87], v[200:203], v[184:187], v[84:87]
	v_mfma_f32_16x16x32_bf16 v[80:83], v[208:211], v[184:187], v[80:83]
	v_mfma_f32_16x16x32_bf16 v[68:71], v[200:203], v[192:195], v[68:71]
	v_mfma_f32_16x16x32_bf16 v[64:67], v[208:211], v[192:195], v[64:67]
	s_add_u32 s20, s60, s18
	s_addc_u32 s21, s61, s19
	s_mov_b32 m0, s40
	s_barrier
	ds_read_b128 v[164:167], v147 offset:49152
	ds_read_b128 v[168:171], v147 offset:50176
	ds_read_b128 v[172:175], v147 offset:51200
	ds_read_b128 v[176:179], v147 offset:52224
	ds_read_b128 v[180:183], v147 offset:53248
	ds_read_b128 v[184:187], v147 offset:54272
	ds_read_b128 v[188:191], v147 offset:55296
	ds_read_b128 v[192:195], v147 offset:56320
	global_load_lds_dwordx4 v134, s[20:21]
	s_mov_b32 m0, s41
	s_nop 0
	global_load_lds_dwordx4 v130, s[20:21]
	s_barrier
	s_waitcnt lgkmcnt(0)
	s_waitcnt lgkmcnt(0)
	v_mfma_f32_16x16x32_bf16 v[60:63], v[148:151], v[164:167], v[60:63]
	v_mfma_f32_16x16x32_bf16 v[56:59], v[156:159], v[164:167], v[56:59]
	v_mfma_f32_16x16x32_bf16 v[44:47], v[148:151], v[172:175], v[44:47]
	v_mfma_f32_16x16x32_bf16 v[40:43], v[156:159], v[172:175], v[40:43]
	v_mfma_f32_16x16x32_bf16 v[28:31], v[148:151], v[180:183], v[28:31]
	v_mfma_f32_16x16x32_bf16 v[24:27], v[156:159], v[180:183], v[24:27]
	v_mfma_f32_16x16x32_bf16 v[12:15], v[148:151], v[188:191], v[12:15]
	v_mfma_f32_16x16x32_bf16 v[8:11], v[156:159], v[188:191], v[8:11]
	v_mfma_f32_16x16x32_bf16 v[60:63], v[152:155], v[168:171], v[60:63]
	v_mfma_f32_16x16x32_bf16 v[56:59], v[160:163], v[168:171], v[56:59]
	v_mfma_f32_16x16x32_bf16 v[44:47], v[152:155], v[176:179], v[44:47]
	v_mfma_f32_16x16x32_bf16 v[40:43], v[160:163], v[176:179], v[40:43]
	v_mfma_f32_16x16x32_bf16 v[28:31], v[152:155], v[184:187], v[28:31]
	v_mfma_f32_16x16x32_bf16 v[24:27], v[160:163], v[184:187], v[24:27]
	v_mfma_f32_16x16x32_bf16 v[12:15], v[152:155], v[192:195], v[12:15]
	v_mfma_f32_16x16x32_bf16 v[8:11], v[160:163], v[192:195], v[8:11]
	s_barrier
	s_add_u32 s18, s56, s18
	s_addc_u32 s19, s57, s19
	s_mov_b32 m0, s42
	s_nop 0
	global_load_lds_dwordx4 v132, s[18:19]
	s_mov_b32 m0, s43
	s_nop 0
	global_load_lds_dwordx4 v128, s[18:19]
	s_waitcnt vmcnt(6)
	s_barrier
	v_mfma_f32_16x16x32_bf16 v[52:55], v[196:199], v[164:167], v[52:55]
	v_mfma_f32_16x16x32_bf16 v[48:51], v[204:207], v[164:167], v[48:51]
	v_mfma_f32_16x16x32_bf16 v[36:39], v[196:199], v[172:175], v[36:39]
	v_mfma_f32_16x16x32_bf16 v[32:35], v[204:207], v[172:175], v[32:35]
	v_mfma_f32_16x16x32_bf16 v[20:23], v[196:199], v[180:183], v[20:23]
	v_mfma_f32_16x16x32_bf16 v[16:19], v[204:207], v[180:183], v[16:19]
	v_mfma_f32_16x16x32_bf16 v[4:7], v[196:199], v[188:191], v[4:7]
	v_mfma_f32_16x16x32_bf16 v[0:3], v[204:207], v[188:191], v[0:3]
	v_mfma_f32_16x16x32_bf16 v[52:55], v[200:203], v[168:171], v[52:55]
	v_mfma_f32_16x16x32_bf16 v[48:51], v[208:211], v[168:171], v[48:51]
	v_mfma_f32_16x16x32_bf16 v[36:39], v[200:203], v[176:179], v[36:39]
	v_mfma_f32_16x16x32_bf16 v[32:35], v[208:211], v[176:179], v[32:35]
	v_mfma_f32_16x16x32_bf16 v[20:23], v[200:203], v[184:187], v[20:23]
	v_mfma_f32_16x16x32_bf16 v[16:19], v[208:211], v[184:187], v[16:19]
	v_mfma_f32_16x16x32_bf16 v[4:7], v[200:203], v[192:195], v[4:7]
	v_mfma_f32_16x16x32_bf16 v[0:3], v[208:211], v[192:195], v[0:3]
	v_lshl_add_u64 v[140:141], v[140:141], 0, s[4:5]
	v_lshl_add_u64 v[142:143], v[142:143], 0, s[4:5]
	s_cmp_ge_u32 s11, s55
	s_mov_b32 s2, s11
	s_barrier
	s_cbranch_scc0 .LBB0_738
	s_andn2_b64 vcc, exec, s[8:9]
	s_cbranch_vccnz .LBB0_734
	s_bitset1_b32 s10, 7
	s_ashr_i32 s11, s10, 31
	s_lshl_b64 s[10:11], s[10:11], 11
	s_add_u32 s10, s24, s10
	s_addc_u32 s11, s25, s11
	v_lshl_add_u64 v[192:193], s[10:11], 0, v[134:135]
	s_mov_b32 m0, s46
	v_lshl_add_u64 v[192:193], v[192:193], 0, s[6:7]
	ds_read_b128 v[140:143], v146
	ds_read_b128 v[148:151], v146 offset:1024
	ds_read_b128 v[152:155], v146 offset:2048
	ds_read_b128 v[156:159], v146 offset:3072
	ds_read_b128 v[160:163], v147
	ds_read_b128 v[164:167], v147 offset:1024
	ds_read_b128 v[168:171], v147 offset:2048
	ds_read_b128 v[172:175], v147 offset:3072
	ds_read_b128 v[176:179], v147 offset:4096
	ds_read_b128 v[180:183], v147 offset:5120
	ds_read_b128 v[184:187], v147 offset:6144
	ds_read_b128 v[188:191], v147 offset:7168
	global_load_lds_dwordx4 v[192:193], off
	v_lshl_add_u64 v[192:193], s[10:11], 0, v[130:131]
	v_lshl_add_u64 v[192:193], v[192:193], 0, s[6:7]
	s_mov_b32 m0, s47
	s_nop 0
	global_load_lds_dwordx4 v[192:193], off
	s_barrier
	s_waitcnt lgkmcnt(0)
	s_waitcnt lgkmcnt(0)
	v_mfma_f32_16x16x32_bf16 v[124:127], v[140:143], v[160:163], v[124:127]
	v_mfma_f32_16x16x32_bf16 v[120:123], v[152:155], v[160:163], v[120:123]
	v_mfma_f32_16x16x32_bf16 v[108:111], v[140:143], v[168:171], v[108:111]
	v_mfma_f32_16x16x32_bf16 v[104:107], v[152:155], v[168:171], v[104:107]
	v_mfma_f32_16x16x32_bf16 v[92:95], v[140:143], v[176:179], v[92:95]
	v_mfma_f32_16x16x32_bf16 v[88:91], v[152:155], v[176:179], v[88:91]
	v_mfma_f32_16x16x32_bf16 v[76:79], v[140:143], v[184:187], v[76:79]
	v_mfma_f32_16x16x32_bf16 v[72:75], v[152:155], v[184:187], v[72:75]
	v_mfma_f32_16x16x32_bf16 v[124:127], v[148:151], v[164:167], v[124:127]
	v_mfma_f32_16x16x32_bf16 v[120:123], v[156:159], v[164:167], v[120:123]
	v_mfma_f32_16x16x32_bf16 v[108:111], v[148:151], v[172:175], v[108:111]
	v_mfma_f32_16x16x32_bf16 v[104:107], v[156:159], v[172:175], v[104:107]
	v_mfma_f32_16x16x32_bf16 v[92:95], v[148:151], v[180:183], v[92:95]
	v_mfma_f32_16x16x32_bf16 v[88:91], v[156:159], v[180:183], v[88:91]
	v_mfma_f32_16x16x32_bf16 v[76:79], v[148:151], v[188:191], v[76:79]
	v_mfma_f32_16x16x32_bf16 v[72:75], v[156:159], v[188:191], v[72:75]
	s_barrier
	ds_read_b128 v[192:195], v146 offset:16384
	ds_read_b128 v[196:199], v146 offset:17408
	ds_read_b128 v[200:203], v146 offset:18432
	ds_read_b128 v[204:207], v146 offset:19456
	s_barrier
	s_waitcnt lgkmcnt(0)
	s_waitcnt lgkmcnt(0)
	v_mfma_f32_16x16x32_bf16 v[116:119], v[192:195], v[160:163], v[116:119]
	v_mfma_f32_16x16x32_bf16 v[112:115], v[200:203], v[160:163], v[112:115]
	v_mfma_f32_16x16x32_bf16 v[100:103], v[192:195], v[168:171], v[100:103]
	v_mfma_f32_16x16x32_bf16 v[96:99], v[200:203], v[168:171], v[96:99]
	v_mfma_f32_16x16x32_bf16 v[84:87], v[192:195], v[176:179], v[84:87]
	v_mfma_f32_16x16x32_bf16 v[80:83], v[200:203], v[176:179], v[80:83]
	v_mfma_f32_16x16x32_bf16 v[68:71], v[192:195], v[184:187], v[68:71]
	v_mfma_f32_16x16x32_bf16 v[64:67], v[200:203], v[184:187], v[64:67]
	v_mfma_f32_16x16x32_bf16 v[116:119], v[196:199], v[164:167], v[116:119]
	v_mfma_f32_16x16x32_bf16 v[112:115], v[204:207], v[164:167], v[112:115]
	v_mfma_f32_16x16x32_bf16 v[100:103], v[196:199], v[172:175], v[100:103]
	v_mfma_f32_16x16x32_bf16 v[96:99], v[204:207], v[172:175], v[96:99]
	v_mfma_f32_16x16x32_bf16 v[84:87], v[196:199], v[180:183], v[84:87]
	v_mfma_f32_16x16x32_bf16 v[80:83], v[204:207], v[180:183], v[80:83]
	v_mfma_f32_16x16x32_bf16 v[68:71], v[196:199], v[188:191], v[68:71]
	v_mfma_f32_16x16x32_bf16 v[64:67], v[204:207], v[188:191], v[64:67]
	s_barrier
	ds_read_b128 v[160:163], v147 offset:16384
	ds_read_b128 v[164:167], v147 offset:17408
	ds_read_b128 v[168:171], v147 offset:18432
	ds_read_b128 v[172:175], v147 offset:19456
	ds_read_b128 v[176:179], v147 offset:20480
	ds_read_b128 v[180:183], v147 offset:21504
	ds_read_b128 v[184:187], v147 offset:22528
	ds_read_b128 v[188:191], v147 offset:23552
	s_waitcnt vmcnt(4)
	s_barrier
	s_waitcnt lgkmcnt(0)
	s_waitcnt lgkmcnt(0)
	v_mfma_f32_16x16x32_bf16 v[60:63], v[140:143], v[160:163], v[60:63]
	v_mfma_f32_16x16x32_bf16 v[56:59], v[152:155], v[160:163], v[56:59]
	v_mfma_f32_16x16x32_bf16 v[44:47], v[140:143], v[168:171], v[44:47]
	v_mfma_f32_16x16x32_bf16 v[40:43], v[152:155], v[168:171], v[40:43]
	v_mfma_f32_16x16x32_bf16 v[28:31], v[140:143], v[176:179], v[28:31]
	v_mfma_f32_16x16x32_bf16 v[24:27], v[152:155], v[176:179], v[24:27]
	v_mfma_f32_16x16x32_bf16 v[12:15], v[140:143], v[184:187], v[12:15]
	v_mfma_f32_16x16x32_bf16 v[8:11], v[152:155], v[184:187], v[8:11]
	v_mfma_f32_16x16x32_bf16 v[60:63], v[148:151], v[164:167], v[60:63]
	v_mfma_f32_16x16x32_bf16 v[56:59], v[156:159], v[164:167], v[56:59]
	v_mfma_f32_16x16x32_bf16 v[44:47], v[148:151], v[172:175], v[44:47]
	v_mfma_f32_16x16x32_bf16 v[40:43], v[156:159], v[172:175], v[40:43]
	v_mfma_f32_16x16x32_bf16 v[28:31], v[148:151], v[180:183], v[28:31]
	v_mfma_f32_16x16x32_bf16 v[24:27], v[156:159], v[180:183], v[24:27]
	v_mfma_f32_16x16x32_bf16 v[12:15], v[148:151], v[188:191], v[12:15]
	v_mfma_f32_16x16x32_bf16 v[8:11], v[156:159], v[188:191], v[8:11]
	v_mfma_f32_16x16x32_bf16 v[52:55], v[192:195], v[160:163], v[52:55]
	v_mfma_f32_16x16x32_bf16 v[48:51], v[200:203], v[160:163], v[48:51]
	v_mfma_f32_16x16x32_bf16 v[36:39], v[192:195], v[168:171], v[36:39]
	v_mfma_f32_16x16x32_bf16 v[32:35], v[200:203], v[168:171], v[32:35]
	v_mfma_f32_16x16x32_bf16 v[20:23], v[192:195], v[176:179], v[20:23]
	v_mfma_f32_16x16x32_bf16 v[16:19], v[200:203], v[176:179], v[16:19]
	v_mfma_f32_16x16x32_bf16 v[4:7], v[192:195], v[184:187], v[4:7]
	v_mfma_f32_16x16x32_bf16 v[0:3], v[200:203], v[184:187], v[0:3]
	v_mfma_f32_16x16x32_bf16 v[52:55], v[196:199], v[164:167], v[52:55]
	v_mfma_f32_16x16x32_bf16 v[48:51], v[204:207], v[164:167], v[48:51]
	v_mfma_f32_16x16x32_bf16 v[36:39], v[196:199], v[172:175], v[36:39]
	v_mfma_f32_16x16x32_bf16 v[32:35], v[204:207], v[172:175], v[32:35]
	v_mfma_f32_16x16x32_bf16 v[20:23], v[196:199], v[180:183], v[20:23]
	v_mfma_f32_16x16x32_bf16 v[16:19], v[204:207], v[180:183], v[16:19]
	v_mfma_f32_16x16x32_bf16 v[4:7], v[196:199], v[188:191], v[4:7]
	v_mfma_f32_16x16x32_bf16 v[0:3], v[204:207], v[188:191], v[0:3]
	s_barrier
	ds_read_b128 v[140:143], v146 offset:32768
	ds_read_b128 v[148:151], v146 offset:33792
	ds_read_b128 v[152:155], v146 offset:34816
	ds_read_b128 v[156:159], v146 offset:35840
	ds_read_b128 v[160:163], v147 offset:32768
	ds_read_b128 v[164:167], v147 offset:33792
	ds_read_b128 v[168:171], v147 offset:34816
	ds_read_b128 v[172:175], v147 offset:35840
	ds_read_b128 v[176:179], v147 offset:36864
	ds_read_b128 v[180:183], v147 offset:37888
	ds_read_b128 v[184:187], v147 offset:38912
	ds_read_b128 v[188:191], v147 offset:39936
	s_waitcnt vmcnt(2)
	s_barrier
	s_waitcnt lgkmcnt(0)
	s_waitcnt lgkmcnt(0)
	v_mfma_f32_16x16x32_bf16 v[124:127], v[140:143], v[160:163], v[124:127]
	v_mfma_f32_16x16x32_bf16 v[120:123], v[152:155], v[160:163], v[120:123]
	v_mfma_f32_16x16x32_bf16 v[108:111], v[140:143], v[168:171], v[108:111]
	v_mfma_f32_16x16x32_bf16 v[104:107], v[152:155], v[168:171], v[104:107]
	v_mfma_f32_16x16x32_bf16 v[92:95], v[140:143], v[176:179], v[92:95]
	v_mfma_f32_16x16x32_bf16 v[88:91], v[152:155], v[176:179], v[88:91]
	v_mfma_f32_16x16x32_bf16 v[76:79], v[140:143], v[184:187], v[76:79]
	v_mfma_f32_16x16x32_bf16 v[72:75], v[152:155], v[184:187], v[72:75]
	v_mfma_f32_16x16x32_bf16 v[124:127], v[148:151], v[164:167], v[124:127]
	v_mfma_f32_16x16x32_bf16 v[120:123], v[156:159], v[164:167], v[120:123]
	v_mfma_f32_16x16x32_bf16 v[108:111], v[148:151], v[172:175], v[108:111]
	v_mfma_f32_16x16x32_bf16 v[104:107], v[156:159], v[172:175], v[104:107]
	v_mfma_f32_16x16x32_bf16 v[92:95], v[148:151], v[180:183], v[92:95]
	v_mfma_f32_16x16x32_bf16 v[88:91], v[156:159], v[180:183], v[88:91]
	v_mfma_f32_16x16x32_bf16 v[76:79], v[148:151], v[188:191], v[76:79]
	v_mfma_f32_16x16x32_bf16 v[72:75], v[156:159], v[188:191], v[72:75]
	s_barrier
	ds_read_b128 v[192:195], v146 offset:49152
	ds_read_b128 v[196:199], v146 offset:50176
	ds_read_b128 v[200:203], v146 offset:51200
	ds_read_b128 v[204:207], v146 offset:52224
	s_waitcnt vmcnt(0)
	s_barrier
	s_waitcnt lgkmcnt(0)
	s_waitcnt lgkmcnt(0)
	v_mfma_f32_16x16x32_bf16 v[116:119], v[192:195], v[160:163], v[116:119]
	v_mfma_f32_16x16x32_bf16 v[112:115], v[200:203], v[160:163], v[112:115]
	v_mfma_f32_16x16x32_bf16 v[100:103], v[192:195], v[168:171], v[100:103]
	v_mfma_f32_16x16x32_bf16 v[96:99], v[200:203], v[168:171], v[96:99]
	v_mfma_f32_16x16x32_bf16 v[84:87], v[192:195], v[176:179], v[84:87]
	v_mfma_f32_16x16x32_bf16 v[80:83], v[200:203], v[176:179], v[80:83]
	v_mfma_f32_16x16x32_bf16 v[68:71], v[192:195], v[184:187], v[68:71]
	v_mfma_f32_16x16x32_bf16 v[64:67], v[200:203], v[184:187], v[64:67]
	v_mfma_f32_16x16x32_bf16 v[116:119], v[196:199], v[164:167], v[116:119]
	v_mfma_f32_16x16x32_bf16 v[112:115], v[204:207], v[164:167], v[112:115]
	v_mfma_f32_16x16x32_bf16 v[100:103], v[196:199], v[172:175], v[100:103]
	v_mfma_f32_16x16x32_bf16 v[96:99], v[204:207], v[172:175], v[96:99]
	v_mfma_f32_16x16x32_bf16 v[84:87], v[196:199], v[180:183], v[84:87]
	v_mfma_f32_16x16x32_bf16 v[80:83], v[204:207], v[180:183], v[80:83]
	v_mfma_f32_16x16x32_bf16 v[68:71], v[196:199], v[188:191], v[68:71]
	v_mfma_f32_16x16x32_bf16 v[64:67], v[204:207], v[188:191], v[64:67]
	s_barrier
	ds_read_b128 v[160:163], v147 offset:49152
	ds_read_b128 v[164:167], v147 offset:50176
	ds_read_b128 v[168:171], v147 offset:51200
	ds_read_b128 v[172:175], v147 offset:52224
	ds_read_b128 v[176:179], v147 offset:53248
	ds_read_b128 v[180:183], v147 offset:54272
	ds_read_b128 v[184:187], v147 offset:55296
	ds_read_b128 v[188:191], v147 offset:56320
	s_barrier
	s_waitcnt lgkmcnt(0)
	s_waitcnt lgkmcnt(0)
	v_mfma_f32_16x16x32_bf16 v[60:63], v[140:143], v[160:163], v[60:63]
	v_mfma_f32_16x16x32_bf16 v[56:59], v[152:155], v[160:163], v[56:59]
	v_mfma_f32_16x16x32_bf16 v[44:47], v[140:143], v[168:171], v[44:47]
	v_mfma_f32_16x16x32_bf16 v[40:43], v[152:155], v[168:171], v[40:43]
	v_mfma_f32_16x16x32_bf16 v[28:31], v[140:143], v[176:179], v[28:31]
	v_mfma_f32_16x16x32_bf16 v[24:27], v[152:155], v[176:179], v[24:27]
	v_mfma_f32_16x16x32_bf16 v[12:15], v[140:143], v[184:187], v[12:15]
	v_mfma_f32_16x16x32_bf16 v[8:11], v[152:155], v[184:187], v[8:11]
	v_mfma_f32_16x16x32_bf16 v[60:63], v[148:151], v[164:167], v[60:63]
	v_mfma_f32_16x16x32_bf16 v[56:59], v[156:159], v[164:167], v[56:59]
	v_mfma_f32_16x16x32_bf16 v[44:47], v[148:151], v[172:175], v[44:47]
	v_mfma_f32_16x16x32_bf16 v[40:43], v[156:159], v[172:175], v[40:43]
	v_mfma_f32_16x16x32_bf16 v[28:31], v[148:151], v[180:183], v[28:31]
	v_mfma_f32_16x16x32_bf16 v[24:27], v[156:159], v[180:183], v[24:27]
	v_mfma_f32_16x16x32_bf16 v[12:15], v[148:151], v[188:191], v[12:15]
	v_mfma_f32_16x16x32_bf16 v[8:11], v[156:159], v[188:191], v[8:11]
	v_mfma_f32_16x16x32_bf16 v[52:55], v[192:195], v[160:163], v[52:55]
	v_mfma_f32_16x16x32_bf16 v[48:51], v[200:203], v[160:163], v[48:51]
	v_mfma_f32_16x16x32_bf16 v[36:39], v[192:195], v[168:171], v[36:39]
	v_mfma_f32_16x16x32_bf16 v[32:35], v[200:203], v[168:171], v[32:35]
	v_mfma_f32_16x16x32_bf16 v[20:23], v[192:195], v[176:179], v[20:23]
	v_mfma_f32_16x16x32_bf16 v[16:19], v[200:203], v[176:179], v[16:19]
	v_mfma_f32_16x16x32_bf16 v[4:7], v[192:195], v[184:187], v[4:7]
	v_mfma_f32_16x16x32_bf16 v[0:3], v[200:203], v[184:187], v[0:3]
	v_mfma_f32_16x16x32_bf16 v[52:55], v[196:199], v[164:167], v[52:55]
	v_mfma_f32_16x16x32_bf16 v[48:51], v[204:207], v[164:167], v[48:51]
	v_mfma_f32_16x16x32_bf16 v[36:39], v[196:199], v[172:175], v[36:39]
	v_mfma_f32_16x16x32_bf16 v[32:35], v[204:207], v[172:175], v[32:35]
	v_mfma_f32_16x16x32_bf16 v[20:23], v[196:199], v[180:183], v[20:23]
	v_mfma_f32_16x16x32_bf16 v[16:19], v[204:207], v[180:183], v[16:19]
	v_mfma_f32_16x16x32_bf16 v[4:7], v[196:199], v[188:191], v[4:7]
	v_mfma_f32_16x16x32_bf16 v[0:3], v[204:207], v[188:191], v[0:3]
	s_barrier
	s_branch .LBB0_734

.LBB0_763:
	ds_read_b128 v[148:151], v146
	ds_read_b128 v[152:155], v146 offset:1024
	ds_read_b128 v[156:159], v146 offset:2048
	ds_read_b128 v[160:163], v146 offset:3072
	s_add_i32 s9, s2, 2
	s_cmp_gt_u32 s2, 61
	s_cselect_b32 s20, s52, s10
	s_cselect_b32 s16, s51, s8
	s_mov_b32 m0, s44
	ds_read_b128 v[164:167], v147
	ds_read_b128 v[168:171], v147 offset:1024
	ds_read_b128 v[172:175], v147 offset:2048
	ds_read_b128 v[176:179], v147 offset:3072
	ds_read_b128 v[180:183], v147 offset:4096
	ds_read_b128 v[184:187], v147 offset:5120
	ds_read_b128 v[188:191], v147 offset:6144
	ds_read_b128 v[192:195], v147 offset:7168
	global_load_lds_dwordx4 v[140:141], off
	s_mov_b32 m0, s45
	s_nop 0
	global_load_lds_dwordx4 v[142:143], off
	s_waitcnt lgkmcnt(8)
	s_barrier
	s_waitcnt lgkmcnt(0)
	s_waitcnt lgkmcnt(0)
	v_mfma_f32_16x16x32_bf16 v[124:127], v[148:151], v[164:167], v[124:127]
	v_mfma_f32_16x16x32_bf16 v[120:123], v[156:159], v[164:167], v[120:123]
	v_mfma_f32_16x16x32_bf16 v[116:119], v[148:151], v[172:175], v[116:119]
	v_mfma_f32_16x16x32_bf16 v[112:115], v[156:159], v[172:175], v[112:115]
	v_mfma_f32_16x16x32_bf16 v[100:103], v[148:151], v[180:183], v[100:103]
	v_mfma_f32_16x16x32_bf16 v[96:99], v[156:159], v[180:183], v[96:99]
	v_mfma_f32_16x16x32_bf16 v[84:87], v[148:151], v[188:191], v[84:87]
	v_mfma_f32_16x16x32_bf16 v[80:83], v[156:159], v[188:191], v[80:83]
	v_mfma_f32_16x16x32_bf16 v[124:127], v[152:155], v[168:171], v[124:127]
	v_mfma_f32_16x16x32_bf16 v[120:123], v[160:163], v[168:171], v[120:123]
	v_mfma_f32_16x16x32_bf16 v[116:119], v[152:155], v[176:179], v[116:119]
	v_mfma_f32_16x16x32_bf16 v[112:115], v[160:163], v[176:179], v[112:115]
	v_mfma_f32_16x16x32_bf16 v[100:103], v[152:155], v[184:187], v[100:103]
	v_mfma_f32_16x16x32_bf16 v[96:99], v[160:163], v[184:187], v[96:99]
	v_mfma_f32_16x16x32_bf16 v[84:87], v[152:155], v[192:195], v[84:87]
	v_mfma_f32_16x16x32_bf16 v[80:83], v[160:163], v[192:195], v[80:83]
	s_barrier
	s_cselect_b32 s2, 0, s9
	s_ashr_i32 s21, s20, 31
	s_lshl_b64 s[18:19], s[20:21], 13
	s_add_u32 s56, s24, s18
	s_addc_u32 s57, s25, s19
	s_lshl_b64 s[18:19], s[2:3], 7
	s_add_u32 s54, s56, s18
	s_addc_u32 s55, s57, s19
	s_mov_b32 m0, s11
	ds_read_b128 v[196:199], v146 offset:16384
	ds_read_b128 v[200:203], v146 offset:17408
	ds_read_b128 v[204:207], v146 offset:18432
	ds_read_b128 v[208:211], v146 offset:19456
	global_load_lds_dwordx4 v132, s[54:55]
	s_mov_b32 m0, s27
	s_nop 0
	global_load_lds_dwordx4 v128, s[54:55]
	s_barrier
	s_waitcnt lgkmcnt(0)
	s_waitcnt lgkmcnt(0)
	v_mfma_f32_16x16x32_bf16 v[108:111], v[196:199], v[164:167], v[108:111]
	v_mfma_f32_16x16x32_bf16 v[104:107], v[204:207], v[164:167], v[104:107]
	v_mfma_f32_16x16x32_bf16 v[92:95], v[196:199], v[172:175], v[92:95]
	v_mfma_f32_16x16x32_bf16 v[88:91], v[204:207], v[172:175], v[88:91]
	v_mfma_f32_16x16x32_bf16 v[76:79], v[196:199], v[180:183], v[76:79]
	v_mfma_f32_16x16x32_bf16 v[72:75], v[204:207], v[180:183], v[72:75]
	v_mfma_f32_16x16x32_bf16 v[68:71], v[196:199], v[188:191], v[68:71]
	v_mfma_f32_16x16x32_bf16 v[64:67], v[204:207], v[188:191], v[64:67]
	v_mfma_f32_16x16x32_bf16 v[108:111], v[200:203], v[168:171], v[108:111]
	v_mfma_f32_16x16x32_bf16 v[104:107], v[208:211], v[168:171], v[104:107]
	v_mfma_f32_16x16x32_bf16 v[92:95], v[200:203], v[176:179], v[92:95]
	v_mfma_f32_16x16x32_bf16 v[88:91], v[208:211], v[176:179], v[88:91]
	v_mfma_f32_16x16x32_bf16 v[76:79], v[200:203], v[184:187], v[76:79]
	v_mfma_f32_16x16x32_bf16 v[72:75], v[208:211], v[184:187], v[72:75]
	v_mfma_f32_16x16x32_bf16 v[68:71], v[200:203], v[192:195], v[68:71]
	v_mfma_f32_16x16x32_bf16 v[64:67], v[208:211], v[192:195], v[64:67]
	s_ashr_i32 s17, s16, 31
	s_lshl_b64 s[54:55], s[16:17], 13
	s_add_u32 s58, s22, s54
	s_addc_u32 s59, s23, s55
	s_add_u32 s54, s58, s18
	s_addc_u32 s55, s59, s19
	s_mov_b32 m0, s26
	s_barrier
	ds_read_b128 v[164:167], v147 offset:16384
	ds_read_b128 v[168:171], v147 offset:17408
	ds_read_b128 v[172:175], v147 offset:18432
	ds_read_b128 v[176:179], v147 offset:19456
	ds_read_b128 v[180:183], v147 offset:20480
	ds_read_b128 v[184:187], v147 offset:21504
	ds_read_b128 v[188:191], v147 offset:22528
	ds_read_b128 v[192:195], v147 offset:23552
	global_load_lds_dwordx4 v134, s[54:55]
	s_mov_b32 m0, s28
	s_nop 0
	global_load_lds_dwordx4 v130, s[54:55]
	s_barrier
	s_waitcnt lgkmcnt(0)
	s_waitcnt lgkmcnt(0)
	v_mfma_f32_16x16x32_bf16 v[60:63], v[148:151], v[164:167], v[60:63]
	v_mfma_f32_16x16x32_bf16 v[56:59], v[156:159], v[164:167], v[56:59]
	v_mfma_f32_16x16x32_bf16 v[52:55], v[148:151], v[172:175], v[52:55]
	v_mfma_f32_16x16x32_bf16 v[48:51], v[156:159], v[172:175], v[48:51]
	v_mfma_f32_16x16x32_bf16 v[36:39], v[148:151], v[180:183], v[36:39]
	v_mfma_f32_16x16x32_bf16 v[32:35], v[156:159], v[180:183], v[32:35]
	v_mfma_f32_16x16x32_bf16 v[20:23], v[148:151], v[188:191], v[20:23]
	v_mfma_f32_16x16x32_bf16 v[16:19], v[156:159], v[188:191], v[16:19]
	v_mfma_f32_16x16x32_bf16 v[60:63], v[152:155], v[168:171], v[60:63]
	v_mfma_f32_16x16x32_bf16 v[56:59], v[160:163], v[168:171], v[56:59]
	v_mfma_f32_16x16x32_bf16 v[52:55], v[152:155], v[176:179], v[52:55]
	v_mfma_f32_16x16x32_bf16 v[48:51], v[160:163], v[176:179], v[48:51]
	v_mfma_f32_16x16x32_bf16 v[36:39], v[152:155], v[184:187], v[36:39]
	v_mfma_f32_16x16x32_bf16 v[32:35], v[160:163], v[184:187], v[32:35]
	v_mfma_f32_16x16x32_bf16 v[20:23], v[152:155], v[192:195], v[20:23]
	v_mfma_f32_16x16x32_bf16 v[16:19], v[160:163], v[192:195], v[16:19]
	s_barrier
	s_bitset1_b32 s20, 7
	s_ashr_i32 s21, s20, 31
	s_lshl_b64 s[20:21], s[20:21], 13
	s_add_u32 s54, s24, s20
	s_addc_u32 s55, s25, s21
	s_add_u32 s20, s54, s18
	s_addc_u32 s21, s55, s19
	s_mov_b32 m0, s29
	s_nop 0
	global_load_lds_dwordx4 v132, s[20:21]
	s_mov_b32 m0, s30
	s_nop 0
	global_load_lds_dwordx4 v128, s[20:21]
	s_waitcnt vmcnt(6)
	s_barrier
	v_mfma_f32_16x16x32_bf16 v[44:47], v[196:199], v[164:167], v[44:47]
	v_mfma_f32_16x16x32_bf16 v[40:43], v[204:207], v[164:167], v[40:43]
	v_mfma_f32_16x16x32_bf16 v[28:31], v[196:199], v[172:175], v[28:31]
	v_mfma_f32_16x16x32_bf16 v[24:27], v[204:207], v[172:175], v[24:27]
	v_mfma_f32_16x16x32_bf16 v[12:15], v[196:199], v[180:183], v[12:15]
	v_mfma_f32_16x16x32_bf16 v[8:11], v[204:207], v[180:183], v[8:11]
	v_mfma_f32_16x16x32_bf16 v[4:7], v[196:199], v[188:191], v[4:7]
	v_mfma_f32_16x16x32_bf16 v[0:3], v[204:207], v[188:191], v[0:3]
	v_mfma_f32_16x16x32_bf16 v[44:47], v[200:203], v[168:171], v[44:47]
	v_mfma_f32_16x16x32_bf16 v[40:43], v[208:211], v[168:171], v[40:43]
	v_mfma_f32_16x16x32_bf16 v[28:31], v[200:203], v[176:179], v[28:31]
	v_mfma_f32_16x16x32_bf16 v[24:27], v[208:211], v[176:179], v[24:27]
	v_mfma_f32_16x16x32_bf16 v[12:15], v[200:203], v[184:187], v[12:15]
	v_mfma_f32_16x16x32_bf16 v[8:11], v[208:211], v[184:187], v[8:11]
	v_mfma_f32_16x16x32_bf16 v[4:7], v[200:203], v[192:195], v[4:7]
	v_mfma_f32_16x16x32_bf16 v[0:3], v[208:211], v[192:195], v[0:3]
	s_barrier
	ds_read_b128 v[148:151], v146 offset:32768
	ds_read_b128 v[152:155], v146 offset:33792
	ds_read_b128 v[156:159], v146 offset:34816
	ds_read_b128 v[160:163], v146 offset:35840
	s_bitset1_b32 s16, 7
	s_ashr_i32 s17, s16, 31
	s_lshl_b64 s[16:17], s[16:17], 13
	s_add_u32 s16, s22, s16
	s_addc_u32 s17, s23, s17
	s_add_u32 s16, s16, s18
	s_addc_u32 s17, s17, s19
	s_mov_b32 m0, s31
	ds_read_b128 v[164:167], v147 offset:32768
	ds_read_b128 v[168:171], v147 offset:33792
	ds_read_b128 v[172:175], v147 offset:34816
	ds_read_b128 v[176:179], v147 offset:35840
	ds_read_b128 v[180:183], v147 offset:36864
	ds_read_b128 v[184:187], v147 offset:37888
	ds_read_b128 v[188:191], v147 offset:38912
	ds_read_b128 v[192:195], v147 offset:39936
	global_load_lds_dwordx4 v134, s[16:17]
	s_mov_b32 m0, s33
	s_nop 0
	global_load_lds_dwordx4 v130, s[16:17]
	s_waitcnt lgkmcnt(8)
	s_barrier
	s_waitcnt lgkmcnt(0)
	s_waitcnt lgkmcnt(0)
	v_mfma_f32_16x16x32_bf16 v[124:127], v[148:151], v[164:167], v[124:127]
	v_mfma_f32_16x16x32_bf16 v[120:123], v[156:159], v[164:167], v[120:123]
	v_mfma_f32_16x16x32_bf16 v[116:119], v[148:151], v[172:175], v[116:119]
	v_mfma_f32_16x16x32_bf16 v[112:115], v[156:159], v[172:175], v[112:115]
	v_mfma_f32_16x16x32_bf16 v[100:103], v[148:151], v[180:183], v[100:103]
	v_mfma_f32_16x16x32_bf16 v[96:99], v[156:159], v[180:183], v[96:99]
	v_mfma_f32_16x16x32_bf16 v[84:87], v[148:151], v[188:191], v[84:87]
	v_mfma_f32_16x16x32_bf16 v[80:83], v[156:159], v[188:191], v[80:83]
	v_mfma_f32_16x16x32_bf16 v[124:127], v[152:155], v[168:171], v[124:127]
	v_mfma_f32_16x16x32_bf16 v[120:123], v[160:163], v[168:171], v[120:123]
	v_mfma_f32_16x16x32_bf16 v[116:119], v[152:155], v[176:179], v[116:119]
	v_mfma_f32_16x16x32_bf16 v[112:115], v[160:163], v[176:179], v[112:115]
	v_mfma_f32_16x16x32_bf16 v[100:103], v[152:155], v[184:187], v[100:103]
	v_mfma_f32_16x16x32_bf16 v[96:99], v[160:163], v[184:187], v[96:99]
	v_mfma_f32_16x16x32_bf16 v[84:87], v[152:155], v[192:195], v[84:87]
	v_mfma_f32_16x16x32_bf16 v[80:83], v[160:163], v[192:195], v[80:83]
	s_barrier
	s_or_b32 s2, s2, 1
	s_lshl_b64 s[16:17], s[2:3], 7
	s_add_u32 s18, s56, s16
	s_addc_u32 s19, s57, s17
	s_mov_b32 m0, s36
	ds_read_b128 v[196:199], v146 offset:49152
	ds_read_b128 v[200:203], v146 offset:50176
	ds_read_b128 v[204:207], v146 offset:51200
	ds_read_b128 v[208:211], v146 offset:52224
	global_load_lds_dwordx4 v132, s[18:19]
	s_mov_b32 m0, s37
	s_nop 0
	global_load_lds_dwordx4 v128, s[18:19]
	s_barrier
	s_waitcnt lgkmcnt(0)
	s_waitcnt lgkmcnt(0)
	v_mfma_f32_16x16x32_bf16 v[108:111], v[196:199], v[164:167], v[108:111]
	v_mfma_f32_16x16x32_bf16 v[104:107], v[204:207], v[164:167], v[104:107]
	v_mfma_f32_16x16x32_bf16 v[92:95], v[196:199], v[172:175], v[92:95]
	v_mfma_f32_16x16x32_bf16 v[88:91], v[204:207], v[172:175], v[88:91]
	v_mfma_f32_16x16x32_bf16 v[76:79], v[196:199], v[180:183], v[76:79]
	v_mfma_f32_16x16x32_bf16 v[72:75], v[204:207], v[180:183], v[72:75]
	v_mfma_f32_16x16x32_bf16 v[68:71], v[196:199], v[188:191], v[68:71]
	v_mfma_f32_16x16x32_bf16 v[64:67], v[204:207], v[188:191], v[64:67]
	v_mfma_f32_16x16x32_bf16 v[108:111], v[200:203], v[168:171], v[108:111]
	v_mfma_f32_16x16x32_bf16 v[104:107], v[208:211], v[168:171], v[104:107]
	v_mfma_f32_16x16x32_bf16 v[92:95], v[200:203], v[176:179], v[92:95]
	v_mfma_f32_16x16x32_bf16 v[88:91], v[208:211], v[176:179], v[88:91]
	v_mfma_f32_16x16x32_bf16 v[76:79], v[200:203], v[184:187], v[76:79]
	v_mfma_f32_16x16x32_bf16 v[72:75], v[208:211], v[184:187], v[72:75]
	v_mfma_f32_16x16x32_bf16 v[68:71], v[200:203], v[192:195], v[68:71]
	v_mfma_f32_16x16x32_bf16 v[64:67], v[208:211], v[192:195], v[64:67]
	s_add_u32 s18, s58, s16
	s_addc_u32 s19, s59, s17
	s_mov_b32 m0, s38
	s_barrier
	ds_read_b128 v[164:167], v147 offset:49152
	ds_read_b128 v[168:171], v147 offset:50176
	ds_read_b128 v[172:175], v147 offset:51200
	ds_read_b128 v[176:179], v147 offset:52224
	ds_read_b128 v[180:183], v147 offset:53248
	ds_read_b128 v[184:187], v147 offset:54272
	ds_read_b128 v[188:191], v147 offset:55296
	ds_read_b128 v[192:195], v147 offset:56320
	global_load_lds_dwordx4 v134, s[18:19]
	s_mov_b32 m0, s39
	s_nop 0
	global_load_lds_dwordx4 v130, s[18:19]
	s_barrier
	s_waitcnt lgkmcnt(0)
	s_waitcnt lgkmcnt(0)
	v_mfma_f32_16x16x32_bf16 v[60:63], v[148:151], v[164:167], v[60:63]
	v_mfma_f32_16x16x32_bf16 v[56:59], v[156:159], v[164:167], v[56:59]
	v_mfma_f32_16x16x32_bf16 v[52:55], v[148:151], v[172:175], v[52:55]
	v_mfma_f32_16x16x32_bf16 v[48:51], v[156:159], v[172:175], v[48:51]
	v_mfma_f32_16x16x32_bf16 v[36:39], v[148:151], v[180:183], v[36:39]
	v_mfma_f32_16x16x32_bf16 v[32:35], v[156:159], v[180:183], v[32:35]
	v_mfma_f32_16x16x32_bf16 v[20:23], v[148:151], v[188:191], v[20:23]
	v_mfma_f32_16x16x32_bf16 v[16:19], v[156:159], v[188:191], v[16:19]
	v_mfma_f32_16x16x32_bf16 v[60:63], v[152:155], v[168:171], v[60:63]
	v_mfma_f32_16x16x32_bf16 v[56:59], v[160:163], v[168:171], v[56:59]
	v_mfma_f32_16x16x32_bf16 v[52:55], v[152:155], v[176:179], v[52:55]
	v_mfma_f32_16x16x32_bf16 v[48:51], v[160:163], v[176:179], v[48:51]
	v_mfma_f32_16x16x32_bf16 v[36:39], v[152:155], v[184:187], v[36:39]
	v_mfma_f32_16x16x32_bf16 v[32:35], v[160:163], v[184:187], v[32:35]
	v_mfma_f32_16x16x32_bf16 v[20:23], v[152:155], v[192:195], v[20:23]
	v_mfma_f32_16x16x32_bf16 v[16:19], v[160:163], v[192:195], v[16:19]
	s_barrier
	s_add_u32 s16, s54, s16
	s_addc_u32 s17, s55, s17
	s_mov_b32 m0, s40
	s_nop 0
	global_load_lds_dwordx4 v132, s[16:17]
	s_mov_b32 m0, s41
	s_nop 0
	global_load_lds_dwordx4 v128, s[16:17]
	s_waitcnt vmcnt(6)
	s_barrier
	v_mfma_f32_16x16x32_bf16 v[44:47], v[196:199], v[164:167], v[44:47]
	v_mfma_f32_16x16x32_bf16 v[40:43], v[204:207], v[164:167], v[40:43]
	v_mfma_f32_16x16x32_bf16 v[28:31], v[196:199], v[172:175], v[28:31]
	v_mfma_f32_16x16x32_bf16 v[24:27], v[204:207], v[172:175], v[24:27]
	v_mfma_f32_16x16x32_bf16 v[12:15], v[196:199], v[180:183], v[12:15]
	v_mfma_f32_16x16x32_bf16 v[8:11], v[204:207], v[180:183], v[8:11]
	v_mfma_f32_16x16x32_bf16 v[4:7], v[196:199], v[188:191], v[4:7]
	v_mfma_f32_16x16x32_bf16 v[0:3], v[204:207], v[188:191], v[0:3]
	v_mfma_f32_16x16x32_bf16 v[44:47], v[200:203], v[168:171], v[44:47]
	v_mfma_f32_16x16x32_bf16 v[40:43], v[208:211], v[168:171], v[40:43]
	v_mfma_f32_16x16x32_bf16 v[28:31], v[200:203], v[176:179], v[28:31]
	v_mfma_f32_16x16x32_bf16 v[24:27], v[208:211], v[176:179], v[24:27]
	v_mfma_f32_16x16x32_bf16 v[12:15], v[200:203], v[184:187], v[12:15]
	v_mfma_f32_16x16x32_bf16 v[8:11], v[208:211], v[184:187], v[8:11]
	v_mfma_f32_16x16x32_bf16 v[4:7], v[200:203], v[192:195], v[4:7]
	v_mfma_f32_16x16x32_bf16 v[0:3], v[208:211], v[192:195], v[0:3]
	v_lshl_add_u64 v[140:141], v[140:141], 0, s[4:5]
	v_lshl_add_u64 v[142:143], v[142:143], 0, s[4:5]
	s_cmp_ge_u32 s9, s53
	s_mov_b32 s2, s9
	s_barrier
	s_cbranch_scc0 .LBB0_763
	s_andn2_b64 vcc, exec, s[6:7]
	s_cbranch_vccnz .LBB0_759
	s_bitset1_b32 s8, 7
	s_ashr_i32 s9, s8, 31
	s_lshl_b64 s[8:9], s[8:9], 13
	s_add_u32 s2, s22, s8
	s_addc_u32 s9, s23, s9
	s_add_u32 s8, s2, 0x1f80
	s_addc_u32 s9, s9, 0
	s_mov_b32 m0, s44
	ds_read_b128 v[140:143], v146
	ds_read_b128 v[148:151], v146 offset:1024
	ds_read_b128 v[152:155], v146 offset:2048
	ds_read_b128 v[156:159], v146 offset:3072
	ds_read_b128 v[160:163], v147
	ds_read_b128 v[164:167], v147 offset:1024
	ds_read_b128 v[168:171], v147 offset:2048
	ds_read_b128 v[172:175], v147 offset:3072
	ds_read_b128 v[176:179], v147 offset:4096
	ds_read_b128 v[180:183], v147 offset:5120
	ds_read_b128 v[184:187], v147 offset:6144
	ds_read_b128 v[188:191], v147 offset:7168
	global_load_lds_dwordx4 v134, s[8:9]
	s_mov_b32 m0, s45
	s_nop 0
	global_load_lds_dwordx4 v130, s[8:9]
	s_barrier
	s_waitcnt lgkmcnt(0)
	s_waitcnt lgkmcnt(0)
	v_mfma_f32_16x16x32_bf16 v[124:127], v[140:143], v[160:163], v[124:127]
	v_mfma_f32_16x16x32_bf16 v[120:123], v[152:155], v[160:163], v[120:123]
	v_mfma_f32_16x16x32_bf16 v[116:119], v[140:143], v[168:171], v[116:119]
	v_mfma_f32_16x16x32_bf16 v[112:115], v[152:155], v[168:171], v[112:115]
	v_mfma_f32_16x16x32_bf16 v[100:103], v[140:143], v[176:179], v[100:103]
	v_mfma_f32_16x16x32_bf16 v[96:99], v[152:155], v[176:179], v[96:99]
	v_mfma_f32_16x16x32_bf16 v[84:87], v[140:143], v[184:187], v[84:87]
	v_mfma_f32_16x16x32_bf16 v[80:83], v[152:155], v[184:187], v[80:83]
	v_mfma_f32_16x16x32_bf16 v[124:127], v[148:151], v[164:167], v[124:127]
	v_mfma_f32_16x16x32_bf16 v[120:123], v[156:159], v[164:167], v[120:123]
	v_mfma_f32_16x16x32_bf16 v[116:119], v[148:151], v[172:175], v[116:119]
	v_mfma_f32_16x16x32_bf16 v[112:115], v[156:159], v[172:175], v[112:115]
	v_mfma_f32_16x16x32_bf16 v[100:103], v[148:151], v[180:183], v[100:103]
	v_mfma_f32_16x16x32_bf16 v[96:99], v[156:159], v[180:183], v[96:99]
	v_mfma_f32_16x16x32_bf16 v[84:87], v[148:151], v[188:191], v[84:87]
	v_mfma_f32_16x16x32_bf16 v[80:83], v[156:159], v[188:191], v[80:83]
	s_barrier
	ds_read_b128 v[192:195], v146 offset:16384
	ds_read_b128 v[196:199], v146 offset:17408
	ds_read_b128 v[200:203], v146 offset:18432
	ds_read_b128 v[204:207], v146 offset:19456
	s_barrier
	s_waitcnt lgkmcnt(0)
	s_waitcnt lgkmcnt(0)
	v_mfma_f32_16x16x32_bf16 v[108:111], v[192:195], v[160:163], v[108:111]
	v_mfma_f32_16x16x32_bf16 v[104:107], v[200:203], v[160:163], v[104:107]
	v_mfma_f32_16x16x32_bf16 v[92:95], v[192:195], v[168:171], v[92:95]
	v_mfma_f32_16x16x32_bf16 v[88:91], v[200:203], v[168:171], v[88:91]
	v_mfma_f32_16x16x32_bf16 v[76:79], v[192:195], v[176:179], v[76:79]
	v_mfma_f32_16x16x32_bf16 v[72:75], v[200:203], v[176:179], v[72:75]
	v_mfma_f32_16x16x32_bf16 v[68:71], v[192:195], v[184:187], v[68:71]
	v_mfma_f32_16x16x32_bf16 v[64:67], v[200:203], v[184:187], v[64:67]
	v_mfma_f32_16x16x32_bf16 v[108:111], v[196:199], v[164:167], v[108:111]
	v_mfma_f32_16x16x32_bf16 v[104:107], v[204:207], v[164:167], v[104:107]
	v_mfma_f32_16x16x32_bf16 v[92:95], v[196:199], v[172:175], v[92:95]
	v_mfma_f32_16x16x32_bf16 v[88:91], v[204:207], v[172:175], v[88:91]
	v_mfma_f32_16x16x32_bf16 v[76:79], v[196:199], v[180:183], v[76:79]
	v_mfma_f32_16x16x32_bf16 v[72:75], v[204:207], v[180:183], v[72:75]
	v_mfma_f32_16x16x32_bf16 v[68:71], v[196:199], v[188:191], v[68:71]
	v_mfma_f32_16x16x32_bf16 v[64:67], v[204:207], v[188:191], v[64:67]
	s_barrier
	ds_read_b128 v[160:163], v147 offset:16384
	ds_read_b128 v[164:167], v147 offset:17408
	ds_read_b128 v[168:171], v147 offset:18432
	ds_read_b128 v[172:175], v147 offset:19456
	ds_read_b128 v[176:179], v147 offset:20480
	ds_read_b128 v[180:183], v147 offset:21504
	ds_read_b128 v[184:187], v147 offset:22528
	ds_read_b128 v[188:191], v147 offset:23552
	s_waitcnt vmcnt(4)
	s_barrier
	s_waitcnt lgkmcnt(0)
	s_waitcnt lgkmcnt(0)
	v_mfma_f32_16x16x32_bf16 v[60:63], v[140:143], v[160:163], v[60:63]
	v_mfma_f32_16x16x32_bf16 v[56:59], v[152:155], v[160:163], v[56:59]
	v_mfma_f32_16x16x32_bf16 v[52:55], v[140:143], v[168:171], v[52:55]
	v_mfma_f32_16x16x32_bf16 v[48:51], v[152:155], v[168:171], v[48:51]
	v_mfma_f32_16x16x32_bf16 v[36:39], v[140:143], v[176:179], v[36:39]
	v_mfma_f32_16x16x32_bf16 v[32:35], v[152:155], v[176:179], v[32:35]
	v_mfma_f32_16x16x32_bf16 v[20:23], v[140:143], v[184:187], v[20:23]
	v_mfma_f32_16x16x32_bf16 v[16:19], v[152:155], v[184:187], v[16:19]
	v_mfma_f32_16x16x32_bf16 v[60:63], v[148:151], v[164:167], v[60:63]
	v_mfma_f32_16x16x32_bf16 v[56:59], v[156:159], v[164:167], v[56:59]
	v_mfma_f32_16x16x32_bf16 v[52:55], v[148:151], v[172:175], v[52:55]
	v_mfma_f32_16x16x32_bf16 v[48:51], v[156:159], v[172:175], v[48:51]
	v_mfma_f32_16x16x32_bf16 v[36:39], v[148:151], v[180:183], v[36:39]
	v_mfma_f32_16x16x32_bf16 v[32:35], v[156:159], v[180:183], v[32:35]
	v_mfma_f32_16x16x32_bf16 v[20:23], v[148:151], v[188:191], v[20:23]
	v_mfma_f32_16x16x32_bf16 v[16:19], v[156:159], v[188:191], v[16:19]
	v_mfma_f32_16x16x32_bf16 v[44:47], v[192:195], v[160:163], v[44:47]
	v_mfma_f32_16x16x32_bf16 v[40:43], v[200:203], v[160:163], v[40:43]
	v_mfma_f32_16x16x32_bf16 v[28:31], v[192:195], v[168:171], v[28:31]
	v_mfma_f32_16x16x32_bf16 v[24:27], v[200:203], v[168:171], v[24:27]
	v_mfma_f32_16x16x32_bf16 v[12:15], v[192:195], v[176:179], v[12:15]
	v_mfma_f32_16x16x32_bf16 v[8:11], v[200:203], v[176:179], v[8:11]
	v_mfma_f32_16x16x32_bf16 v[4:7], v[192:195], v[184:187], v[4:7]
	v_mfma_f32_16x16x32_bf16 v[0:3], v[200:203], v[184:187], v[0:3]
	v_mfma_f32_16x16x32_bf16 v[44:47], v[196:199], v[164:167], v[44:47]
	v_mfma_f32_16x16x32_bf16 v[40:43], v[204:207], v[164:167], v[40:43]
	v_mfma_f32_16x16x32_bf16 v[28:31], v[196:199], v[172:175], v[28:31]
	v_mfma_f32_16x16x32_bf16 v[24:27], v[204:207], v[172:175], v[24:27]
	v_mfma_f32_16x16x32_bf16 v[12:15], v[196:199], v[180:183], v[12:15]
	v_mfma_f32_16x16x32_bf16 v[8:11], v[204:207], v[180:183], v[8:11]
	v_mfma_f32_16x16x32_bf16 v[4:7], v[196:199], v[188:191], v[4:7]
	v_mfma_f32_16x16x32_bf16 v[0:3], v[204:207], v[188:191], v[0:3]
	s_barrier
	ds_read_b128 v[140:143], v146 offset:32768
	ds_read_b128 v[148:151], v146 offset:33792
	ds_read_b128 v[152:155], v146 offset:34816
	ds_read_b128 v[156:159], v146 offset:35840
	ds_read_b128 v[160:163], v147 offset:32768
	ds_read_b128 v[164:167], v147 offset:33792
	ds_read_b128 v[168:171], v147 offset:34816
	ds_read_b128 v[172:175], v147 offset:35840
	ds_read_b128 v[176:179], v147 offset:36864
	ds_read_b128 v[180:183], v147 offset:37888
	ds_read_b128 v[184:187], v147 offset:38912
	ds_read_b128 v[188:191], v147 offset:39936
	s_waitcnt vmcnt(2)
	s_barrier
	s_waitcnt lgkmcnt(0)
	s_waitcnt lgkmcnt(0)
	v_mfma_f32_16x16x32_bf16 v[124:127], v[140:143], v[160:163], v[124:127]
	v_mfma_f32_16x16x32_bf16 v[120:123], v[152:155], v[160:163], v[120:123]
	v_mfma_f32_16x16x32_bf16 v[116:119], v[140:143], v[168:171], v[116:119]
	v_mfma_f32_16x16x32_bf16 v[112:115], v[152:155], v[168:171], v[112:115]
	v_mfma_f32_16x16x32_bf16 v[100:103], v[140:143], v[176:179], v[100:103]
	v_mfma_f32_16x16x32_bf16 v[96:99], v[152:155], v[176:179], v[96:99]
	v_mfma_f32_16x16x32_bf16 v[84:87], v[140:143], v[184:187], v[84:87]
	v_mfma_f32_16x16x32_bf16 v[80:83], v[152:155], v[184:187], v[80:83]
	v_mfma_f32_16x16x32_bf16 v[124:127], v[148:151], v[164:167], v[124:127]
	v_mfma_f32_16x16x32_bf16 v[120:123], v[156:159], v[164:167], v[120:123]
	v_mfma_f32_16x16x32_bf16 v[116:119], v[148:151], v[172:175], v[116:119]
	v_mfma_f32_16x16x32_bf16 v[112:115], v[156:159], v[172:175], v[112:115]
	v_mfma_f32_16x16x32_bf16 v[100:103], v[148:151], v[180:183], v[100:103]
	v_mfma_f32_16x16x32_bf16 v[96:99], v[156:159], v[180:183], v[96:99]
	v_mfma_f32_16x16x32_bf16 v[84:87], v[148:151], v[188:191], v[84:87]
	v_mfma_f32_16x16x32_bf16 v[80:83], v[156:159], v[188:191], v[80:83]
	s_barrier
	ds_read_b128 v[192:195], v146 offset:49152
	ds_read_b128 v[196:199], v146 offset:50176
	ds_read_b128 v[200:203], v146 offset:51200
	ds_read_b128 v[204:207], v146 offset:52224
	s_waitcnt vmcnt(0)
	s_barrier
	s_waitcnt lgkmcnt(0)
	s_waitcnt lgkmcnt(0)
	v_mfma_f32_16x16x32_bf16 v[108:111], v[192:195], v[160:163], v[108:111]
	v_mfma_f32_16x16x32_bf16 v[104:107], v[200:203], v[160:163], v[104:107]
	v_mfma_f32_16x16x32_bf16 v[92:95], v[192:195], v[168:171], v[92:95]
	v_mfma_f32_16x16x32_bf16 v[88:91], v[200:203], v[168:171], v[88:91]
	v_mfma_f32_16x16x32_bf16 v[76:79], v[192:195], v[176:179], v[76:79]
	v_mfma_f32_16x16x32_bf16 v[72:75], v[200:203], v[176:179], v[72:75]
	v_mfma_f32_16x16x32_bf16 v[68:71], v[192:195], v[184:187], v[68:71]
	v_mfma_f32_16x16x32_bf16 v[64:67], v[200:203], v[184:187], v[64:67]
	v_mfma_f32_16x16x32_bf16 v[108:111], v[196:199], v[164:167], v[108:111]
	v_mfma_f32_16x16x32_bf16 v[104:107], v[204:207], v[164:167], v[104:107]
	v_mfma_f32_16x16x32_bf16 v[92:95], v[196:199], v[172:175], v[92:95]
	v_mfma_f32_16x16x32_bf16 v[88:91], v[204:207], v[172:175], v[88:91]
	v_mfma_f32_16x16x32_bf16 v[76:79], v[196:199], v[180:183], v[76:79]
	v_mfma_f32_16x16x32_bf16 v[72:75], v[204:207], v[180:183], v[72:75]
	v_mfma_f32_16x16x32_bf16 v[68:71], v[196:199], v[188:191], v[68:71]
	v_mfma_f32_16x16x32_bf16 v[64:67], v[204:207], v[188:191], v[64:67]
	s_barrier
	ds_read_b128 v[160:163], v147 offset:49152
	ds_read_b128 v[164:167], v147 offset:50176
	ds_read_b128 v[168:171], v147 offset:51200
	ds_read_b128 v[172:175], v147 offset:52224
	ds_read_b128 v[176:179], v147 offset:53248
	ds_read_b128 v[180:183], v147 offset:54272
	ds_read_b128 v[184:187], v147 offset:55296
	ds_read_b128 v[188:191], v147 offset:56320
	s_barrier
	s_waitcnt lgkmcnt(0)
	s_waitcnt lgkmcnt(0)
	v_mfma_f32_16x16x32_bf16 v[60:63], v[140:143], v[160:163], v[60:63]
	v_mfma_f32_16x16x32_bf16 v[56:59], v[152:155], v[160:163], v[56:59]
	v_mfma_f32_16x16x32_bf16 v[52:55], v[140:143], v[168:171], v[52:55]
	v_mfma_f32_16x16x32_bf16 v[48:51], v[152:155], v[168:171], v[48:51]
	v_mfma_f32_16x16x32_bf16 v[36:39], v[140:143], v[176:179], v[36:39]
	v_mfma_f32_16x16x32_bf16 v[32:35], v[152:155], v[176:179], v[32:35]
	v_mfma_f32_16x16x32_bf16 v[20:23], v[140:143], v[184:187], v[20:23]
	v_mfma_f32_16x16x32_bf16 v[16:19], v[152:155], v[184:187], v[16:19]
	v_mfma_f32_16x16x32_bf16 v[60:63], v[148:151], v[164:167], v[60:63]
	v_mfma_f32_16x16x32_bf16 v[56:59], v[156:159], v[164:167], v[56:59]
	v_mfma_f32_16x16x32_bf16 v[52:55], v[148:151], v[172:175], v[52:55]
	v_mfma_f32_16x16x32_bf16 v[48:51], v[156:159], v[172:175], v[48:51]
	v_mfma_f32_16x16x32_bf16 v[36:39], v[148:151], v[180:183], v[36:39]
	v_mfma_f32_16x16x32_bf16 v[32:35], v[156:159], v[180:183], v[32:35]
	v_mfma_f32_16x16x32_bf16 v[20:23], v[148:151], v[188:191], v[20:23]
	v_mfma_f32_16x16x32_bf16 v[16:19], v[156:159], v[188:191], v[16:19]
	v_mfma_f32_16x16x32_bf16 v[44:47], v[192:195], v[160:163], v[44:47]
	v_mfma_f32_16x16x32_bf16 v[40:43], v[200:203], v[160:163], v[40:43]
	v_mfma_f32_16x16x32_bf16 v[28:31], v[192:195], v[168:171], v[28:31]
	v_mfma_f32_16x16x32_bf16 v[24:27], v[200:203], v[168:171], v[24:27]
	v_mfma_f32_16x16x32_bf16 v[12:15], v[192:195], v[176:179], v[12:15]
	v_mfma_f32_16x16x32_bf16 v[8:11], v[200:203], v[176:179], v[8:11]
	v_mfma_f32_16x16x32_bf16 v[4:7], v[192:195], v[184:187], v[4:7]
	v_mfma_f32_16x16x32_bf16 v[0:3], v[200:203], v[184:187], v[0:3]
	v_mfma_f32_16x16x32_bf16 v[44:47], v[196:199], v[164:167], v[44:47]
	v_mfma_f32_16x16x32_bf16 v[40:43], v[204:207], v[164:167], v[40:43]
	v_mfma_f32_16x16x32_bf16 v[28:31], v[196:199], v[172:175], v[28:31]
	v_mfma_f32_16x16x32_bf16 v[24:27], v[204:207], v[172:175], v[24:27]
	v_mfma_f32_16x16x32_bf16 v[12:15], v[196:199], v[180:183], v[12:15]
	v_mfma_f32_16x16x32_bf16 v[8:11], v[204:207], v[180:183], v[8:11]
	v_mfma_f32_16x16x32_bf16 v[4:7], v[196:199], v[188:191], v[4:7]
	v_mfma_f32_16x16x32_bf16 v[0:3], v[204:207], v[188:191], v[0:3]
	s_barrier
	s_branch .LBB0_759
